# GELU/sigmoid epilogue IEEE-division chains replaced by f32 rcp*mul with dead chain code removed, stacked on the flips-removed deferred-conversion build
# speedup vs baseline: 1.0131x; 1.0131x over previous
; #define PG8_STAGE(bufoff, gbase, voff) do { _Pragma("unroll") for (int _i = 0; _i < 2; ++_i) \
;         __builtin_amdgcn_global_load_lds((const unsigned*)((const char*)(gbase) + (voff)[_i]), (LAS unsigned*)(lds + (bufoff) + ldsw + _i * 8192), 16, 0, 0); } while (0)
; #define PG8_LDA(dst, b, h) do { _Pragma("unroll") for (int m = 0; m < 4; ++m) _Pragma("unroll") for (int k = 0; k < 2; ++k) dst[m][k] = *(const LAS bf16x8*)(lds + PG8_SA(b, h) + aoff + m * 2048 + k * 1024); } while (0)
; #define PG8_LDB(dst, b, h) do { _Pragma("unroll") for (int n = 0; n < 2; ++n) _Pragma("unroll") for (int k = 0; k < 2; ++k) dst[n][k] = *(const LAS bf16x8*)(lds + PG8_SB(b, h) + boff + n * 2048 + k * 1024); } while (0)
; #define PG8_MMA(ai, bj, At, Bt) do { __builtin_amdgcn_s_setprio(1); _Pragma("unroll") for (int m = 0; m < 4; ++m) _Pragma("unroll") for (int n = 0; n < 2; ++n) _Pragma("unroll") for (int k = 0; k < 2; ++k) \
;         acc[ai][bj][m][n] = __builtin_amdgcn_mfma_f32_16x16x32_bf16(Bt[n][k], At[m][k], acc[ai][bj][m][n], 0, 0, 0); __builtin_amdgcn_s_setprio(0); } while (0)
; #define PG8_WAIT_L(n) asm volatile("s_waitcnt lgkmcnt(" #n ")" ::: "memory")
; #define PG8_BAR __builtin_amdgcn_s_barrier()
; #define PG8_SCHED __builtin_amdgcn_sched_barrier(0)
; template <class Epi, class Sched>
; __device__ __forceinline__ void gemm_phase(LAS unsigned char* lds, const Gemm g, const Sched& S, const Epi& E) {
;     ...
;             const char* a1 = cA + (size_t)(t + 1) * kstep;
;             const char* a2 = last ? nA : cA + (size_t)(t + 2) * kstep; const char* b2 = last ? nB : cB + (size_t)(t + 2) * kstep;
;             const char* a3 = a2 + kstep; const char* b3 = b2 + kstep;
;             PG8_LDB(B0, 0, 0); PG8_SCHED; PG8_LDA(At, 0, 0); PG8_STAGE(PG8_SA(1, 1), a1 + hstepA, voffA);
;             PG8_WAIT_L(8); PG8_BAR; PG8_WAIT_L(0); PG8_MMA(0, 0, At, B0); PG8_BAR; PG8_SCHED;
;             PG8_LDB(B1, 0, 1); PG8_STAGE(PG8_SB(0, 0), b2, voffB);
;             PG8_BAR; PG8_WAIT_L(0); PG8_MMA(0, 1, At, B1); PG8_BAR;
;             PG8_LDA(At, 0, 1); PG8_STAGE(PG8_SA(0, 0), a2, voffA);
;             PG8_BAR; PG8_WAIT_L(0); PG8_MMA(1, 0, At, B0); PG8_BAR; PG8_SCHED;
.LBB0_595:
	v_add_u32_e32 v144, s24, v1
	ds_read_b128 v[172:175], v144
	ds_read_b128 v[176:179], v144 offset:1024
	ds_read_b128 v[180:183], v144 offset:2048
	ds_read_b128 v[184:187], v144 offset:3072
	s_add_u32 s42, s36, 0x100
	s_addc_u32 s43, s37, 0
	s_cmp_eq_u32 s54, 8
	s_cselect_b32 s47, s21, s43
	s_cselect_b32 s46, s20, s42
	s_cselect_b32 s45, s1, s29
	s_cselect_b32 s44, s0, s28
	v_lshl_add_u64 v[144:145], s[36:37], 0, v[140:141]
	s_add_i32 m0, s34, 0xc000
	ds_read_b128 v[188:191], v170
	ds_read_b128 v[192:195], v170 offset:1024
	ds_read_b128 v[196:199], v170 offset:2048
	ds_read_b128 v[210:213], v170 offset:3072
	ds_read_b128 v[214:217], v170 offset:4096
	ds_read_b128 v[218:221], v170 offset:5120
	ds_read_b128 v[222:225], v170 offset:6144
	ds_read_b128 v[226:229], v170 offset:7168
	global_load_lds_dwordx4 v[144:145], off
	v_lshl_add_u64 v[144:145], s[36:37], 0, v[142:143]
	s_add_i32 m0, s34, 0xe000
	s_nop 0
	global_load_lds_dwordx4 v[144:145], off
	s_waitcnt lgkmcnt(8)
	s_barrier
	s_waitcnt lgkmcnt(0)
	v_mfma_f32_16x16x32_bf16 v[126:129], v[172:175], v[188:191], v[126:129]
	v_mfma_f32_16x16x32_bf16 v[122:125], v[180:183], v[188:191], v[122:125]
	v_mfma_f32_16x16x32_bf16 v[110:113], v[172:175], v[196:199], v[110:113]
	v_mfma_f32_16x16x32_bf16 v[106:109], v[180:183], v[196:199], v[106:109]
	v_mfma_f32_16x16x32_bf16 v[94:97], v[172:175], v[214:217], v[94:97]
	v_mfma_f32_16x16x32_bf16 v[90:93], v[180:183], v[214:217], v[90:93]
	v_mfma_f32_16x16x32_bf16 v[78:81], v[172:175], v[222:225], v[78:81]
	v_mfma_f32_16x16x32_bf16 v[74:77], v[180:183], v[222:225], v[74:77]
	v_mfma_f32_16x16x32_bf16 v[126:129], v[176:179], v[192:195], v[126:129]
	v_mfma_f32_16x16x32_bf16 v[122:125], v[184:187], v[192:195], v[122:125]
	v_mfma_f32_16x16x32_bf16 v[110:113], v[176:179], v[210:213], v[110:113]
	v_mfma_f32_16x16x32_bf16 v[106:109], v[184:187], v[210:213], v[106:109]
	v_mfma_f32_16x16x32_bf16 v[94:97], v[176:179], v[218:221], v[94:97]
	v_mfma_f32_16x16x32_bf16 v[90:93], v[184:187], v[218:221], v[90:93]
	v_mfma_f32_16x16x32_bf16 v[78:81], v[176:179], v[226:229], v[78:81]
	v_mfma_f32_16x16x32_bf16 v[74:77], v[184:187], v[226:229], v[74:77]
	s_barrier
	v_add_u32_e32 v144, s25, v1
	s_add_i32 s23, s24, s13
	ds_read_b128 v[230:233], v144
	ds_read_b128 v[234:237], v144 offset:1024
	ds_read_b128 v[238:241], v144 offset:2048
	ds_read_b128 v[242:245], v144 offset:3072
	v_lshl_add_u64 v[144:145], s[44:45], 0, v[132:133]
	s_mov_b32 m0, s23
	v_lshl_add_u64 v[246:247], s[44:45], 0, v[136:137]
	global_load_lds_dwordx4 v[144:145], off
	s_add_i32 m0, s23, 0x2000
	s_nop 0
	global_load_lds_dwordx4 v[246:247], off
	s_barrier
	s_waitcnt lgkmcnt(0)
	v_mfma_f32_16x16x32_bf16 v[118:121], v[230:233], v[188:191], v[118:121]
	v_mfma_f32_16x16x32_bf16 v[114:117], v[238:241], v[188:191], v[114:117]
	v_mfma_f32_16x16x32_bf16 v[102:105], v[230:233], v[196:199], v[102:105]
	v_mfma_f32_16x16x32_bf16 v[98:101], v[238:241], v[196:199], v[98:101]
	v_mfma_f32_16x16x32_bf16 v[86:89], v[230:233], v[214:217], v[86:89]
	v_mfma_f32_16x16x32_bf16 v[82:85], v[238:241], v[214:217], v[82:85]
	v_mfma_f32_16x16x32_bf16 v[70:73], v[230:233], v[222:225], v[70:73]
	v_mfma_f32_16x16x32_bf16 v[66:69], v[238:241], v[222:225], v[66:69]
	v_mfma_f32_16x16x32_bf16 v[118:121], v[234:237], v[192:195], v[118:121]
	v_mfma_f32_16x16x32_bf16 v[114:117], v[242:245], v[192:195], v[114:117]
	v_mfma_f32_16x16x32_bf16 v[102:105], v[234:237], v[210:213], v[102:105]
	v_mfma_f32_16x16x32_bf16 v[98:101], v[242:245], v[210:213], v[98:101]
	v_mfma_f32_16x16x32_bf16 v[86:89], v[234:237], v[218:221], v[86:89]
	v_mfma_f32_16x16x32_bf16 v[82:85], v[242:245], v[218:221], v[82:85]
	v_mfma_f32_16x16x32_bf16 v[70:73], v[234:237], v[226:229], v[70:73]
	v_mfma_f32_16x16x32_bf16 v[66:69], v[242:245], v[226:229], v[66:69]
	s_mov_b32 m0, s34
	v_lshl_add_u64 v[248:249], s[46:47], 0, v[130:131]
	s_barrier
	ds_read_b128 v[188:191], v170 offset:16384
	ds_read_b128 v[192:195], v170 offset:17408
	ds_read_b128 v[196:199], v170 offset:18432
	ds_read_b128 v[210:213], v170 offset:19456
	ds_read_b128 v[214:217], v170 offset:20480
	ds_read_b128 v[218:221], v170 offset:21504
	ds_read_b128 v[222:225], v170 offset:22528
	ds_read_b128 v[226:229], v170 offset:23552
	global_load_lds_dwordx4 v[248:249], off
	v_lshl_add_u64 v[250:251], s[46:47], 0, v[134:135]
	s_mov_b32 m0, s35
	s_nop 0
	global_load_lds_dwordx4 v[250:251], off
	s_barrier
	s_waitcnt lgkmcnt(0)
	v_mfma_f32_16x16x32_bf16 v[62:65], v[172:175], v[188:191], v[62:65]
	v_mfma_f32_16x16x32_bf16 v[58:61], v[180:183], v[188:191], v[58:61]
	v_mfma_f32_16x16x32_bf16 v[46:49], v[172:175], v[196:199], v[46:49]
	v_mfma_f32_16x16x32_bf16 v[42:45], v[180:183], v[196:199], v[42:45]
	v_mfma_f32_16x16x32_bf16 v[30:33], v[172:175], v[214:217], v[30:33]
	v_mfma_f32_16x16x32_bf16 v[26:29], v[180:183], v[214:217], v[26:29]
	v_mfma_f32_16x16x32_bf16 v[14:17], v[172:175], v[222:225], v[14:17]
	v_mfma_f32_16x16x32_bf16 v[10:13], v[180:183], v[222:225], v[10:13]
	v_mfma_f32_16x16x32_bf16 v[62:65], v[176:179], v[192:195], v[62:65]
	v_mfma_f32_16x16x32_bf16 v[58:61], v[184:187], v[192:195], v[58:61]
	v_mfma_f32_16x16x32_bf16 v[46:49], v[176:179], v[210:213], v[46:49]
	v_mfma_f32_16x16x32_bf16 v[42:45], v[184:187], v[210:213], v[42:45]
	v_mfma_f32_16x16x32_bf16 v[30:33], v[176:179], v[218:221], v[30:33]
	v_mfma_f32_16x16x32_bf16 v[26:29], v[184:187], v[218:221], v[26:29]
	v_mfma_f32_16x16x32_bf16 v[14:17], v[176:179], v[226:229], v[14:17]
	v_mfma_f32_16x16x32_bf16 v[10:13], v[184:187], v[226:229], v[10:13]
	s_barrier
; #define PG8_STAGE(bufoff, gbase, voff) do { _Pragma("unroll") for (int _i = 0; _i < 2; ++_i) \
;         __builtin_amdgcn_global_load_lds((const unsigned*)((const char*)(gbase) + (voff)[_i]), (LAS unsigned*)(lds + (bufoff) + ldsw + _i * 8192), 16, 0, 0); } while (0)
; #define PG8_LDA(dst, b, h) do { _Pragma("unroll") for (int m = 0; m < 4; ++m) _Pragma("unroll") for (int k = 0; k < 2; ++k) dst[m][k] = *(const LAS bf16x8*)(lds + PG8_SA(b, h) + aoff + m * 2048 + k * 1024); } while (0)
; #define PG8_LDB(dst, b, h) do { _Pragma("unroll") for (int n = 0; n < 2; ++n) _Pragma("unroll") for (int k = 0; k < 2; ++k) dst[n][k] = *(const LAS bf16x8*)(lds + PG8_SB(b, h) + boff + n * 2048 + k * 1024); } while (0)
; #define PG8_MMA(ai, bj, At, Bt) do { __builtin_amdgcn_s_setprio(1); _Pragma("unroll") for (int m = 0; m < 4; ++m) _Pragma("unroll") for (int n = 0; n < 2; ++n) _Pragma("unroll") for (int k = 0; k < 2; ++k) \
;         acc[ai][bj][m][n] = __builtin_amdgcn_mfma_f32_16x16x32_bf16(Bt[n][k], At[m][k], acc[ai][bj][m][n], 0, 0, 0); __builtin_amdgcn_s_setprio(0); } while (0)
; #define PG8_WAIT_V(n) asm volatile("s_waitcnt vmcnt(" #n ")" ::: "memory")
; #define PG8_WAIT_L(n) asm volatile("s_waitcnt lgkmcnt(" #n ")" ::: "memory")
; #define PG8_BAR __builtin_amdgcn_s_barrier()
; #define PG8_SCHED __builtin_amdgcn_sched_barrier(0)
; template <class Epi, class Sched>
; __device__ __forceinline__ void gemm_phase(LAS unsigned char* lds, const Gemm g, const Sched& S, const Epi& E) {
;     ...
;             PG8_STAGE(PG8_SB(0, 1), b2 + hstepB, voffB);
;             PG8_WAIT_V(6); PG8_BAR; PG8_MMA(1, 1, At, B1); PG8_BAR;
;             PG8_LDB(B0, 1, 0); PG8_SCHED; PG8_LDA(At, 1, 0); PG8_STAGE(PG8_SA(0, 1), a2 + hstepA, voffA);
;             PG8_WAIT_L(8); PG8_BAR; PG8_WAIT_L(0); PG8_MMA(0, 0, At, B0); PG8_BAR; PG8_SCHED;
;             PG8_LDB(B1, 1, 1); PG8_STAGE(PG8_SB(1, 0), b3, voffB);
;             PG8_BAR; PG8_WAIT_L(0); PG8_MMA(0, 1, At, B1); PG8_BAR;
;             PG8_LDA(At, 1, 1); PG8_STAGE(PG8_SA(1, 0), a3, voffA);
;             PG8_BAR; PG8_WAIT_L(0); PG8_MMA(1, 0, At, B0); PG8_BAR; PG8_SCHED;
	s_add_u32 s36, s44, 0x30000
	s_addc_u32 s37, s45, 0
	s_add_i32 s23, s25, s13
	v_lshl_add_u64 v[172:173], s[36:37], 0, v[132:133]
	s_mov_b32 m0, s23
	s_nop 0
	global_load_lds_dwordx4 v[172:173], off
	v_lshl_add_u64 v[172:173], s[36:37], 0, v[136:137]
	s_add_i32 m0, s23, 0x2000
	s_nop 0
	global_load_lds_dwordx4 v[172:173], off
	s_waitcnt vmcnt(6)
	s_barrier
	v_mfma_f32_16x16x32_bf16 v[54:57], v[230:233], v[188:191], v[54:57]
	v_mfma_f32_16x16x32_bf16 v[50:53], v[238:241], v[188:191], v[50:53]
	v_mfma_f32_16x16x32_bf16 v[38:41], v[230:233], v[196:199], v[38:41]
	v_mfma_f32_16x16x32_bf16 v[34:37], v[238:241], v[196:199], v[34:37]
	v_mfma_f32_16x16x32_bf16 v[22:25], v[230:233], v[214:217], v[22:25]
	v_mfma_f32_16x16x32_bf16 v[18:21], v[238:241], v[214:217], v[18:21]
	v_mfma_f32_16x16x32_bf16 v[6:9], v[230:233], v[222:225], v[6:9]
	v_mfma_f32_16x16x32_bf16 v[2:5], v[238:241], v[222:225], v[2:5]
	v_mfma_f32_16x16x32_bf16 v[54:57], v[234:237], v[192:195], v[54:57]
	v_mfma_f32_16x16x32_bf16 v[50:53], v[242:245], v[192:195], v[50:53]
	v_mfma_f32_16x16x32_bf16 v[38:41], v[234:237], v[210:213], v[38:41]
	v_mfma_f32_16x16x32_bf16 v[34:37], v[242:245], v[210:213], v[34:37]
	v_mfma_f32_16x16x32_bf16 v[22:25], v[234:237], v[218:221], v[22:25]
	v_mfma_f32_16x16x32_bf16 v[18:21], v[242:245], v[218:221], v[18:21]
	v_mfma_f32_16x16x32_bf16 v[6:9], v[234:237], v[226:229], v[6:9]
	v_mfma_f32_16x16x32_bf16 v[2:5], v[242:245], v[226:229], v[2:5]
	v_add_u32_e32 v171, s27, v1
	s_barrier
	ds_read_b128 v[172:175], v171
	ds_read_b128 v[176:179], v171 offset:1024
	ds_read_b128 v[180:183], v171 offset:2048
	ds_read_b128 v[184:187], v171 offset:3072
	s_add_u32 s36, s46, 0x30000
	s_addc_u32 s37, s47, 0
	s_mov_b32 m0, s48
	v_lshl_add_u64 v[230:231], s[36:37], 0, v[130:131]
	ds_read_b128 v[188:191], v170 offset:32768
	ds_read_b128 v[192:195], v170 offset:33792
	ds_read_b128 v[196:199], v170 offset:34816
	ds_read_b128 v[210:213], v170 offset:35840
	ds_read_b128 v[214:217], v170 offset:36864
	ds_read_b128 v[218:221], v170 offset:37888
	ds_read_b128 v[222:225], v170 offset:38912
	ds_read_b128 v[226:229], v170 offset:39936
	global_load_lds_dwordx4 v[230:231], off
	v_lshl_add_u64 v[230:231], s[36:37], 0, v[134:135]
	s_mov_b32 m0, s49
	s_nop 0
	global_load_lds_dwordx4 v[230:231], off
	s_waitcnt lgkmcnt(8)
	s_barrier
	s_waitcnt lgkmcnt(0)
	v_mfma_f32_16x16x32_bf16 v[126:129], v[172:175], v[188:191], v[126:129]
	v_mfma_f32_16x16x32_bf16 v[122:125], v[180:183], v[188:191], v[122:125]
	v_mfma_f32_16x16x32_bf16 v[110:113], v[172:175], v[196:199], v[110:113]
	v_mfma_f32_16x16x32_bf16 v[106:109], v[180:183], v[196:199], v[106:109]
	v_mfma_f32_16x16x32_bf16 v[94:97], v[172:175], v[214:217], v[94:97]
	v_mfma_f32_16x16x32_bf16 v[90:93], v[180:183], v[214:217], v[90:93]
	v_mfma_f32_16x16x32_bf16 v[78:81], v[172:175], v[222:225], v[78:81]
	v_mfma_f32_16x16x32_bf16 v[74:77], v[180:183], v[222:225], v[74:77]
	v_mfma_f32_16x16x32_bf16 v[126:129], v[176:179], v[192:195], v[126:129]
	v_mfma_f32_16x16x32_bf16 v[122:125], v[184:187], v[192:195], v[122:125]
	v_mfma_f32_16x16x32_bf16 v[110:113], v[176:179], v[210:213], v[110:113]
	v_mfma_f32_16x16x32_bf16 v[106:109], v[184:187], v[210:213], v[106:109]
	v_mfma_f32_16x16x32_bf16 v[94:97], v[176:179], v[218:221], v[94:97]
	v_mfma_f32_16x16x32_bf16 v[90:93], v[184:187], v[218:221], v[90:93]
	v_mfma_f32_16x16x32_bf16 v[78:81], v[176:179], v[226:229], v[78:81]
	v_mfma_f32_16x16x32_bf16 v[74:77], v[184:187], v[226:229], v[74:77]
	s_barrier
	s_add_i32 s23, s27, s13
	v_add_u32_e32 v171, s31, v1
	v_lshl_add_u64 v[144:145], v[144:145], 0, s[10:11]
	s_mov_b32 m0, s23
	ds_read_b128 v[230:233], v171
	ds_read_b128 v[234:237], v171 offset:1024
	ds_read_b128 v[238:241], v171 offset:2048
	ds_read_b128 v[242:245], v171 offset:3072
	global_load_lds_dwordx4 v[144:145], off
	v_lshl_add_u64 v[144:145], v[246:247], 0, s[10:11]
	s_add_i32 m0, s23, 0x2000
	s_nop 0
	global_load_lds_dwordx4 v[144:145], off
	s_barrier
	s_waitcnt lgkmcnt(0)
	v_mfma_f32_16x16x32_bf16 v[118:121], v[230:233], v[188:191], v[118:121]
	v_mfma_f32_16x16x32_bf16 v[114:117], v[238:241], v[188:191], v[114:117]
	v_mfma_f32_16x16x32_bf16 v[102:105], v[230:233], v[196:199], v[102:105]
	v_mfma_f32_16x16x32_bf16 v[98:101], v[238:241], v[196:199], v[98:101]
	v_mfma_f32_16x16x32_bf16 v[86:89], v[230:233], v[214:217], v[86:89]
	v_mfma_f32_16x16x32_bf16 v[82:85], v[238:241], v[214:217], v[82:85]
	v_mfma_f32_16x16x32_bf16 v[70:73], v[230:233], v[222:225], v[70:73]
	v_mfma_f32_16x16x32_bf16 v[66:69], v[238:241], v[222:225], v[66:69]
	v_mfma_f32_16x16x32_bf16 v[118:121], v[234:237], v[192:195], v[118:121]
	v_mfma_f32_16x16x32_bf16 v[114:117], v[242:245], v[192:195], v[114:117]
	v_mfma_f32_16x16x32_bf16 v[102:105], v[234:237], v[210:213], v[102:105]
	v_mfma_f32_16x16x32_bf16 v[98:101], v[242:245], v[210:213], v[98:101]
	v_mfma_f32_16x16x32_bf16 v[86:89], v[234:237], v[218:221], v[86:89]
	v_mfma_f32_16x16x32_bf16 v[82:85], v[242:245], v[218:221], v[82:85]
	v_mfma_f32_16x16x32_bf16 v[70:73], v[234:237], v[226:229], v[70:73]
	v_mfma_f32_16x16x32_bf16 v[66:69], v[242:245], v[226:229], v[66:69]
	s_mov_b32 m0, s50
	v_lshl_add_u64 v[144:145], v[248:249], 0, s[10:11]
	s_barrier
	ds_read_b128 v[188:191], v170 offset:49152
	ds_read_b128 v[192:195], v170 offset:50176
	ds_read_b128 v[196:199], v170 offset:51200
	ds_read_b128 v[210:213], v170 offset:52224
	ds_read_b128 v[214:217], v170 offset:53248
	ds_read_b128 v[218:221], v170 offset:54272
	ds_read_b128 v[222:225], v170 offset:55296
	ds_read_b128 v[226:229], v170 offset:56320
	global_load_lds_dwordx4 v[144:145], off
	v_lshl_add_u64 v[144:145], v[250:251], 0, s[10:11]
	s_mov_b32 m0, s51
	s_nop 0
	global_load_lds_dwordx4 v[144:145], off
	s_barrier
; #define LAS __attribute__((address_space(3)))
; __device__ __forceinline__ unsigned cvt_pk_bf16(float lo, float hi) { unsigned r; asm volatile("v_cvt_pk_bf16_f32 %0, %1, %2" : "=v"(r) : "v"(lo), "v"(hi)); return r; }
; __device__ __forceinline__ float gelu_tanh(float x) { const float z = 0.7978845608f * (x + 0.044715f * x * x * x); const float th = 1.0f - 2.0f / (__expf(2.0f * z) + 1.0f); return 0.5f * x * (1.0f + th); }
; #define PG8_STAGE(bufoff, gbase, voff) do { _Pragma("unroll") for (int _i = 0; _i < 2; ++_i) \
;         __builtin_amdgcn_global_load_lds((const unsigned*)((const char*)(gbase) + (voff)[_i]), (LAS unsigned*)(lds + (bufoff) + ldsw + _i * 8192), 16, 0, 0); } while (0)
; #define PG8_WAIT_V(n) asm volatile("s_waitcnt vmcnt(" #n ")" ::: "memory")
; #define PG8_WAIT_L(n) asm volatile("s_waitcnt lgkmcnt(" #n ")" ::: "memory")
; #define PG8_BAR __builtin_amdgcn_s_barrier()
; #define PG8_SCHED __builtin_amdgcn_sched_barrier(0)
;     __device__ __forceinline__ void operator()(const f32x4 (&acc)[2][2][4][2], const Unit& u, int ui, const LAS float* rtab, int wr, int wc, int fr, int fq) const {
;         const int g = u.pm; const int n0 = wr * 64 + fr; const int lc0 = (u.pn & 1) * 256 + wc * 32 + 8 * fq;
; #pragma unroll
;         for (int ai = 0; ai < 2; ++ai)
; #pragma unroll
;             for (int m = 0; m < 4; ++m) {
;                 const int n = n0 + ai * HALF + m * 16;
; #pragma unroll
;                 for (int bj = 0; bj < 2; ++bj) {
;                     const int lc = lc0 + bj * HALF, t = lc >> 4, co = lc & 15; const int token = n * 32 + t;
;                     const f32x4 a0 = acc[ai][bj][m][0], a1 = acc[ai][bj][m][1];
;                     u32x4 w; w.x = cvt_pk_bf16(gelu_tanh(a0[0]), gelu_tanh(a0[1])); w.y = cvt_pk_bf16(gelu_tanh(a0[2]), gelu_tanh(a0[3]));
;                     w.z = cvt_pk_bf16(gelu_tanh(a1[0]), gelu_tanh(a1[1])); w.w = cvt_pk_bf16(gelu_tanh(a1[2]), gelu_tanh(a1[3]));
;                     *(u32x4*)(Y + (size_t)token * 1024 + 16 * g + co) = w;
; template <class Epi, class Sched>
; __device__ __forceinline__ void gemm_phase(LAS unsigned char* lds, const Gemm g, const Sched& S, const Epi& E) {
;     ...
;             PG8_BAR; PG8_WAIT_L(0); PG8_MMA(1, 0, At, B0); PG8_BAR; PG8_SCHED;
;             PG8_STAGE(PG8_SB(1, 1), b3 + hstepB, voffB);
;             PG8_WAIT_V(6); PG8_BAR; PG8_MMA(1, 1, At, B1); PG8_BAR;
;         }
	s_waitcnt lgkmcnt(0)
	v_mfma_f32_16x16x32_bf16 v[62:65], v[172:175], v[188:191], v[62:65]
	v_mfma_f32_16x16x32_bf16 v[58:61], v[180:183], v[188:191], v[58:61]
	v_mfma_f32_16x16x32_bf16 v[46:49], v[172:175], v[196:199], v[46:49]
	v_mfma_f32_16x16x32_bf16 v[42:45], v[180:183], v[196:199], v[42:45]
	v_mfma_f32_16x16x32_bf16 v[30:33], v[172:175], v[214:217], v[30:33]
	v_mfma_f32_16x16x32_bf16 v[26:29], v[180:183], v[214:217], v[26:29]
	v_mfma_f32_16x16x32_bf16 v[14:17], v[172:175], v[222:225], v[14:17]
	v_mfma_f32_16x16x32_bf16 v[10:13], v[180:183], v[222:225], v[10:13]
	v_mfma_f32_16x16x32_bf16 v[62:65], v[176:179], v[192:195], v[62:65]
	v_mfma_f32_16x16x32_bf16 v[58:61], v[184:187], v[192:195], v[58:61]
	v_mfma_f32_16x16x32_bf16 v[46:49], v[176:179], v[210:213], v[46:49]
	v_mfma_f32_16x16x32_bf16 v[42:45], v[184:187], v[210:213], v[42:45]
	v_mfma_f32_16x16x32_bf16 v[30:33], v[176:179], v[218:221], v[30:33]
	v_mfma_f32_16x16x32_bf16 v[26:29], v[184:187], v[218:221], v[26:29]
	v_mfma_f32_16x16x32_bf16 v[14:17], v[176:179], v[226:229], v[14:17]
	v_mfma_f32_16x16x32_bf16 v[10:13], v[184:187], v[226:229], v[10:13]
	s_barrier
	s_add_u32 s36, s44, 0x30080
	s_addc_u32 s37, s45, 0
	s_add_i32 s23, s31, s13
	v_lshl_add_u64 v[144:145], s[36:37], 0, v[132:133]
	s_mov_b32 m0, s23
	s_nop 0
	global_load_lds_dwordx4 v[144:145], off
	v_lshl_add_u64 v[144:145], s[36:37], 0, v[136:137]
	s_add_i32 m0, s23, 0x2000
	s_nop 0
	global_load_lds_dwordx4 v[144:145], off
	s_waitcnt vmcnt(6)
	s_barrier
	v_mfma_f32_16x16x32_bf16 v[54:57], v[230:233], v[188:191], v[54:57]
	v_mfma_f32_16x16x32_bf16 v[50:53], v[238:241], v[188:191], v[50:53]
	v_mfma_f32_16x16x32_bf16 v[38:41], v[230:233], v[196:199], v[38:41]
	v_mfma_f32_16x16x32_bf16 v[34:37], v[238:241], v[196:199], v[34:37]
	v_mfma_f32_16x16x32_bf16 v[22:25], v[230:233], v[214:217], v[22:25]
	v_mfma_f32_16x16x32_bf16 v[18:21], v[238:241], v[214:217], v[18:21]
	v_mfma_f32_16x16x32_bf16 v[6:9], v[230:233], v[222:225], v[6:9]
	v_mfma_f32_16x16x32_bf16 v[2:5], v[238:241], v[222:225], v[2:5]
	v_mfma_f32_16x16x32_bf16 v[54:57], v[234:237], v[192:195], v[54:57]
	v_mfma_f32_16x16x32_bf16 v[50:53], v[242:245], v[192:195], v[50:53]
	v_mfma_f32_16x16x32_bf16 v[38:41], v[234:237], v[210:213], v[38:41]
	v_mfma_f32_16x16x32_bf16 v[34:37], v[242:245], v[210:213], v[34:37]
	v_mfma_f32_16x16x32_bf16 v[22:25], v[234:237], v[218:221], v[22:25]
	v_mfma_f32_16x16x32_bf16 v[18:21], v[242:245], v[218:221], v[18:21]
	v_mfma_f32_16x16x32_bf16 v[6:9], v[234:237], v[226:229], v[6:9]
	v_mfma_f32_16x16x32_bf16 v[2:5], v[242:245], v[226:229], v[2:5]
	s_add_i32 s54, s54, 2
	s_add_u32 s28, s28, 0x100
	s_addc_u32 s29, s29, 0
	s_cmp_gt_u32 s54, 9
	s_mov_b64 s[36:37], s[42:43]
	s_barrier
	s_cbranch_scc0 .LBB0_595
	v_mul_f32_e32 v144, 0x3d372713, v126
	v_mul_f32_e32 v144, v126, v144
	v_fma_f32 v144, v126, v144, v126
	v_mul_f32_e32 v144, 0x3f4c422a, v144
	v_add_f32_e32 v144, v144, v144
	v_mul_f32_e32 v144, 0x3fb8aa3b, v144
	v_exp_f32_e32 v144, v144
	v_mul_f32_e32 v126, 0.5, v126
	s_lshl_b32 s23, s26, 8
	s_and_b32 s23, s23, 0x100
	v_add_f32_e32 v145, 1.0, v144
	v_div_scale_f32 v172, s[28:29], v145, v145, 2.0
	v_rcp_f32_e32 v173, v172
	v_or_b32_e32 v144, s23, v162
	v_lshrrev_b32_e32 v171, 4, v144
	v_or_b32_e32 v144, v171, v146
	v_fma_f32 v174, -v172, v173, 1.0
	v_fmac_f32_e32 v173, v174, v173
	v_div_scale_f32 v174, vcc, 2.0, v145, 2.0
	v_mul_f32_e32 v175, v174, v173
	v_mul_f32_e32 v174, 0x3d372713, v127
	v_mul_f32_e32 v174, v127, v174
	v_fma_f32 v174, v127, v174, v127
	v_mul_f32_e32 v174, 0x3f4c422a, v174
	v_add_f32_e32 v174, v174, v174
	v_mul_f32_e32 v174, 0x3fb8aa3b, v174
	v_exp_f32_e32 v174, v174
	v_rcp_f32_e32 v145, v145
	s_nop 0
	v_add_f32_e32 v145, v145, v145
	v_sub_f32_e32 v145, 1.0, v145
	v_add_f32_e32 v172, 1.0, v174
	v_div_scale_f32 v173, s[28:29], v172, v172, 2.0
	v_rcp_f32_e32 v174, v173
	v_add_f32_e32 v145, 1.0, v145
	v_mul_f32_e32 v126, v126, v145
	v_mul_f32_e32 v127, 0.5, v127
	v_fma_f32 v145, -v173, v174, 1.0
	v_fmac_f32_e32 v174, v145, v174
	v_div_scale_f32 v145, vcc, 2.0, v172, 2.0
	v_mul_f32_e32 v175, v145, v174
	v_fma_f32 v176, -v173, v175, v145
	v_mul_f32_e32 v173, 0x3d372713, v128
	v_mul_f32_e32 v173, v128, v173
	v_fma_f32 v173, v128, v173, v128
	v_mul_f32_e32 v173, 0x3f4c422a, v173
	v_add_f32_e32 v173, v173, v173
	v_mul_f32_e32 v173, 0x3fb8aa3b, v173
	v_exp_f32_e32 v173, v173
	v_rcp_f32_e32 v145, v172
	s_nop 0
	v_add_f32_e32 v145, v145, v145
	v_sub_f32_e32 v145, 1.0, v145
	v_add_f32_e32 v172, 1.0, v173
	v_add_f32_e32 v145, 1.0, v145
	v_mul_f32_e32 v127, v127, v145
	v_cvt_pk_bf16_f32 v126, v126, v127
	v_mul_f32_e32 v173, 0x3d372713, v129
	v_mul_f32_e32 v173, v129, v173
	v_fma_f32 v173, v129, v173, v129
	v_mul_f32_e32 v173, 0x3f4c422a, v173
	v_add_f32_e32 v173, v173, v173
	v_mul_f32_e32 v173, 0x3fb8aa3b, v173
	v_exp_f32_e32 v173, v173
	v_rcp_f32_e32 v127, v172
	s_nop 0
	v_add_f32_e32 v127, v127, v127
	v_sub_f32_e32 v127, 1.0, v127
	v_add_f32_e32 v145, 1.0, v173
	v_div_scale_f32 v172, s[28:29], v145, v145, 2.0
	v_rcp_f32_e32 v173, v172
	v_mul_f32_e32 v128, 0.5, v128
	v_add_f32_e32 v127, 1.0, v127
	v_mul_f32_e32 v127, v128, v127
	v_fma_f32 v128, -v172, v173, 1.0
	v_fmac_f32_e32 v173, v128, v173
	v_div_scale_f32 v128, vcc, 2.0, v145, 2.0
	v_mul_f32_e32 v174, v128, v173
	v_fma_f32 v175, -v172, v174, v128
	v_mul_f32_e32 v172, 0x3d372713, v122
	v_mul_f32_e32 v172, v122, v172
	v_fma_f32 v172, v122, v172, v122
	v_mul_f32_e32 v172, 0x3f4c422a, v172
	v_add_f32_e32 v172, v172, v172
	v_mul_f32_e32 v172, 0x3fb8aa3b, v172
	v_exp_f32_e32 v172, v172
	v_rcp_f32_e32 v128, v145
	s_nop 0
	v_add_f32_e32 v128, v128, v128
	v_sub_f32_e32 v128, 1.0, v128
; #define LAS __attribute__((address_space(3)))
; __device__ __forceinline__ unsigned cvt_pk_bf16(float lo, float hi) { unsigned r; asm volatile("v_cvt_pk_bf16_f32 %0, %1, %2" : "=v"(r) : "v"(lo), "v"(hi)); return r; }
; __device__ __forceinline__ float gelu_tanh(float x) { const float z = 0.7978845608f * (x + 0.044715f * x * x * x); const float th = 1.0f - 2.0f / (__expf(2.0f * z) + 1.0f); return 0.5f * x * (1.0f + th); }
;     __device__ __forceinline__ void operator()(const f32x4 (&acc)[2][2][4][2], const Unit& u, int ui, const LAS float* rtab, int wr, int wc, int fr, int fq) const {
;         const int g = u.pm; const int n0 = wr * 64 + fr; const int lc0 = (u.pn & 1) * 256 + wc * 32 + 8 * fq;
; #pragma unroll
;         for (int ai = 0; ai < 2; ++ai)
; #pragma unroll
;             for (int m = 0; m < 4; ++m) {
;                 const int n = n0 + ai * HALF + m * 16;
; #pragma unroll
;                 for (int bj = 0; bj < 2; ++bj) {
;                     const int lc = lc0 + bj * HALF, t = lc >> 4, co = lc & 15; const int token = n * 32 + t;
;                     const f32x4 a0 = acc[ai][bj][m][0], a1 = acc[ai][bj][m][1];
;                     u32x4 w; w.x = cvt_pk_bf16(gelu_tanh(a0[0]), gelu_tanh(a0[1])); w.y = cvt_pk_bf16(gelu_tanh(a0[2]), gelu_tanh(a0[3]));
;                     w.z = cvt_pk_bf16(gelu_tanh(a1[0]), gelu_tanh(a1[1])); w.w = cvt_pk_bf16(gelu_tanh(a1[2]), gelu_tanh(a1[3]));
;                     *(u32x4*)(Y + (size_t)token * 1024 + 16 * g + co) = w;
	v_add_f32_e32 v145, 1.0, v172
	v_mul_f32_e32 v129, 0.5, v129
	v_add_f32_e32 v128, 1.0, v128
	v_mul_f32_e32 v128, v129, v128
	v_cvt_pk_bf16_f32 v127, v127, v128
	v_mul_f32_e32 v172, 0x3d372713, v123
	v_mul_f32_e32 v172, v123, v172
	v_fma_f32 v172, v123, v172, v123
	v_mul_f32_e32 v172, 0x3f4c422a, v172
	v_add_f32_e32 v172, v172, v172
	v_mul_f32_e32 v172, 0x3fb8aa3b, v172
	v_exp_f32_e32 v172, v172
	v_rcp_f32_e32 v128, v145
	s_nop 0
	v_add_f32_e32 v128, v128, v128
	v_sub_f32_e32 v128, 1.0, v128
	v_add_f32_e32 v129, 1.0, v172
	v_mul_f32_e32 v122, 0.5, v122
	v_add_f32_e32 v128, 1.0, v128
	v_mul_f32_e32 v122, v122, v128
	v_mul_f32_e32 v145, 0x3d372713, v124
	v_mul_f32_e32 v145, v124, v145
	v_fma_f32 v145, v124, v145, v124
	v_mul_f32_e32 v145, 0x3f4c422a, v145
	v_add_f32_e32 v145, v145, v145
	v_mul_f32_e32 v145, 0x3fb8aa3b, v145
	v_exp_f32_e32 v145, v145
	v_rcp_f32_e32 v128, v129
	s_nop 0
	v_add_f32_e32 v128, v128, v128
	v_sub_f32_e32 v128, 1.0, v128
	v_add_f32_e32 v129, 1.0, v145
	v_mul_f32_e32 v123, 0.5, v123
	v_add_f32_e32 v128, 1.0, v128
	v_mul_f32_e32 v123, v123, v128
	v_cvt_pk_bf16_f32 v128, v122, v123
	v_mul_f32_e32 v145, 0x3d372713, v125
	v_mul_f32_e32 v145, v125, v145
	v_fma_f32 v145, v125, v145, v125
	v_mul_f32_e32 v145, 0x3f4c422a, v145
	v_add_f32_e32 v145, v145, v145
	v_mul_f32_e32 v145, 0x3fb8aa3b, v145
	v_exp_f32_e32 v145, v145
	v_rcp_f32_e32 v122, v129
	s_nop 0
	v_add_f32_e32 v122, v122, v122
	v_sub_f32_e32 v122, 1.0, v122
	v_add_f32_e32 v123, 1.0, v145
	v_mul_f32_e32 v124, 0.5, v124
	v_add_f32_e32 v122, 1.0, v122
	v_mul_f32_e32 v122, v124, v122
	v_rcp_f32_e32 v123, v123
	s_nop 0
	v_add_f32_e32 v123, v123, v123
	v_sub_f32_e32 v123, 1.0, v123
	v_mul_f32_e32 v124, 0.5, v125
	v_add_f32_e32 v123, 1.0, v123
	v_mul_f32_e32 v123, v124, v123
	v_cvt_pk_bf16_f32 v129, v122, v123
	v_mul_f32_e32 v122, 0x3d372713, v118
	v_mul_f32_e32 v122, v118, v122
	v_fma_f32 v122, v118, v122, v118
	v_mul_f32_e32 v122, 0x3f4c422a, v122
	v_add_f32_e32 v122, v122, v122
	v_mul_f32_e32 v122, 0x3fb8aa3b, v122
	v_exp_f32_e32 v124, v122
	v_ashrrev_i32_e32 v145, 31, v144
	v_lshlrev_b64 v[122:123], 11, v[144:145]
	v_lshl_add_u64 v[122:123], v[138:139], 0, v[122:123]
	v_add_f32_e32 v125, 1.0, v124
	global_store_dwordx4 v[122:123], v[126:129], off
	v_mul_f32_e32 v118, 0.5, v118
	v_or_b32_e32 v124, 8, v171
	v_mul_f32_e32 v127, 0x3d372713, v119
	v_mul_f32_e32 v127, v119, v127
	v_fma_f32 v127, v119, v127, v119
	v_mul_f32_e32 v127, 0x3f4c422a, v127
	v_add_f32_e32 v127, v127, v127
	v_mul_f32_e32 v127, 0x3fb8aa3b, v127
	v_exp_f32_e32 v127, v127
	v_rcp_f32_e32 v123, v125
	s_nop 0
	v_add_f32_e32 v123, v123, v123
	v_add_f32_e32 v125, 1.0, v127
	v_sub_f32_e32 v123, 1.0, v123
	v_add_f32_e32 v123, 1.0, v123
	v_mul_f32_e32 v118, v118, v123
	v_mul_f32_e32 v126, 0x3d372713, v120
	v_mul_f32_e32 v126, v120, v126
	v_fma_f32 v126, v120, v126, v120
	v_mul_f32_e32 v126, 0x3f4c422a, v126
	v_add_f32_e32 v126, v126, v126
	v_mul_f32_e32 v126, 0x3fb8aa3b, v126
	v_exp_f32_e32 v126, v126
	v_rcp_f32_e32 v123, v125
	s_nop 0
	v_add_f32_e32 v123, v123, v123
	v_sub_f32_e32 v123, 1.0, v123
	v_add_f32_e32 v125, 1.0, v126
	v_mul_f32_e32 v119, 0.5, v119
	v_add_f32_e32 v123, 1.0, v123
	v_mul_f32_e32 v119, v119, v123
	v_cvt_pk_bf16_f32 v118, v118, v119
	v_mul_f32_e32 v126, 0x3d372713, v121
	v_mul_f32_e32 v126, v121, v126
	v_fma_f32 v126, v121, v126, v121
	v_mul_f32_e32 v126, 0x3f4c422a, v126
	v_add_f32_e32 v126, v126, v126
	v_mul_f32_e32 v126, 0x3fb8aa3b, v126
	v_exp_f32_e32 v126, v126
	v_rcp_f32_e32 v119, v125
	s_nop 0
	v_add_f32_e32 v119, v119, v119
	v_sub_f32_e32 v119, 1.0, v119
	v_add_f32_e32 v123, 1.0, v126
	v_mul_f32_e32 v120, 0.5, v120
	v_add_f32_e32 v119, 1.0, v119
	v_mul_f32_e32 v119, v120, v119
	v_mul_f32_e32 v125, 0x3d372713, v114
	v_mul_f32_e32 v125, v114, v125
	v_fma_f32 v125, v114, v125, v114
	v_mul_f32_e32 v125, 0x3f4c422a, v125
	v_add_f32_e32 v125, v125, v125
	v_mul_f32_e32 v125, 0x3fb8aa3b, v125
	v_exp_f32_e32 v125, v125
	v_rcp_f32_e32 v120, v123
	s_nop 0
	v_add_f32_e32 v120, v120, v120
	v_sub_f32_e32 v120, 1.0, v120
	v_add_f32_e32 v123, 1.0, v125
	v_mul_f32_e32 v121, 0.5, v121
	v_add_f32_e32 v120, 1.0, v120
	v_mul_f32_e32 v120, v121, v120
	v_cvt_pk_bf16_f32 v119, v119, v120
	v_mul_f32_e32 v125, 0x3d372713, v115
	v_mul_f32_e32 v125, v115, v125
	v_fma_f32 v125, v115, v125, v115
	v_mul_f32_e32 v125, 0x3f4c422a, v125
	v_add_f32_e32 v125, v125, v125
	v_mul_f32_e32 v125, 0x3fb8aa3b, v125
	v_exp_f32_e32 v125, v125
	v_rcp_f32_e32 v120, v123
	s_nop 0
	v_add_f32_e32 v120, v120, v120
	v_sub_f32_e32 v120, 1.0, v120
	v_add_f32_e32 v121, 1.0, v125
	v_mul_f32_e32 v114, 0.5, v114
	v_add_f32_e32 v120, 1.0, v120
	v_mul_f32_e32 v114, v114, v120
	v_mul_f32_e32 v123, 0x3d372713, v116
	v_mul_f32_e32 v123, v116, v123
	v_fma_f32 v123, v116, v123, v116
	v_mul_f32_e32 v123, 0x3f4c422a, v123
	v_add_f32_e32 v123, v123, v123
	v_mul_f32_e32 v123, 0x3fb8aa3b, v123
	v_exp_f32_e32 v123, v123
	v_rcp_f32_e32 v120, v121
	s_nop 0
	v_add_f32_e32 v120, v120, v120
	v_sub_f32_e32 v120, 1.0, v120
	v_add_f32_e32 v121, 1.0, v123
	v_mul_f32_e32 v115, 0.5, v115
	v_add_f32_e32 v120, 1.0, v120
	v_mul_f32_e32 v115, v115, v120
	v_cvt_pk_bf16_f32 v120, v114, v115
	v_mul_f32_e32 v123, 0x3d372713, v117
	v_mul_f32_e32 v123, v117, v123
	v_fma_f32 v123, v117, v123, v117
	v_mul_f32_e32 v123, 0x3f4c422a, v123
	v_add_f32_e32 v123, v123, v123
	v_mul_f32_e32 v123, 0x3fb8aa3b, v123
	v_exp_f32_e32 v123, v123
	v_rcp_f32_e32 v114, v121
	s_nop 0
	v_add_f32_e32 v114, v114, v114
	v_sub_f32_e32 v114, 1.0, v114
	v_add_f32_e32 v115, 1.0, v123
	v_mul_f32_e32 v116, 0.5, v116
	v_add_f32_e32 v114, 1.0, v114
	v_mul_f32_e32 v114, v116, v114
	v_rcp_f32_e32 v115, v115
; #define LAS __attribute__((address_space(3)))
; __device__ __forceinline__ unsigned cvt_pk_bf16(float lo, float hi) { unsigned r; asm volatile("v_cvt_pk_bf16_f32 %0, %1, %2" : "=v"(r) : "v"(lo), "v"(hi)); return r; }
; __device__ __forceinline__ float gelu_tanh(float x) { const float z = 0.7978845608f * (x + 0.044715f * x * x * x); const float th = 1.0f - 2.0f / (__expf(2.0f * z) + 1.0f); return 0.5f * x * (1.0f + th); }
;     __device__ __forceinline__ void operator()(const f32x4 (&acc)[2][2][4][2], const Unit& u, int ui, const LAS float* rtab, int wr, int wc, int fr, int fq) const {
;         const int g = u.pm; const int n0 = wr * 64 + fr; const int lc0 = (u.pn & 1) * 256 + wc * 32 + 8 * fq;
; #pragma unroll
;         for (int ai = 0; ai < 2; ++ai)
; #pragma unroll
;             for (int m = 0; m < 4; ++m) {
;                 const int n = n0 + ai * HALF + m * 16;
; #pragma unroll
;                 for (int bj = 0; bj < 2; ++bj) {
;                     const int lc = lc0 + bj * HALF, t = lc >> 4, co = lc & 15; const int token = n * 32 + t;
;                     const f32x4 a0 = acc[ai][bj][m][0], a1 = acc[ai][bj][m][1];
;                     u32x4 w; w.x = cvt_pk_bf16(gelu_tanh(a0[0]), gelu_tanh(a0[1])); w.y = cvt_pk_bf16(gelu_tanh(a0[2]), gelu_tanh(a0[3]));
;                     w.z = cvt_pk_bf16(gelu_tanh(a1[0]), gelu_tanh(a1[1])); w.w = cvt_pk_bf16(gelu_tanh(a1[2]), gelu_tanh(a1[3]));
;                     *(u32x4*)(Y + (size_t)token * 1024 + 16 * g + co) = w;
	s_nop 0
	v_add_f32_e32 v115, v115, v115
	v_sub_f32_e32 v115, 1.0, v115
	v_mul_f32_e32 v116, 0.5, v117
	v_add_f32_e32 v115, 1.0, v115
	v_mul_f32_e32 v115, v116, v115
	v_mul_f32_e32 v116, 0x3d372713, v110
	v_mul_f32_e32 v116, v110, v116
	v_fma_f32 v116, v110, v116, v110
	v_mul_f32_e32 v116, 0x3f4c422a, v116
	v_add_f32_e32 v116, v116, v116
	v_mul_f32_e32 v116, 0x3fb8aa3b, v116
	v_exp_f32_e32 v116, v116
	v_or_b32_e32 v122, v124, v146
	v_ashrrev_i32_e32 v123, 31, v122
	v_cvt_pk_bf16_f32 v121, v114, v115
	v_add_f32_e32 v116, 1.0, v116
	v_lshlrev_b64 v[114:115], 11, v[122:123]
	v_lshl_add_u64 v[114:115], v[138:139], 0, v[114:115]
	global_store_dwordx4 v[114:115], v[118:121], off
	v_mul_f32_e32 v110, 0.5, v110
	v_mul_f32_e32 v117, 0x3d372713, v111
	v_mul_f32_e32 v117, v111, v117
	v_fma_f32 v117, v111, v117, v111
	v_mul_f32_e32 v117, 0x3f4c422a, v117
	v_add_f32_e32 v117, v117, v117
	v_mul_f32_e32 v117, 0x3fb8aa3b, v117
	v_exp_f32_e32 v117, v117
	v_rcp_f32_e32 v115, v116
	s_nop 0
	v_add_f32_e32 v115, v115, v115
	v_sub_f32_e32 v115, 1.0, v115
	v_add_f32_e32 v116, 1.0, v117
	v_add_f32_e32 v115, 1.0, v115
	v_mul_f32_e32 v110, v110, v115
	v_mul_f32_e32 v111, 0.5, v111
	v_mul_f32_e32 v117, 0x3d372713, v112
	v_mul_f32_e32 v117, v112, v117
	v_fma_f32 v117, v112, v117, v112
	v_mul_f32_e32 v117, 0x3f4c422a, v117
	v_add_f32_e32 v117, v117, v117
	v_mul_f32_e32 v117, 0x3fb8aa3b, v117
	v_exp_f32_e32 v117, v117
	v_rcp_f32_e32 v115, v116
	s_nop 0
	v_add_f32_e32 v115, v115, v115
	v_sub_f32_e32 v115, 1.0, v115
	v_add_f32_e32 v116, 1.0, v117
	v_add_f32_e32 v115, 1.0, v115
	v_mul_f32_e32 v111, v111, v115
	v_cvt_pk_bf16_f32 v110, v110, v111
	v_mul_f32_e32 v117, 0x3d372713, v113
	v_mul_f32_e32 v117, v113, v117
	v_fma_f32 v117, v113, v117, v113
	v_mul_f32_e32 v117, 0x3f4c422a, v117
	v_add_f32_e32 v117, v117, v117
	v_mul_f32_e32 v117, 0x3fb8aa3b, v117
	v_exp_f32_e32 v117, v117
	v_rcp_f32_e32 v111, v116
	s_nop 0
	v_add_f32_e32 v111, v111, v111
	v_sub_f32_e32 v111, 1.0, v111
	v_add_f32_e32 v115, 1.0, v117
	v_mul_f32_e32 v112, 0.5, v112
	v_add_f32_e32 v111, 1.0, v111
	v_mul_f32_e32 v111, v112, v111
	v_mul_f32_e32 v116, 0x3d372713, v106
	v_mul_f32_e32 v116, v106, v116
	v_fma_f32 v116, v106, v116, v106
	v_mul_f32_e32 v116, 0x3f4c422a, v116
	v_add_f32_e32 v116, v116, v116
	v_mul_f32_e32 v116, 0x3fb8aa3b, v116
	v_exp_f32_e32 v116, v116
	v_rcp_f32_e32 v112, v115
	s_nop 0
	v_add_f32_e32 v112, v112, v112
	v_sub_f32_e32 v112, 1.0, v112
	v_add_f32_e32 v115, 1.0, v116
	v_mul_f32_e32 v113, 0.5, v113
	v_add_f32_e32 v112, 1.0, v112
	v_mul_f32_e32 v112, v113, v112
	v_cvt_pk_bf16_f32 v111, v111, v112
	v_mul_f32_e32 v116, 0x3d372713, v107
	v_mul_f32_e32 v116, v107, v116
	v_fma_f32 v116, v107, v116, v107
	v_mul_f32_e32 v116, 0x3f4c422a, v116
	v_add_f32_e32 v116, v116, v116
	v_mul_f32_e32 v116, 0x3fb8aa3b, v116
	v_exp_f32_e32 v116, v116
	v_rcp_f32_e32 v112, v115
	s_nop 0
	v_add_f32_e32 v112, v112, v112
	v_sub_f32_e32 v112, 1.0, v112
	v_add_f32_e32 v113, 1.0, v116
	v_mul_f32_e32 v106, 0.5, v106
	v_add_f32_e32 v112, 1.0, v112
	v_mul_f32_e32 v106, v106, v112
	v_mul_f32_e32 v115, 0x3d372713, v108
	v_mul_f32_e32 v115, v108, v115
	v_fma_f32 v115, v108, v115, v108
	v_mul_f32_e32 v115, 0x3f4c422a, v115
	v_add_f32_e32 v115, v115, v115
	v_mul_f32_e32 v115, 0x3fb8aa3b, v115
	v_exp_f32_e32 v115, v115
	v_rcp_f32_e32 v112, v113
	s_nop 0
	v_add_f32_e32 v112, v112, v112
	v_sub_f32_e32 v112, 1.0, v112
	v_add_f32_e32 v113, 1.0, v115
	v_mul_f32_e32 v107, 0.5, v107
	v_add_f32_e32 v112, 1.0, v112
	v_mul_f32_e32 v107, v107, v112
	v_cvt_pk_bf16_f32 v112, v106, v107
	v_mul_f32_e32 v115, 0x3d372713, v109
	v_mul_f32_e32 v115, v109, v115
	v_fma_f32 v115, v109, v115, v109
	v_mul_f32_e32 v115, 0x3f4c422a, v115
	v_add_f32_e32 v115, v115, v115
	v_mul_f32_e32 v115, 0x3fb8aa3b, v115
	v_exp_f32_e32 v115, v115
	v_rcp_f32_e32 v106, v113
	s_nop 0
	v_add_f32_e32 v106, v106, v106
	v_sub_f32_e32 v106, 1.0, v106
	v_add_f32_e32 v107, 1.0, v115
	v_mul_f32_e32 v108, 0.5, v108
	v_add_f32_e32 v106, 1.0, v106
	v_mul_f32_e32 v106, v108, v106
	v_rcp_f32_e32 v107, v107
	s_nop 0
	v_add_f32_e32 v107, v107, v107
	v_sub_f32_e32 v107, 1.0, v107
	v_mul_f32_e32 v108, 0.5, v109
	v_add_f32_e32 v107, 1.0, v107
	v_mul_f32_e32 v107, v108, v107
	v_mul_f32_e32 v108, 0x3d372713, v102
	v_mul_f32_e32 v108, v102, v108
	v_fma_f32 v108, v102, v108, v102
	v_mul_f32_e32 v108, 0x3f4c422a, v108
	v_add_f32_e32 v108, v108, v108
	v_mul_f32_e32 v108, 0x3fb8aa3b, v108
	v_exp_f32_e32 v108, v108
	v_or_b32_e32 v114, v171, v147
	v_ashrrev_i32_e32 v115, 31, v114
	v_cvt_pk_bf16_f32 v113, v106, v107
	v_add_f32_e32 v108, 1.0, v108
	v_lshlrev_b64 v[106:107], 11, v[114:115]
	v_lshl_add_u64 v[106:107], v[138:139], 0, v[106:107]
	global_store_dwordx4 v[106:107], v[110:113], off
	v_mul_f32_e32 v102, 0.5, v102
	v_mul_f32_e32 v109, 0x3d372713, v103
	v_mul_f32_e32 v109, v103, v109
	v_fma_f32 v109, v103, v109, v103
	v_mul_f32_e32 v109, 0x3f4c422a, v109
	v_add_f32_e32 v109, v109, v109
	v_mul_f32_e32 v109, 0x3fb8aa3b, v109
	v_exp_f32_e32 v109, v109
	v_rcp_f32_e32 v107, v108
	s_nop 0
	v_add_f32_e32 v107, v107, v107
	v_sub_f32_e32 v107, 1.0, v107
	v_add_f32_e32 v108, 1.0, v109
	v_add_f32_e32 v107, 1.0, v107
	v_mul_f32_e32 v102, v102, v107
	v_mul_f32_e32 v103, 0.5, v103
	v_mul_f32_e32 v109, 0x3d372713, v104
	v_mul_f32_e32 v109, v104, v109
	v_fma_f32 v109, v104, v109, v104
	v_mul_f32_e32 v109, 0x3f4c422a, v109
	v_add_f32_e32 v109, v109, v109
	v_mul_f32_e32 v109, 0x3fb8aa3b, v109
	v_exp_f32_e32 v109, v109
	v_rcp_f32_e32 v107, v108
	s_nop 0
	v_add_f32_e32 v107, v107, v107
	v_sub_f32_e32 v107, 1.0, v107
	v_add_f32_e32 v108, 1.0, v109
	v_add_f32_e32 v107, 1.0, v107
	v_mul_f32_e32 v103, v103, v107
; #define LAS __attribute__((address_space(3)))
; __device__ __forceinline__ unsigned cvt_pk_bf16(float lo, float hi) { unsigned r; asm volatile("v_cvt_pk_bf16_f32 %0, %1, %2" : "=v"(r) : "v"(lo), "v"(hi)); return r; }
; __device__ __forceinline__ float gelu_tanh(float x) { const float z = 0.7978845608f * (x + 0.044715f * x * x * x); const float th = 1.0f - 2.0f / (__expf(2.0f * z) + 1.0f); return 0.5f * x * (1.0f + th); }
;     __device__ __forceinline__ void operator()(const f32x4 (&acc)[2][2][4][2], const Unit& u, int ui, const LAS float* rtab, int wr, int wc, int fr, int fq) const {
;         const int g = u.pm; const int n0 = wr * 64 + fr; const int lc0 = (u.pn & 1) * 256 + wc * 32 + 8 * fq;
; #pragma unroll
;         for (int ai = 0; ai < 2; ++ai)
; #pragma unroll
;             for (int m = 0; m < 4; ++m) {
;                 const int n = n0 + ai * HALF + m * 16;
; #pragma unroll
;                 for (int bj = 0; bj < 2; ++bj) {
;                     const int lc = lc0 + bj * HALF, t = lc >> 4, co = lc & 15; const int token = n * 32 + t;
;                     const f32x4 a0 = acc[ai][bj][m][0], a1 = acc[ai][bj][m][1];
;                     u32x4 w; w.x = cvt_pk_bf16(gelu_tanh(a0[0]), gelu_tanh(a0[1])); w.y = cvt_pk_bf16(gelu_tanh(a0[2]), gelu_tanh(a0[3]));
;                     w.z = cvt_pk_bf16(gelu_tanh(a1[0]), gelu_tanh(a1[1])); w.w = cvt_pk_bf16(gelu_tanh(a1[2]), gelu_tanh(a1[3]));
;                     *(u32x4*)(Y + (size_t)token * 1024 + 16 * g + co) = w;
	v_cvt_pk_bf16_f32 v102, v102, v103
	v_mul_f32_e32 v109, 0x3d372713, v105
	v_mul_f32_e32 v109, v105, v109
	v_fma_f32 v109, v105, v109, v105
	v_mul_f32_e32 v109, 0x3f4c422a, v109
	v_add_f32_e32 v109, v109, v109
	v_mul_f32_e32 v109, 0x3fb8aa3b, v109
	v_exp_f32_e32 v109, v109
	v_rcp_f32_e32 v103, v108
	s_nop 0
	v_add_f32_e32 v103, v103, v103
	v_sub_f32_e32 v103, 1.0, v103
	v_add_f32_e32 v107, 1.0, v109
	v_mul_f32_e32 v104, 0.5, v104
	v_add_f32_e32 v103, 1.0, v103
	v_mul_f32_e32 v103, v104, v103
	v_mul_f32_e32 v108, 0x3d372713, v98
	v_mul_f32_e32 v108, v98, v108
	v_fma_f32 v108, v98, v108, v98
	v_mul_f32_e32 v108, 0x3f4c422a, v108
	v_add_f32_e32 v108, v108, v108
	v_mul_f32_e32 v108, 0x3fb8aa3b, v108
	v_exp_f32_e32 v108, v108
	v_rcp_f32_e32 v104, v107
	s_nop 0
	v_add_f32_e32 v104, v104, v104
	v_sub_f32_e32 v104, 1.0, v104
	v_add_f32_e32 v107, 1.0, v108
	v_mul_f32_e32 v105, 0.5, v105
	v_add_f32_e32 v104, 1.0, v104
	v_mul_f32_e32 v104, v105, v104
	v_cvt_pk_bf16_f32 v103, v103, v104
	v_mul_f32_e32 v108, 0x3d372713, v99
	v_mul_f32_e32 v108, v99, v108
	v_fma_f32 v108, v99, v108, v99
	v_mul_f32_e32 v108, 0x3f4c422a, v108
	v_add_f32_e32 v108, v108, v108
	v_mul_f32_e32 v108, 0x3fb8aa3b, v108
	v_exp_f32_e32 v108, v108
	v_rcp_f32_e32 v104, v107
	s_nop 0
	v_add_f32_e32 v104, v104, v104
	v_sub_f32_e32 v104, 1.0, v104
	v_add_f32_e32 v105, 1.0, v108
	v_mul_f32_e32 v98, 0.5, v98
	v_add_f32_e32 v104, 1.0, v104
	v_mul_f32_e32 v98, v98, v104
	v_mul_f32_e32 v107, 0x3d372713, v100
	v_mul_f32_e32 v107, v100, v107
	v_fma_f32 v107, v100, v107, v100
	v_mul_f32_e32 v107, 0x3f4c422a, v107
	v_add_f32_e32 v107, v107, v107
	v_mul_f32_e32 v107, 0x3fb8aa3b, v107
	v_exp_f32_e32 v107, v107
	v_rcp_f32_e32 v104, v105
	s_nop 0
	v_add_f32_e32 v104, v104, v104
	v_sub_f32_e32 v104, 1.0, v104
	v_add_f32_e32 v105, 1.0, v107
	v_mul_f32_e32 v99, 0.5, v99
	v_add_f32_e32 v104, 1.0, v104
	v_mul_f32_e32 v99, v99, v104
	v_cvt_pk_bf16_f32 v104, v98, v99
	v_mul_f32_e32 v107, 0x3d372713, v101
	v_mul_f32_e32 v107, v101, v107
	v_fma_f32 v107, v101, v107, v101
	v_mul_f32_e32 v107, 0x3f4c422a, v107
	v_add_f32_e32 v107, v107, v107
	v_mul_f32_e32 v107, 0x3fb8aa3b, v107
	v_exp_f32_e32 v107, v107
	v_rcp_f32_e32 v98, v105
	s_nop 0
	v_add_f32_e32 v98, v98, v98
	v_sub_f32_e32 v98, 1.0, v98
	v_add_f32_e32 v99, 1.0, v107
	v_mul_f32_e32 v100, 0.5, v100
	v_add_f32_e32 v98, 1.0, v98
	v_mul_f32_e32 v98, v100, v98
	v_rcp_f32_e32 v99, v99
	s_nop 0
	v_add_f32_e32 v99, v99, v99
	v_sub_f32_e32 v99, 1.0, v99
	v_mul_f32_e32 v100, 0.5, v101
	v_add_f32_e32 v99, 1.0, v99
	v_mul_f32_e32 v99, v100, v99
	v_mul_f32_e32 v100, 0x3d372713, v94
	v_mul_f32_e32 v100, v94, v100
	v_fma_f32 v100, v94, v100, v94
	v_mul_f32_e32 v100, 0x3f4c422a, v100
	v_add_f32_e32 v100, v100, v100
	v_mul_f32_e32 v100, 0x3fb8aa3b, v100
	v_exp_f32_e32 v100, v100
	v_or_b32_e32 v106, v124, v147
	v_ashrrev_i32_e32 v107, 31, v106
	v_cvt_pk_bf16_f32 v105, v98, v99
	v_add_f32_e32 v100, 1.0, v100
	v_lshlrev_b64 v[98:99], 11, v[106:107]
	v_lshl_add_u64 v[98:99], v[138:139], 0, v[98:99]
	global_store_dwordx4 v[98:99], v[102:105], off
	v_mul_f32_e32 v94, 0.5, v94
	v_mul_f32_e32 v101, 0x3d372713, v95
	v_mul_f32_e32 v101, v95, v101
	v_fma_f32 v101, v95, v101, v95
	v_mul_f32_e32 v101, 0x3f4c422a, v101
	v_add_f32_e32 v101, v101, v101
	v_mul_f32_e32 v101, 0x3fb8aa3b, v101
	v_exp_f32_e32 v101, v101
	v_rcp_f32_e32 v99, v100
	s_nop 0
	v_add_f32_e32 v99, v99, v99
	v_sub_f32_e32 v99, 1.0, v99
	v_add_f32_e32 v100, 1.0, v101
	v_add_f32_e32 v99, 1.0, v99
	v_mul_f32_e32 v94, v94, v99
	v_mul_f32_e32 v95, 0.5, v95
	v_mul_f32_e32 v101, 0x3d372713, v96
	v_mul_f32_e32 v101, v96, v101
	v_fma_f32 v101, v96, v101, v96
	v_mul_f32_e32 v101, 0x3f4c422a, v101
	v_add_f32_e32 v101, v101, v101
	v_mul_f32_e32 v101, 0x3fb8aa3b, v101
	v_exp_f32_e32 v101, v101
	v_rcp_f32_e32 v99, v100
	s_nop 0
	v_add_f32_e32 v99, v99, v99
	v_sub_f32_e32 v99, 1.0, v99
	v_add_f32_e32 v100, 1.0, v101
	v_add_f32_e32 v99, 1.0, v99
	v_mul_f32_e32 v95, v95, v99
	v_cvt_pk_bf16_f32 v94, v94, v95
	v_mul_f32_e32 v101, 0x3d372713, v97
	v_mul_f32_e32 v101, v97, v101
	v_fma_f32 v101, v97, v101, v97
	v_mul_f32_e32 v101, 0x3f4c422a, v101
	v_add_f32_e32 v101, v101, v101
	v_mul_f32_e32 v101, 0x3fb8aa3b, v101
	v_exp_f32_e32 v101, v101
	v_rcp_f32_e32 v95, v100
	s_nop 0
	v_add_f32_e32 v95, v95, v95
	v_sub_f32_e32 v95, 1.0, v95
	v_add_f32_e32 v99, 1.0, v101
	v_mul_f32_e32 v96, 0.5, v96
	v_add_f32_e32 v95, 1.0, v95
	v_mul_f32_e32 v95, v96, v95
	v_mul_f32_e32 v100, 0x3d372713, v90
	v_mul_f32_e32 v100, v90, v100
	v_fma_f32 v100, v90, v100, v90
	v_mul_f32_e32 v100, 0x3f4c422a, v100
	v_add_f32_e32 v100, v100, v100
	v_mul_f32_e32 v100, 0x3fb8aa3b, v100
	v_exp_f32_e32 v100, v100
	v_rcp_f32_e32 v96, v99
	s_nop 0
	v_add_f32_e32 v96, v96, v96
	v_sub_f32_e32 v96, 1.0, v96
	v_add_f32_e32 v99, 1.0, v100
	v_mul_f32_e32 v97, 0.5, v97
	v_add_f32_e32 v96, 1.0, v96
	v_mul_f32_e32 v96, v97, v96
	v_cvt_pk_bf16_f32 v95, v95, v96
	v_mul_f32_e32 v100, 0x3d372713, v91
	v_mul_f32_e32 v100, v91, v100
	v_fma_f32 v100, v91, v100, v91
	v_mul_f32_e32 v100, 0x3f4c422a, v100
	v_add_f32_e32 v100, v100, v100
	v_mul_f32_e32 v100, 0x3fb8aa3b, v100
	v_exp_f32_e32 v100, v100
	v_rcp_f32_e32 v96, v99
	s_nop 0
	v_add_f32_e32 v96, v96, v96
	v_sub_f32_e32 v96, 1.0, v96
	v_add_f32_e32 v97, 1.0, v100
	v_mul_f32_e32 v90, 0.5, v90
	v_add_f32_e32 v96, 1.0, v96
	v_mul_f32_e32 v90, v90, v96
	v_mul_f32_e32 v99, 0x3d372713, v92
	v_mul_f32_e32 v99, v92, v99
	v_fma_f32 v99, v92, v99, v92
	v_mul_f32_e32 v99, 0x3f4c422a, v99
	v_add_f32_e32 v99, v99, v99
	v_mul_f32_e32 v99, 0x3fb8aa3b, v99
	v_exp_f32_e32 v99, v99
	v_rcp_f32_e32 v96, v97
	s_nop 0
	v_add_f32_e32 v96, v96, v96
; #define LAS __attribute__((address_space(3)))
; __device__ __forceinline__ unsigned cvt_pk_bf16(float lo, float hi) { unsigned r; asm volatile("v_cvt_pk_bf16_f32 %0, %1, %2" : "=v"(r) : "v"(lo), "v"(hi)); return r; }
; __device__ __forceinline__ float gelu_tanh(float x) { const float z = 0.7978845608f * (x + 0.044715f * x * x * x); const float th = 1.0f - 2.0f / (__expf(2.0f * z) + 1.0f); return 0.5f * x * (1.0f + th); }
;     __device__ __forceinline__ void operator()(const f32x4 (&acc)[2][2][4][2], const Unit& u, int ui, const LAS float* rtab, int wr, int wc, int fr, int fq) const {
;         const int g = u.pm; const int n0 = wr * 64 + fr; const int lc0 = (u.pn & 1) * 256 + wc * 32 + 8 * fq;
; #pragma unroll
;         for (int ai = 0; ai < 2; ++ai)
; #pragma unroll
;             for (int m = 0; m < 4; ++m) {
;                 const int n = n0 + ai * HALF + m * 16;
; #pragma unroll
;                 for (int bj = 0; bj < 2; ++bj) {
;                     const int lc = lc0 + bj * HALF, t = lc >> 4, co = lc & 15; const int token = n * 32 + t;
;                     const f32x4 a0 = acc[ai][bj][m][0], a1 = acc[ai][bj][m][1];
;                     u32x4 w; w.x = cvt_pk_bf16(gelu_tanh(a0[0]), gelu_tanh(a0[1])); w.y = cvt_pk_bf16(gelu_tanh(a0[2]), gelu_tanh(a0[3]));
;                     w.z = cvt_pk_bf16(gelu_tanh(a1[0]), gelu_tanh(a1[1])); w.w = cvt_pk_bf16(gelu_tanh(a1[2]), gelu_tanh(a1[3]));
;                     *(u32x4*)(Y + (size_t)token * 1024 + 16 * g + co) = w;
	v_sub_f32_e32 v96, 1.0, v96
	v_add_f32_e32 v97, 1.0, v99
	v_mul_f32_e32 v91, 0.5, v91
	v_add_f32_e32 v96, 1.0, v96
	v_mul_f32_e32 v91, v91, v96
	v_cvt_pk_bf16_f32 v96, v90, v91
	v_mul_f32_e32 v99, 0x3d372713, v93
	v_mul_f32_e32 v99, v93, v99
	v_fma_f32 v99, v93, v99, v93
	v_mul_f32_e32 v99, 0x3f4c422a, v99
	v_add_f32_e32 v99, v99, v99
	v_mul_f32_e32 v99, 0x3fb8aa3b, v99
	v_exp_f32_e32 v99, v99
	v_rcp_f32_e32 v90, v97
	s_nop 0
	v_add_f32_e32 v90, v90, v90
	v_sub_f32_e32 v90, 1.0, v90
	v_add_f32_e32 v91, 1.0, v99
	v_mul_f32_e32 v92, 0.5, v92
	v_add_f32_e32 v90, 1.0, v90
	v_mul_f32_e32 v90, v92, v90
	v_rcp_f32_e32 v91, v91
	s_nop 0
	v_add_f32_e32 v91, v91, v91
	v_sub_f32_e32 v91, 1.0, v91
	v_mul_f32_e32 v92, 0.5, v93
	v_add_f32_e32 v91, 1.0, v91
	v_mul_f32_e32 v91, v92, v91
	v_mul_f32_e32 v92, 0x3d372713, v86
	v_mul_f32_e32 v92, v86, v92
	v_fma_f32 v92, v86, v92, v86
	v_mul_f32_e32 v92, 0x3f4c422a, v92
	v_add_f32_e32 v92, v92, v92
	v_mul_f32_e32 v92, 0x3fb8aa3b, v92
	v_exp_f32_e32 v92, v92
	v_or_b32_e32 v98, v171, v148
	v_ashrrev_i32_e32 v99, 31, v98
	v_cvt_pk_bf16_f32 v97, v90, v91
	v_add_f32_e32 v92, 1.0, v92
	v_lshlrev_b64 v[90:91], 11, v[98:99]
	v_lshl_add_u64 v[90:91], v[138:139], 0, v[90:91]
	global_store_dwordx4 v[90:91], v[94:97], off
	v_mul_f32_e32 v86, 0.5, v86
	v_mul_f32_e32 v93, 0x3d372713, v87
	v_mul_f32_e32 v93, v87, v93
	v_fma_f32 v93, v87, v93, v87
	v_mul_f32_e32 v93, 0x3f4c422a, v93
	v_add_f32_e32 v93, v93, v93
	v_mul_f32_e32 v93, 0x3fb8aa3b, v93
	v_exp_f32_e32 v93, v93
	v_rcp_f32_e32 v91, v92
	s_nop 0
	v_add_f32_e32 v91, v91, v91
	v_sub_f32_e32 v91, 1.0, v91
	v_add_f32_e32 v92, 1.0, v93
	v_add_f32_e32 v91, 1.0, v91
	v_mul_f32_e32 v86, v86, v91
	v_mul_f32_e32 v87, 0.5, v87
	v_mul_f32_e32 v93, 0x3d372713, v88
	v_mul_f32_e32 v93, v88, v93
	v_fma_f32 v93, v88, v93, v88
	v_mul_f32_e32 v93, 0x3f4c422a, v93
	v_add_f32_e32 v93, v93, v93
	v_mul_f32_e32 v93, 0x3fb8aa3b, v93
	v_exp_f32_e32 v93, v93
	v_rcp_f32_e32 v91, v92
	s_nop 0
	v_add_f32_e32 v91, v91, v91
	v_sub_f32_e32 v91, 1.0, v91
	v_add_f32_e32 v92, 1.0, v93
	v_add_f32_e32 v91, 1.0, v91
	v_mul_f32_e32 v87, v87, v91
	v_cvt_pk_bf16_f32 v86, v86, v87
	v_mul_f32_e32 v93, 0x3d372713, v89
	v_mul_f32_e32 v93, v89, v93
	v_fma_f32 v93, v89, v93, v89
	v_mul_f32_e32 v93, 0x3f4c422a, v93
	v_add_f32_e32 v93, v93, v93
	v_mul_f32_e32 v93, 0x3fb8aa3b, v93
	v_exp_f32_e32 v93, v93
	v_rcp_f32_e32 v87, v92
	s_nop 0
	v_add_f32_e32 v87, v87, v87
	v_sub_f32_e32 v87, 1.0, v87
	v_add_f32_e32 v91, 1.0, v93
	v_mul_f32_e32 v88, 0.5, v88
	v_add_f32_e32 v87, 1.0, v87
	v_mul_f32_e32 v87, v88, v87
	v_mul_f32_e32 v92, 0x3d372713, v82
	v_mul_f32_e32 v92, v82, v92
	v_fma_f32 v92, v82, v92, v82
	v_mul_f32_e32 v92, 0x3f4c422a, v92
	v_add_f32_e32 v92, v92, v92
	v_mul_f32_e32 v92, 0x3fb8aa3b, v92
	v_exp_f32_e32 v92, v92
	v_rcp_f32_e32 v88, v91
	s_nop 0
	v_add_f32_e32 v88, v88, v88
	v_sub_f32_e32 v88, 1.0, v88
	v_add_f32_e32 v91, 1.0, v92
	v_mul_f32_e32 v89, 0.5, v89
	v_add_f32_e32 v88, 1.0, v88
	v_mul_f32_e32 v88, v89, v88
	v_cvt_pk_bf16_f32 v87, v87, v88
	v_mul_f32_e32 v92, 0x3d372713, v83
	v_mul_f32_e32 v92, v83, v92
	v_fma_f32 v92, v83, v92, v83
	v_mul_f32_e32 v92, 0x3f4c422a, v92
	v_add_f32_e32 v92, v92, v92
	v_mul_f32_e32 v92, 0x3fb8aa3b, v92
	v_exp_f32_e32 v92, v92
	v_rcp_f32_e32 v88, v91
	s_nop 0
	v_add_f32_e32 v88, v88, v88
	v_sub_f32_e32 v88, 1.0, v88
	v_add_f32_e32 v89, 1.0, v92
	v_mul_f32_e32 v82, 0.5, v82
	v_add_f32_e32 v88, 1.0, v88
	v_mul_f32_e32 v82, v82, v88
	v_mul_f32_e32 v91, 0x3d372713, v84
	v_mul_f32_e32 v91, v84, v91
	v_fma_f32 v91, v84, v91, v84
	v_mul_f32_e32 v91, 0x3f4c422a, v91
	v_add_f32_e32 v91, v91, v91
	v_mul_f32_e32 v91, 0x3fb8aa3b, v91
	v_exp_f32_e32 v91, v91
	v_rcp_f32_e32 v88, v89
	s_nop 0
	v_add_f32_e32 v88, v88, v88
	v_sub_f32_e32 v88, 1.0, v88
	v_add_f32_e32 v89, 1.0, v91
	v_mul_f32_e32 v83, 0.5, v83
	v_add_f32_e32 v88, 1.0, v88
	v_mul_f32_e32 v83, v83, v88
	v_cvt_pk_bf16_f32 v88, v82, v83
	v_mul_f32_e32 v91, 0x3d372713, v85
	v_mul_f32_e32 v91, v85, v91
	v_fma_f32 v91, v85, v91, v85
	v_mul_f32_e32 v91, 0x3f4c422a, v91
	v_add_f32_e32 v91, v91, v91
	v_mul_f32_e32 v91, 0x3fb8aa3b, v91
	v_exp_f32_e32 v91, v91
	v_rcp_f32_e32 v82, v89
	s_nop 0
	v_add_f32_e32 v82, v82, v82
	v_sub_f32_e32 v82, 1.0, v82
	v_add_f32_e32 v83, 1.0, v91
	v_mul_f32_e32 v84, 0.5, v84
	v_add_f32_e32 v82, 1.0, v82
	v_mul_f32_e32 v82, v84, v82
	v_rcp_f32_e32 v83, v83
	s_nop 0
	v_add_f32_e32 v83, v83, v83
	v_sub_f32_e32 v83, 1.0, v83
	v_mul_f32_e32 v84, 0.5, v85
	v_add_f32_e32 v83, 1.0, v83
	v_mul_f32_e32 v83, v84, v83
	v_mul_f32_e32 v84, 0x3d372713, v78
	v_mul_f32_e32 v84, v78, v84
	v_fma_f32 v84, v78, v84, v78
	v_mul_f32_e32 v84, 0x3f4c422a, v84
	v_add_f32_e32 v84, v84, v84
	v_mul_f32_e32 v84, 0x3fb8aa3b, v84
	v_exp_f32_e32 v84, v84
	v_or_b32_e32 v90, v124, v148
	v_ashrrev_i32_e32 v91, 31, v90
	v_cvt_pk_bf16_f32 v89, v82, v83
	v_add_f32_e32 v84, 1.0, v84
	v_lshlrev_b64 v[82:83], 11, v[90:91]
	v_lshl_add_u64 v[82:83], v[138:139], 0, v[82:83]
	global_store_dwordx4 v[82:83], v[86:89], off
	v_mul_f32_e32 v78, 0.5, v78
	v_mul_f32_e32 v85, 0x3d372713, v79
	v_mul_f32_e32 v85, v79, v85
	v_fma_f32 v85, v79, v85, v79
	v_mul_f32_e32 v85, 0x3f4c422a, v85
	v_add_f32_e32 v85, v85, v85
	v_mul_f32_e32 v85, 0x3fb8aa3b, v85
	v_exp_f32_e32 v85, v85
	v_rcp_f32_e32 v83, v84
	s_nop 0
	v_add_f32_e32 v83, v83, v83
	v_sub_f32_e32 v83, 1.0, v83
	v_add_f32_e32 v84, 1.0, v85
	v_add_f32_e32 v83, 1.0, v83
	v_mul_f32_e32 v78, v78, v83
	v_mul_f32_e32 v79, 0.5, v79
	v_mul_f32_e32 v85, 0x3d372713, v80
	v_mul_f32_e32 v85, v80, v85
	v_fma_f32 v85, v80, v85, v80
	v_mul_f32_e32 v85, 0x3f4c422a, v85
	v_add_f32_e32 v85, v85, v85
	v_mul_f32_e32 v85, 0x3fb8aa3b, v85
; #define LAS __attribute__((address_space(3)))
; __device__ __forceinline__ unsigned cvt_pk_bf16(float lo, float hi) { unsigned r; asm volatile("v_cvt_pk_bf16_f32 %0, %1, %2" : "=v"(r) : "v"(lo), "v"(hi)); return r; }
; __device__ __forceinline__ float gelu_tanh(float x) { const float z = 0.7978845608f * (x + 0.044715f * x * x * x); const float th = 1.0f - 2.0f / (__expf(2.0f * z) + 1.0f); return 0.5f * x * (1.0f + th); }
;     __device__ __forceinline__ void operator()(const f32x4 (&acc)[2][2][4][2], const Unit& u, int ui, const LAS float* rtab, int wr, int wc, int fr, int fq) const {
;         const int g = u.pm; const int n0 = wr * 64 + fr; const int lc0 = (u.pn & 1) * 256 + wc * 32 + 8 * fq;
; #pragma unroll
;         for (int ai = 0; ai < 2; ++ai)
; #pragma unroll
;             for (int m = 0; m < 4; ++m) {
;                 const int n = n0 + ai * HALF + m * 16;
; #pragma unroll
;                 for (int bj = 0; bj < 2; ++bj) {
;                     const int lc = lc0 + bj * HALF, t = lc >> 4, co = lc & 15; const int token = n * 32 + t;
;                     const f32x4 a0 = acc[ai][bj][m][0], a1 = acc[ai][bj][m][1];
;                     u32x4 w; w.x = cvt_pk_bf16(gelu_tanh(a0[0]), gelu_tanh(a0[1])); w.y = cvt_pk_bf16(gelu_tanh(a0[2]), gelu_tanh(a0[3]));
;                     w.z = cvt_pk_bf16(gelu_tanh(a1[0]), gelu_tanh(a1[1])); w.w = cvt_pk_bf16(gelu_tanh(a1[2]), gelu_tanh(a1[3]));
;                     *(u32x4*)(Y + (size_t)token * 1024 + 16 * g + co) = w;
	v_exp_f32_e32 v85, v85
	v_rcp_f32_e32 v83, v84
	s_nop 0
	v_add_f32_e32 v83, v83, v83
	v_sub_f32_e32 v83, 1.0, v83
	v_add_f32_e32 v84, 1.0, v85
	v_add_f32_e32 v83, 1.0, v83
	v_mul_f32_e32 v79, v79, v83
	v_cvt_pk_bf16_f32 v78, v78, v79
	v_mul_f32_e32 v85, 0x3d372713, v81
	v_mul_f32_e32 v85, v81, v85
	v_fma_f32 v85, v81, v85, v81
	v_mul_f32_e32 v85, 0x3f4c422a, v85
	v_add_f32_e32 v85, v85, v85
	v_mul_f32_e32 v85, 0x3fb8aa3b, v85
	v_exp_f32_e32 v85, v85
	v_rcp_f32_e32 v79, v84
	s_nop 0
	v_add_f32_e32 v79, v79, v79
	v_sub_f32_e32 v79, 1.0, v79
	v_add_f32_e32 v83, 1.0, v85
	v_mul_f32_e32 v80, 0.5, v80
	v_add_f32_e32 v79, 1.0, v79
	v_mul_f32_e32 v79, v80, v79
	v_mul_f32_e32 v84, 0x3d372713, v74
	v_mul_f32_e32 v84, v74, v84
	v_fma_f32 v84, v74, v84, v74
	v_mul_f32_e32 v84, 0x3f4c422a, v84
	v_add_f32_e32 v84, v84, v84
	v_mul_f32_e32 v84, 0x3fb8aa3b, v84
	v_exp_f32_e32 v84, v84
	v_rcp_f32_e32 v80, v83
	s_nop 0
	v_add_f32_e32 v80, v80, v80
	v_sub_f32_e32 v80, 1.0, v80
	v_add_f32_e32 v83, 1.0, v84
	v_mul_f32_e32 v81, 0.5, v81
	v_add_f32_e32 v80, 1.0, v80
	v_mul_f32_e32 v80, v81, v80
	v_cvt_pk_bf16_f32 v79, v79, v80
	v_mul_f32_e32 v84, 0x3d372713, v75
	v_mul_f32_e32 v84, v75, v84
	v_fma_f32 v84, v75, v84, v75
	v_mul_f32_e32 v84, 0x3f4c422a, v84
	v_add_f32_e32 v84, v84, v84
	v_mul_f32_e32 v84, 0x3fb8aa3b, v84
	v_exp_f32_e32 v84, v84
	v_rcp_f32_e32 v80, v83
	s_nop 0
	v_add_f32_e32 v80, v80, v80
	v_sub_f32_e32 v80, 1.0, v80
	v_add_f32_e32 v81, 1.0, v84
	v_mul_f32_e32 v74, 0.5, v74
	v_add_f32_e32 v80, 1.0, v80
	v_mul_f32_e32 v74, v74, v80
	v_mul_f32_e32 v83, 0x3d372713, v76
	v_mul_f32_e32 v83, v76, v83
	v_fma_f32 v83, v76, v83, v76
	v_mul_f32_e32 v83, 0x3f4c422a, v83
	v_add_f32_e32 v83, v83, v83
	v_mul_f32_e32 v83, 0x3fb8aa3b, v83
	v_exp_f32_e32 v83, v83
	v_rcp_f32_e32 v80, v81
	s_nop 0
	v_add_f32_e32 v80, v80, v80
	v_sub_f32_e32 v80, 1.0, v80
	v_add_f32_e32 v81, 1.0, v83
	v_mul_f32_e32 v75, 0.5, v75
	v_add_f32_e32 v80, 1.0, v80
	v_mul_f32_e32 v75, v75, v80
	v_cvt_pk_bf16_f32 v80, v74, v75
	v_mul_f32_e32 v83, 0x3d372713, v77
	v_mul_f32_e32 v83, v77, v83
	v_fma_f32 v83, v77, v83, v77
	v_mul_f32_e32 v83, 0x3f4c422a, v83
	v_add_f32_e32 v83, v83, v83
	v_mul_f32_e32 v83, 0x3fb8aa3b, v83
	v_exp_f32_e32 v83, v83
	v_rcp_f32_e32 v74, v81
	s_nop 0
	v_add_f32_e32 v74, v74, v74
	v_sub_f32_e32 v74, 1.0, v74
	v_add_f32_e32 v75, 1.0, v83
	v_mul_f32_e32 v76, 0.5, v76
	v_add_f32_e32 v74, 1.0, v74
	v_mul_f32_e32 v74, v76, v74
	v_rcp_f32_e32 v75, v75
	s_nop 0
	v_add_f32_e32 v75, v75, v75
	v_sub_f32_e32 v75, 1.0, v75
	v_mul_f32_e32 v76, 0.5, v77
	v_add_f32_e32 v75, 1.0, v75
	v_mul_f32_e32 v75, v76, v75
	v_mul_f32_e32 v76, 0x3d372713, v70
	v_mul_f32_e32 v76, v70, v76
	v_fma_f32 v76, v70, v76, v70
	v_mul_f32_e32 v76, 0x3f4c422a, v76
	v_add_f32_e32 v76, v76, v76
	v_mul_f32_e32 v76, 0x3fb8aa3b, v76
	v_exp_f32_e32 v76, v76
	v_or_b32_e32 v82, v171, v149
	v_ashrrev_i32_e32 v83, 31, v82
	v_cvt_pk_bf16_f32 v81, v74, v75
	v_add_f32_e32 v76, 1.0, v76
	v_lshlrev_b64 v[74:75], 11, v[82:83]
	v_lshl_add_u64 v[74:75], v[138:139], 0, v[74:75]
	global_store_dwordx4 v[74:75], v[78:81], off
	v_mul_f32_e32 v70, 0.5, v70
	v_mul_f32_e32 v77, 0x3d372713, v71
	v_mul_f32_e32 v77, v71, v77
	v_fma_f32 v77, v71, v77, v71
	v_mul_f32_e32 v77, 0x3f4c422a, v77
	v_add_f32_e32 v77, v77, v77
	v_mul_f32_e32 v77, 0x3fb8aa3b, v77
	v_exp_f32_e32 v77, v77
	v_rcp_f32_e32 v75, v76
	s_nop 0
	v_add_f32_e32 v75, v75, v75
	v_sub_f32_e32 v75, 1.0, v75
	v_add_f32_e32 v76, 1.0, v77
	v_add_f32_e32 v75, 1.0, v75
	v_mul_f32_e32 v70, v70, v75
	v_mul_f32_e32 v71, 0.5, v71
	v_mul_f32_e32 v77, 0x3d372713, v72
	v_mul_f32_e32 v77, v72, v77
	v_fma_f32 v77, v72, v77, v72
	v_mul_f32_e32 v77, 0x3f4c422a, v77
	v_add_f32_e32 v77, v77, v77
	v_mul_f32_e32 v77, 0x3fb8aa3b, v77
	v_exp_f32_e32 v77, v77
	v_rcp_f32_e32 v75, v76
	s_nop 0
	v_add_f32_e32 v75, v75, v75
	v_sub_f32_e32 v75, 1.0, v75
	v_add_f32_e32 v76, 1.0, v77
	v_add_f32_e32 v75, 1.0, v75
	v_mul_f32_e32 v71, v71, v75
	v_cvt_pk_bf16_f32 v70, v70, v71
	v_mul_f32_e32 v77, 0x3d372713, v73
	v_mul_f32_e32 v77, v73, v77
	v_fma_f32 v77, v73, v77, v73
	v_mul_f32_e32 v77, 0x3f4c422a, v77
	v_add_f32_e32 v77, v77, v77
	v_mul_f32_e32 v77, 0x3fb8aa3b, v77
	v_exp_f32_e32 v77, v77
	v_rcp_f32_e32 v71, v76
	s_nop 0
	v_add_f32_e32 v71, v71, v71
	v_sub_f32_e32 v71, 1.0, v71
	v_add_f32_e32 v75, 1.0, v77
	v_mul_f32_e32 v72, 0.5, v72
	v_add_f32_e32 v71, 1.0, v71
	v_mul_f32_e32 v71, v72, v71
	v_mul_f32_e32 v76, 0x3d372713, v66
	v_mul_f32_e32 v76, v66, v76
	v_fma_f32 v76, v66, v76, v66
	v_mul_f32_e32 v76, 0x3f4c422a, v76
	v_add_f32_e32 v76, v76, v76
	v_mul_f32_e32 v76, 0x3fb8aa3b, v76
	v_exp_f32_e32 v76, v76
	v_rcp_f32_e32 v72, v75
	s_nop 0
	v_add_f32_e32 v72, v72, v72
	v_sub_f32_e32 v72, 1.0, v72
	v_add_f32_e32 v75, 1.0, v76
	v_mul_f32_e32 v73, 0.5, v73
	v_add_f32_e32 v72, 1.0, v72
	v_mul_f32_e32 v72, v73, v72
	v_cvt_pk_bf16_f32 v71, v71, v72
	v_mul_f32_e32 v76, 0x3d372713, v67
	v_mul_f32_e32 v76, v67, v76
	v_fma_f32 v76, v67, v76, v67
	v_mul_f32_e32 v76, 0x3f4c422a, v76
	v_add_f32_e32 v76, v76, v76
	v_mul_f32_e32 v76, 0x3fb8aa3b, v76
	v_exp_f32_e32 v76, v76
	v_rcp_f32_e32 v72, v75
	s_nop 0
	v_add_f32_e32 v72, v72, v72
	v_sub_f32_e32 v72, 1.0, v72
	v_add_f32_e32 v73, 1.0, v76
	v_mul_f32_e32 v66, 0.5, v66
	v_add_f32_e32 v72, 1.0, v72
	v_mul_f32_e32 v66, v66, v72
	v_mul_f32_e32 v75, 0x3d372713, v68
	v_mul_f32_e32 v75, v68, v75
	v_fma_f32 v75, v68, v75, v68
	v_mul_f32_e32 v75, 0x3f4c422a, v75
	v_add_f32_e32 v75, v75, v75
	v_mul_f32_e32 v75, 0x3fb8aa3b, v75
	v_exp_f32_e32 v75, v75
	v_rcp_f32_e32 v72, v73
	s_nop 0
	v_add_f32_e32 v72, v72, v72
	v_sub_f32_e32 v72, 1.0, v72
	v_add_f32_e32 v73, 1.0, v75
; #define LAS __attribute__((address_space(3)))
; __device__ __forceinline__ unsigned cvt_pk_bf16(float lo, float hi) { unsigned r; asm volatile("v_cvt_pk_bf16_f32 %0, %1, %2" : "=v"(r) : "v"(lo), "v"(hi)); return r; }
; __device__ __forceinline__ float gelu_tanh(float x) { const float z = 0.7978845608f * (x + 0.044715f * x * x * x); const float th = 1.0f - 2.0f / (__expf(2.0f * z) + 1.0f); return 0.5f * x * (1.0f + th); }
;     __device__ __forceinline__ void operator()(const f32x4 (&acc)[2][2][4][2], const Unit& u, int ui, const LAS float* rtab, int wr, int wc, int fr, int fq) const {
;         const int g = u.pm; const int n0 = wr * 64 + fr; const int lc0 = (u.pn & 1) * 256 + wc * 32 + 8 * fq;
; #pragma unroll
;         for (int ai = 0; ai < 2; ++ai)
; #pragma unroll
;             for (int m = 0; m < 4; ++m) {
;                 const int n = n0 + ai * HALF + m * 16;
; #pragma unroll
;                 for (int bj = 0; bj < 2; ++bj) {
;                     const int lc = lc0 + bj * HALF, t = lc >> 4, co = lc & 15; const int token = n * 32 + t;
;                     const f32x4 a0 = acc[ai][bj][m][0], a1 = acc[ai][bj][m][1];
;                     u32x4 w; w.x = cvt_pk_bf16(gelu_tanh(a0[0]), gelu_tanh(a0[1])); w.y = cvt_pk_bf16(gelu_tanh(a0[2]), gelu_tanh(a0[3]));
;                     w.z = cvt_pk_bf16(gelu_tanh(a1[0]), gelu_tanh(a1[1])); w.w = cvt_pk_bf16(gelu_tanh(a1[2]), gelu_tanh(a1[3]));
;                     *(u32x4*)(Y + (size_t)token * 1024 + 16 * g + co) = w;
	v_mul_f32_e32 v67, 0.5, v67
	v_add_f32_e32 v72, 1.0, v72
	v_mul_f32_e32 v67, v67, v72
	v_cvt_pk_bf16_f32 v72, v66, v67
	v_mul_f32_e32 v75, 0x3d372713, v69
	v_mul_f32_e32 v75, v69, v75
	v_fma_f32 v75, v69, v75, v69
	v_mul_f32_e32 v75, 0x3f4c422a, v75
	v_add_f32_e32 v75, v75, v75
	v_mul_f32_e32 v75, 0x3fb8aa3b, v75
	v_exp_f32_e32 v75, v75
	v_rcp_f32_e32 v66, v73
	s_nop 0
	v_add_f32_e32 v66, v66, v66
	v_sub_f32_e32 v66, 1.0, v66
	v_add_f32_e32 v67, 1.0, v75
	v_mul_f32_e32 v68, 0.5, v68
	v_add_f32_e32 v66, 1.0, v66
	v_mul_f32_e32 v66, v68, v66
	v_rcp_f32_e32 v67, v67
	s_nop 0
	v_add_f32_e32 v67, v67, v67
	v_sub_f32_e32 v67, 1.0, v67
	v_mul_f32_e32 v68, 0.5, v69
	v_add_f32_e32 v67, 1.0, v67
	v_mul_f32_e32 v67, v68, v67
	v_mul_f32_e32 v68, 0x3d372713, v62
	v_mul_f32_e32 v68, v62, v68
	v_fma_f32 v68, v62, v68, v62
	v_mul_f32_e32 v68, 0x3f4c422a, v68
	v_add_f32_e32 v68, v68, v68
	v_mul_f32_e32 v68, 0x3fb8aa3b, v68
	v_exp_f32_e32 v68, v68
	v_or_b32_e32 v74, v124, v149
	v_ashrrev_i32_e32 v75, 31, v74
	v_cvt_pk_bf16_f32 v73, v66, v67
	v_add_f32_e32 v68, 1.0, v68
	v_lshlrev_b64 v[66:67], 11, v[74:75]
	v_lshl_add_u64 v[66:67], v[138:139], 0, v[66:67]
	global_store_dwordx4 v[66:67], v[70:73], off
	v_mul_f32_e32 v62, 0.5, v62
	v_mul_f32_e32 v69, 0x3d372713, v63
	v_mul_f32_e32 v69, v63, v69
	v_fma_f32 v69, v63, v69, v63
	v_mul_f32_e32 v69, 0x3f4c422a, v69
	v_add_f32_e32 v69, v69, v69
	v_mul_f32_e32 v69, 0x3fb8aa3b, v69
	v_exp_f32_e32 v69, v69
	v_rcp_f32_e32 v67, v68
	s_nop 0
	v_add_f32_e32 v67, v67, v67
	v_sub_f32_e32 v67, 1.0, v67
	v_add_f32_e32 v68, 1.0, v69
	v_add_f32_e32 v67, 1.0, v67
	v_mul_f32_e32 v62, v62, v67
	v_mul_f32_e32 v63, 0.5, v63
	v_mul_f32_e32 v69, 0x3d372713, v64
	v_mul_f32_e32 v69, v64, v69
	v_fma_f32 v69, v64, v69, v64
	v_mul_f32_e32 v69, 0x3f4c422a, v69
	v_add_f32_e32 v69, v69, v69
	v_mul_f32_e32 v69, 0x3fb8aa3b, v69
	v_exp_f32_e32 v69, v69
	v_rcp_f32_e32 v67, v68
	s_nop 0
	v_add_f32_e32 v67, v67, v67
	v_sub_f32_e32 v67, 1.0, v67
	v_add_f32_e32 v68, 1.0, v69
	v_add_f32_e32 v67, 1.0, v67
	v_mul_f32_e32 v63, v63, v67
	v_cvt_pk_bf16_f32 v62, v62, v63
	v_mul_f32_e32 v69, 0x3d372713, v65
	v_mul_f32_e32 v69, v65, v69
	v_fma_f32 v69, v65, v69, v65
	v_mul_f32_e32 v69, 0x3f4c422a, v69
	v_add_f32_e32 v69, v69, v69
	v_mul_f32_e32 v69, 0x3fb8aa3b, v69
	v_exp_f32_e32 v69, v69
	v_rcp_f32_e32 v63, v68
	s_nop 0
	v_add_f32_e32 v63, v63, v63
	v_sub_f32_e32 v63, 1.0, v63
	v_add_f32_e32 v67, 1.0, v69
	v_mul_f32_e32 v64, 0.5, v64
	v_add_f32_e32 v63, 1.0, v63
	v_mul_f32_e32 v63, v64, v63
	v_mul_f32_e32 v68, 0x3d372713, v58
	v_mul_f32_e32 v68, v58, v68
	v_fma_f32 v68, v58, v68, v58
	v_mul_f32_e32 v68, 0x3f4c422a, v68
	v_add_f32_e32 v68, v68, v68
	v_mul_f32_e32 v68, 0x3fb8aa3b, v68
	v_exp_f32_e32 v68, v68
	v_rcp_f32_e32 v64, v67
	s_nop 0
	v_add_f32_e32 v64, v64, v64
	v_sub_f32_e32 v64, 1.0, v64
	v_add_f32_e32 v67, 1.0, v68
	v_mul_f32_e32 v65, 0.5, v65
	v_add_f32_e32 v64, 1.0, v64
	v_mul_f32_e32 v64, v65, v64
	v_cvt_pk_bf16_f32 v63, v63, v64
	v_mul_f32_e32 v68, 0x3d372713, v59
	v_mul_f32_e32 v68, v59, v68
	v_fma_f32 v68, v59, v68, v59
	v_mul_f32_e32 v68, 0x3f4c422a, v68
	v_add_f32_e32 v68, v68, v68
	v_mul_f32_e32 v68, 0x3fb8aa3b, v68
	v_exp_f32_e32 v68, v68
	v_rcp_f32_e32 v64, v67
	s_nop 0
	v_add_f32_e32 v64, v64, v64
	v_sub_f32_e32 v64, 1.0, v64
	v_add_f32_e32 v65, 1.0, v68
	v_mul_f32_e32 v58, 0.5, v58
	v_add_f32_e32 v64, 1.0, v64
	v_mul_f32_e32 v58, v58, v64
	v_mul_f32_e32 v67, 0x3d372713, v60
	v_mul_f32_e32 v67, v60, v67
	v_fma_f32 v67, v60, v67, v60
	v_mul_f32_e32 v67, 0x3f4c422a, v67
	v_add_f32_e32 v67, v67, v67
	v_mul_f32_e32 v67, 0x3fb8aa3b, v67
	v_exp_f32_e32 v67, v67
	v_rcp_f32_e32 v64, v65
	s_nop 0
	v_add_f32_e32 v64, v64, v64
	v_sub_f32_e32 v64, 1.0, v64
	v_add_f32_e32 v65, 1.0, v67
	v_mul_f32_e32 v59, 0.5, v59
	v_add_f32_e32 v64, 1.0, v64
	v_mul_f32_e32 v59, v59, v64
	v_cvt_pk_bf16_f32 v64, v58, v59
	v_mul_f32_e32 v67, 0x3d372713, v61
	v_mul_f32_e32 v67, v61, v67
	v_fma_f32 v67, v61, v67, v61
	v_mul_f32_e32 v67, 0x3f4c422a, v67
	v_add_f32_e32 v67, v67, v67
	v_mul_f32_e32 v67, 0x3fb8aa3b, v67
	v_exp_f32_e32 v67, v67
	v_rcp_f32_e32 v58, v65
	s_nop 0
	v_add_f32_e32 v58, v58, v58
	v_sub_f32_e32 v58, 1.0, v58
	v_add_f32_e32 v59, 1.0, v67
	v_mul_f32_e32 v60, 0.5, v60
	v_add_f32_e32 v58, 1.0, v58
	v_mul_f32_e32 v58, v60, v58
	v_rcp_f32_e32 v59, v59
	s_nop 0
	v_add_f32_e32 v59, v59, v59
	v_sub_f32_e32 v59, 1.0, v59
	v_mul_f32_e32 v60, 0.5, v61
	v_add_f32_e32 v59, 1.0, v59
	v_mul_f32_e32 v59, v60, v59
	v_mul_f32_e32 v60, 0x3d372713, v54
	v_mul_f32_e32 v60, v54, v60
	v_fma_f32 v60, v54, v60, v54
	v_mul_f32_e32 v60, 0x3f4c422a, v60
	v_add_f32_e32 v60, v60, v60
	v_mul_f32_e32 v60, 0x3fb8aa3b, v60
	v_exp_f32_e32 v60, v60
	v_or_b32_e32 v66, v171, v150
	v_ashrrev_i32_e32 v67, 31, v66
	v_cvt_pk_bf16_f32 v65, v58, v59
	v_add_f32_e32 v60, 1.0, v60
	v_lshlrev_b64 v[58:59], 11, v[66:67]
	v_lshl_add_u64 v[58:59], v[138:139], 0, v[58:59]
	global_store_dwordx4 v[58:59], v[62:65], off
	v_mul_f32_e32 v54, 0.5, v54
	v_mul_f32_e32 v61, 0x3d372713, v55
	v_mul_f32_e32 v61, v55, v61
	v_fma_f32 v61, v55, v61, v55
	v_mul_f32_e32 v61, 0x3f4c422a, v61
	v_add_f32_e32 v61, v61, v61
	v_mul_f32_e32 v61, 0x3fb8aa3b, v61
	v_exp_f32_e32 v61, v61
	v_rcp_f32_e32 v59, v60
	s_nop 0
	v_add_f32_e32 v59, v59, v59
	v_sub_f32_e32 v59, 1.0, v59
	v_add_f32_e32 v60, 1.0, v61
	v_add_f32_e32 v59, 1.0, v59
	v_mul_f32_e32 v54, v54, v59
	v_mul_f32_e32 v55, 0.5, v55
	v_mul_f32_e32 v61, 0x3d372713, v56
	v_mul_f32_e32 v61, v56, v61
	v_fma_f32 v61, v56, v61, v56
	v_mul_f32_e32 v61, 0x3f4c422a, v61
	v_add_f32_e32 v61, v61, v61
	v_mul_f32_e32 v61, 0x3fb8aa3b, v61
	v_exp_f32_e32 v61, v61
	v_rcp_f32_e32 v59, v60
; #define LAS __attribute__((address_space(3)))
; __device__ __forceinline__ unsigned cvt_pk_bf16(float lo, float hi) { unsigned r; asm volatile("v_cvt_pk_bf16_f32 %0, %1, %2" : "=v"(r) : "v"(lo), "v"(hi)); return r; }
; __device__ __forceinline__ float gelu_tanh(float x) { const float z = 0.7978845608f * (x + 0.044715f * x * x * x); const float th = 1.0f - 2.0f / (__expf(2.0f * z) + 1.0f); return 0.5f * x * (1.0f + th); }
;     __device__ __forceinline__ void operator()(const f32x4 (&acc)[2][2][4][2], const Unit& u, int ui, const LAS float* rtab, int wr, int wc, int fr, int fq) const {
;         const int g = u.pm; const int n0 = wr * 64 + fr; const int lc0 = (u.pn & 1) * 256 + wc * 32 + 8 * fq;
; #pragma unroll
;         for (int ai = 0; ai < 2; ++ai)
; #pragma unroll
;             for (int m = 0; m < 4; ++m) {
;                 const int n = n0 + ai * HALF + m * 16;
; #pragma unroll
;                 for (int bj = 0; bj < 2; ++bj) {
;                     const int lc = lc0 + bj * HALF, t = lc >> 4, co = lc & 15; const int token = n * 32 + t;
;                     const f32x4 a0 = acc[ai][bj][m][0], a1 = acc[ai][bj][m][1];
;                     u32x4 w; w.x = cvt_pk_bf16(gelu_tanh(a0[0]), gelu_tanh(a0[1])); w.y = cvt_pk_bf16(gelu_tanh(a0[2]), gelu_tanh(a0[3]));
;                     w.z = cvt_pk_bf16(gelu_tanh(a1[0]), gelu_tanh(a1[1])); w.w = cvt_pk_bf16(gelu_tanh(a1[2]), gelu_tanh(a1[3]));
;                     *(u32x4*)(Y + (size_t)token * 1024 + 16 * g + co) = w;
	s_nop 0
	v_add_f32_e32 v59, v59, v59
	v_sub_f32_e32 v59, 1.0, v59
	v_add_f32_e32 v60, 1.0, v61
	v_add_f32_e32 v59, 1.0, v59
	v_mul_f32_e32 v55, v55, v59
	v_cvt_pk_bf16_f32 v54, v54, v55
	v_mul_f32_e32 v61, 0x3d372713, v57
	v_mul_f32_e32 v61, v57, v61
	v_fma_f32 v61, v57, v61, v57
	v_mul_f32_e32 v61, 0x3f4c422a, v61
	v_add_f32_e32 v61, v61, v61
	v_mul_f32_e32 v61, 0x3fb8aa3b, v61
	v_exp_f32_e32 v61, v61
	v_rcp_f32_e32 v55, v60
	s_nop 0
	v_add_f32_e32 v55, v55, v55
	v_sub_f32_e32 v55, 1.0, v55
	v_add_f32_e32 v59, 1.0, v61
	v_mul_f32_e32 v56, 0.5, v56
	v_add_f32_e32 v55, 1.0, v55
	v_mul_f32_e32 v55, v56, v55
	v_mul_f32_e32 v60, 0x3d372713, v50
	v_mul_f32_e32 v60, v50, v60
	v_fma_f32 v60, v50, v60, v50
	v_mul_f32_e32 v60, 0x3f4c422a, v60
	v_add_f32_e32 v60, v60, v60
	v_mul_f32_e32 v60, 0x3fb8aa3b, v60
	v_exp_f32_e32 v60, v60
	v_rcp_f32_e32 v56, v59
	s_nop 0
	v_add_f32_e32 v56, v56, v56
	v_sub_f32_e32 v56, 1.0, v56
	v_add_f32_e32 v59, 1.0, v60
	v_mul_f32_e32 v57, 0.5, v57
	v_add_f32_e32 v56, 1.0, v56
	v_mul_f32_e32 v56, v57, v56
	v_cvt_pk_bf16_f32 v55, v55, v56
	v_mul_f32_e32 v60, 0x3d372713, v51
	v_mul_f32_e32 v60, v51, v60
	v_fma_f32 v60, v51, v60, v51
	v_mul_f32_e32 v60, 0x3f4c422a, v60
	v_add_f32_e32 v60, v60, v60
	v_mul_f32_e32 v60, 0x3fb8aa3b, v60
	v_exp_f32_e32 v60, v60
	v_rcp_f32_e32 v56, v59
	s_nop 0
	v_add_f32_e32 v56, v56, v56
	v_sub_f32_e32 v56, 1.0, v56
	v_add_f32_e32 v57, 1.0, v60
	v_mul_f32_e32 v50, 0.5, v50
	v_add_f32_e32 v56, 1.0, v56
	v_mul_f32_e32 v50, v50, v56
	v_mul_f32_e32 v59, 0x3d372713, v52
	v_mul_f32_e32 v59, v52, v59
	v_fma_f32 v59, v52, v59, v52
	v_mul_f32_e32 v59, 0x3f4c422a, v59
	v_add_f32_e32 v59, v59, v59
	v_mul_f32_e32 v59, 0x3fb8aa3b, v59
	v_exp_f32_e32 v59, v59
	v_rcp_f32_e32 v56, v57
	s_nop 0
	v_add_f32_e32 v56, v56, v56
	v_sub_f32_e32 v56, 1.0, v56
	v_add_f32_e32 v57, 1.0, v59
	v_mul_f32_e32 v51, 0.5, v51
	v_add_f32_e32 v56, 1.0, v56
	v_mul_f32_e32 v51, v51, v56
	v_cvt_pk_bf16_f32 v56, v50, v51
	v_mul_f32_e32 v59, 0x3d372713, v53
	v_mul_f32_e32 v59, v53, v59
	v_fma_f32 v59, v53, v59, v53
	v_mul_f32_e32 v59, 0x3f4c422a, v59
	v_add_f32_e32 v59, v59, v59
	v_mul_f32_e32 v59, 0x3fb8aa3b, v59
	v_exp_f32_e32 v59, v59
	v_rcp_f32_e32 v50, v57
	s_nop 0
	v_add_f32_e32 v50, v50, v50
	v_sub_f32_e32 v50, 1.0, v50
	v_add_f32_e32 v51, 1.0, v59
	v_mul_f32_e32 v52, 0.5, v52
	v_add_f32_e32 v50, 1.0, v50
	v_mul_f32_e32 v50, v52, v50
	v_rcp_f32_e32 v51, v51
	s_nop 0
	v_add_f32_e32 v51, v51, v51
	v_sub_f32_e32 v51, 1.0, v51
	v_mul_f32_e32 v52, 0.5, v53
	v_add_f32_e32 v51, 1.0, v51
	v_mul_f32_e32 v51, v52, v51
	v_mul_f32_e32 v52, 0x3d372713, v46
	v_mul_f32_e32 v52, v46, v52
	v_fma_f32 v52, v46, v52, v46
	v_mul_f32_e32 v52, 0x3f4c422a, v52
	v_add_f32_e32 v52, v52, v52
	v_mul_f32_e32 v52, 0x3fb8aa3b, v52
	v_exp_f32_e32 v52, v52
	v_or_b32_e32 v58, v124, v150
	v_ashrrev_i32_e32 v59, 31, v58
	v_cvt_pk_bf16_f32 v57, v50, v51
	v_add_f32_e32 v52, 1.0, v52
	v_lshlrev_b64 v[50:51], 11, v[58:59]
	v_lshl_add_u64 v[50:51], v[138:139], 0, v[50:51]
	global_store_dwordx4 v[50:51], v[54:57], off
	v_mul_f32_e32 v46, 0.5, v46
	v_mul_f32_e32 v53, 0x3d372713, v47
	v_mul_f32_e32 v53, v47, v53
	v_fma_f32 v53, v47, v53, v47
	v_mul_f32_e32 v53, 0x3f4c422a, v53
	v_add_f32_e32 v53, v53, v53
	v_mul_f32_e32 v53, 0x3fb8aa3b, v53
	v_exp_f32_e32 v53, v53
	v_rcp_f32_e32 v51, v52
	s_nop 0
	v_add_f32_e32 v51, v51, v51
	v_sub_f32_e32 v51, 1.0, v51
	v_add_f32_e32 v52, 1.0, v53
	v_add_f32_e32 v51, 1.0, v51
	v_mul_f32_e32 v46, v46, v51
	v_mul_f32_e32 v47, 0.5, v47
	v_mul_f32_e32 v53, 0x3d372713, v48
	v_mul_f32_e32 v53, v48, v53
	v_fma_f32 v53, v48, v53, v48
	v_mul_f32_e32 v53, 0x3f4c422a, v53
	v_add_f32_e32 v53, v53, v53
	v_mul_f32_e32 v53, 0x3fb8aa3b, v53
	v_exp_f32_e32 v53, v53
	v_rcp_f32_e32 v51, v52
	s_nop 0
	v_add_f32_e32 v51, v51, v51
	v_sub_f32_e32 v51, 1.0, v51
	v_add_f32_e32 v52, 1.0, v53
	v_add_f32_e32 v51, 1.0, v51
	v_mul_f32_e32 v47, v47, v51
	v_cvt_pk_bf16_f32 v46, v46, v47
	v_mul_f32_e32 v53, 0x3d372713, v49
	v_mul_f32_e32 v53, v49, v53
	v_fma_f32 v53, v49, v53, v49
	v_mul_f32_e32 v53, 0x3f4c422a, v53
	v_add_f32_e32 v53, v53, v53
	v_mul_f32_e32 v53, 0x3fb8aa3b, v53
	v_exp_f32_e32 v53, v53
	v_rcp_f32_e32 v47, v52
	s_nop 0
	v_add_f32_e32 v47, v47, v47
	v_sub_f32_e32 v47, 1.0, v47
	v_add_f32_e32 v51, 1.0, v53
	v_mul_f32_e32 v48, 0.5, v48
	v_add_f32_e32 v47, 1.0, v47
	v_mul_f32_e32 v47, v48, v47
	v_mul_f32_e32 v52, 0x3d372713, v42
	v_mul_f32_e32 v52, v42, v52
	v_fma_f32 v52, v42, v52, v42
	v_mul_f32_e32 v52, 0x3f4c422a, v52
	v_add_f32_e32 v52, v52, v52
	v_mul_f32_e32 v52, 0x3fb8aa3b, v52
	v_exp_f32_e32 v52, v52
	v_rcp_f32_e32 v48, v51
	s_nop 0
	v_add_f32_e32 v48, v48, v48
	v_sub_f32_e32 v48, 1.0, v48
	v_add_f32_e32 v51, 1.0, v52
	v_mul_f32_e32 v49, 0.5, v49
	v_add_f32_e32 v48, 1.0, v48
	v_mul_f32_e32 v48, v49, v48
	v_cvt_pk_bf16_f32 v47, v47, v48
	v_mul_f32_e32 v52, 0x3d372713, v43
	v_mul_f32_e32 v52, v43, v52
	v_fma_f32 v52, v43, v52, v43
	v_mul_f32_e32 v52, 0x3f4c422a, v52
	v_add_f32_e32 v52, v52, v52
	v_mul_f32_e32 v52, 0x3fb8aa3b, v52
	v_exp_f32_e32 v52, v52
	v_rcp_f32_e32 v48, v51
	s_nop 0
	v_add_f32_e32 v48, v48, v48
	v_sub_f32_e32 v48, 1.0, v48
	v_add_f32_e32 v49, 1.0, v52
	v_mul_f32_e32 v42, 0.5, v42
	v_add_f32_e32 v48, 1.0, v48
	v_mul_f32_e32 v42, v42, v48
	v_mul_f32_e32 v51, 0x3d372713, v44
	v_mul_f32_e32 v51, v44, v51
	v_fma_f32 v51, v44, v51, v44
	v_mul_f32_e32 v51, 0x3f4c422a, v51
	v_add_f32_e32 v51, v51, v51
	v_mul_f32_e32 v51, 0x3fb8aa3b, v51
	v_exp_f32_e32 v51, v51
	v_rcp_f32_e32 v48, v49
	s_nop 0
	v_add_f32_e32 v48, v48, v48
	v_sub_f32_e32 v48, 1.0, v48
	v_add_f32_e32 v49, 1.0, v51
	v_mul_f32_e32 v43, 0.5, v43
	v_add_f32_e32 v48, 1.0, v48
; #define LAS __attribute__((address_space(3)))
; __device__ __forceinline__ unsigned cvt_pk_bf16(float lo, float hi) { unsigned r; asm volatile("v_cvt_pk_bf16_f32 %0, %1, %2" : "=v"(r) : "v"(lo), "v"(hi)); return r; }
; __device__ __forceinline__ float gelu_tanh(float x) { const float z = 0.7978845608f * (x + 0.044715f * x * x * x); const float th = 1.0f - 2.0f / (__expf(2.0f * z) + 1.0f); return 0.5f * x * (1.0f + th); }
;     __device__ __forceinline__ void operator()(const f32x4 (&acc)[2][2][4][2], const Unit& u, int ui, const LAS float* rtab, int wr, int wc, int fr, int fq) const {
;         const int g = u.pm; const int n0 = wr * 64 + fr; const int lc0 = (u.pn & 1) * 256 + wc * 32 + 8 * fq;
; #pragma unroll
;         for (int ai = 0; ai < 2; ++ai)
; #pragma unroll
;             for (int m = 0; m < 4; ++m) {
;                 const int n = n0 + ai * HALF + m * 16;
; #pragma unroll
;                 for (int bj = 0; bj < 2; ++bj) {
;                     const int lc = lc0 + bj * HALF, t = lc >> 4, co = lc & 15; const int token = n * 32 + t;
;                     const f32x4 a0 = acc[ai][bj][m][0], a1 = acc[ai][bj][m][1];
;                     u32x4 w; w.x = cvt_pk_bf16(gelu_tanh(a0[0]), gelu_tanh(a0[1])); w.y = cvt_pk_bf16(gelu_tanh(a0[2]), gelu_tanh(a0[3]));
;                     w.z = cvt_pk_bf16(gelu_tanh(a1[0]), gelu_tanh(a1[1])); w.w = cvt_pk_bf16(gelu_tanh(a1[2]), gelu_tanh(a1[3]));
;                     *(u32x4*)(Y + (size_t)token * 1024 + 16 * g + co) = w;
	v_mul_f32_e32 v43, v43, v48
	v_cvt_pk_bf16_f32 v48, v42, v43
	v_mul_f32_e32 v51, 0x3d372713, v45
	v_mul_f32_e32 v51, v45, v51
	v_fma_f32 v51, v45, v51, v45
	v_mul_f32_e32 v51, 0x3f4c422a, v51
	v_add_f32_e32 v51, v51, v51
	v_mul_f32_e32 v51, 0x3fb8aa3b, v51
	v_exp_f32_e32 v51, v51
	v_rcp_f32_e32 v42, v49
	s_nop 0
	v_add_f32_e32 v42, v42, v42
	v_sub_f32_e32 v42, 1.0, v42
	v_add_f32_e32 v43, 1.0, v51
	v_mul_f32_e32 v44, 0.5, v44
	v_add_f32_e32 v42, 1.0, v42
	v_mul_f32_e32 v42, v44, v42
	v_rcp_f32_e32 v43, v43
	s_nop 0
	v_add_f32_e32 v43, v43, v43
	v_sub_f32_e32 v43, 1.0, v43
	v_mul_f32_e32 v44, 0.5, v45
	v_add_f32_e32 v43, 1.0, v43
	v_mul_f32_e32 v43, v44, v43
	v_mul_f32_e32 v44, 0x3d372713, v38
	v_mul_f32_e32 v44, v38, v44
	v_fma_f32 v44, v38, v44, v38
	v_mul_f32_e32 v44, 0x3f4c422a, v44
	v_add_f32_e32 v44, v44, v44
	v_mul_f32_e32 v44, 0x3fb8aa3b, v44
	v_exp_f32_e32 v44, v44
	v_or_b32_e32 v50, v171, v151
	v_ashrrev_i32_e32 v51, 31, v50
	v_cvt_pk_bf16_f32 v49, v42, v43
	v_add_f32_e32 v44, 1.0, v44
	v_lshlrev_b64 v[42:43], 11, v[50:51]
	v_lshl_add_u64 v[42:43], v[138:139], 0, v[42:43]
	global_store_dwordx4 v[42:43], v[46:49], off
	v_mul_f32_e32 v38, 0.5, v38
	v_mul_f32_e32 v45, 0x3d372713, v39
	v_mul_f32_e32 v45, v39, v45
	v_fma_f32 v45, v39, v45, v39
	v_mul_f32_e32 v45, 0x3f4c422a, v45
	v_add_f32_e32 v45, v45, v45
	v_mul_f32_e32 v45, 0x3fb8aa3b, v45
	v_exp_f32_e32 v45, v45
	v_rcp_f32_e32 v43, v44
	s_nop 0
	v_add_f32_e32 v43, v43, v43
	v_sub_f32_e32 v43, 1.0, v43
	v_add_f32_e32 v44, 1.0, v45
	v_add_f32_e32 v43, 1.0, v43
	v_mul_f32_e32 v38, v38, v43
	v_mul_f32_e32 v39, 0.5, v39
	v_mul_f32_e32 v45, 0x3d372713, v40
	v_mul_f32_e32 v45, v40, v45
	v_fma_f32 v45, v40, v45, v40
	v_mul_f32_e32 v45, 0x3f4c422a, v45
	v_add_f32_e32 v45, v45, v45
	v_mul_f32_e32 v45, 0x3fb8aa3b, v45
	v_exp_f32_e32 v45, v45
	v_rcp_f32_e32 v43, v44
	s_nop 0
	v_add_f32_e32 v43, v43, v43
	v_sub_f32_e32 v43, 1.0, v43
	v_add_f32_e32 v44, 1.0, v45
	v_add_f32_e32 v43, 1.0, v43
	v_mul_f32_e32 v39, v39, v43
	v_cvt_pk_bf16_f32 v38, v38, v39
	v_mul_f32_e32 v45, 0x3d372713, v41
	v_mul_f32_e32 v45, v41, v45
	v_fma_f32 v45, v41, v45, v41
	v_mul_f32_e32 v45, 0x3f4c422a, v45
	v_add_f32_e32 v45, v45, v45
	v_mul_f32_e32 v45, 0x3fb8aa3b, v45
	v_exp_f32_e32 v45, v45
	v_rcp_f32_e32 v39, v44
	s_nop 0
	v_add_f32_e32 v39, v39, v39
	v_sub_f32_e32 v39, 1.0, v39
	v_add_f32_e32 v43, 1.0, v45
	v_mul_f32_e32 v40, 0.5, v40
	v_add_f32_e32 v39, 1.0, v39
	v_mul_f32_e32 v39, v40, v39
	v_mul_f32_e32 v44, 0x3d372713, v34
	v_mul_f32_e32 v44, v34, v44
	v_fma_f32 v44, v34, v44, v34
	v_mul_f32_e32 v44, 0x3f4c422a, v44
	v_add_f32_e32 v44, v44, v44
	v_mul_f32_e32 v44, 0x3fb8aa3b, v44
	v_exp_f32_e32 v44, v44
	v_rcp_f32_e32 v40, v43
	s_nop 0
	v_add_f32_e32 v40, v40, v40
	v_sub_f32_e32 v40, 1.0, v40
	v_add_f32_e32 v43, 1.0, v44
	v_mul_f32_e32 v41, 0.5, v41
	v_add_f32_e32 v40, 1.0, v40
	v_mul_f32_e32 v40, v41, v40
	v_cvt_pk_bf16_f32 v39, v39, v40
	v_mul_f32_e32 v44, 0x3d372713, v35
	v_mul_f32_e32 v44, v35, v44
	v_fma_f32 v44, v35, v44, v35
	v_mul_f32_e32 v44, 0x3f4c422a, v44
	v_add_f32_e32 v44, v44, v44
	v_mul_f32_e32 v44, 0x3fb8aa3b, v44
	v_exp_f32_e32 v44, v44
	v_rcp_f32_e32 v40, v43
	s_nop 0
	v_add_f32_e32 v40, v40, v40
	v_sub_f32_e32 v40, 1.0, v40
	v_add_f32_e32 v41, 1.0, v44
	v_mul_f32_e32 v34, 0.5, v34
	v_add_f32_e32 v40, 1.0, v40
	v_mul_f32_e32 v34, v34, v40
	v_mul_f32_e32 v43, 0x3d372713, v36
	v_mul_f32_e32 v43, v36, v43
	v_fma_f32 v43, v36, v43, v36
	v_mul_f32_e32 v43, 0x3f4c422a, v43
	v_add_f32_e32 v43, v43, v43
	v_mul_f32_e32 v43, 0x3fb8aa3b, v43
	v_exp_f32_e32 v43, v43
	v_rcp_f32_e32 v40, v41
	s_nop 0
	v_add_f32_e32 v40, v40, v40
	v_sub_f32_e32 v40, 1.0, v40
	v_add_f32_e32 v41, 1.0, v43
	v_mul_f32_e32 v35, 0.5, v35
	v_add_f32_e32 v40, 1.0, v40
	v_mul_f32_e32 v35, v35, v40
	v_cvt_pk_bf16_f32 v40, v34, v35
	v_mul_f32_e32 v43, 0x3d372713, v37
	v_mul_f32_e32 v43, v37, v43
	v_fma_f32 v43, v37, v43, v37
	v_mul_f32_e32 v43, 0x3f4c422a, v43
	v_add_f32_e32 v43, v43, v43
	v_mul_f32_e32 v43, 0x3fb8aa3b, v43
	v_exp_f32_e32 v43, v43
	v_rcp_f32_e32 v34, v41
	s_nop 0
	v_add_f32_e32 v34, v34, v34
	v_sub_f32_e32 v34, 1.0, v34
	v_add_f32_e32 v35, 1.0, v43
	v_mul_f32_e32 v36, 0.5, v36
	v_add_f32_e32 v34, 1.0, v34
	v_mul_f32_e32 v34, v36, v34
	v_rcp_f32_e32 v35, v35
	s_nop 0
	v_add_f32_e32 v35, v35, v35
	v_sub_f32_e32 v35, 1.0, v35
	v_mul_f32_e32 v36, 0.5, v37
	v_add_f32_e32 v35, 1.0, v35
	v_mul_f32_e32 v35, v36, v35
	v_mul_f32_e32 v36, 0x3d372713, v30
	v_mul_f32_e32 v36, v30, v36
	v_fma_f32 v36, v30, v36, v30
	v_mul_f32_e32 v36, 0x3f4c422a, v36
	v_add_f32_e32 v36, v36, v36
	v_mul_f32_e32 v36, 0x3fb8aa3b, v36
	v_exp_f32_e32 v36, v36
	v_or_b32_e32 v42, v124, v151
	v_ashrrev_i32_e32 v43, 31, v42
	v_cvt_pk_bf16_f32 v41, v34, v35
	v_add_f32_e32 v36, 1.0, v36
	v_lshlrev_b64 v[34:35], 11, v[42:43]
	v_lshl_add_u64 v[34:35], v[138:139], 0, v[34:35]
	global_store_dwordx4 v[34:35], v[38:41], off
	v_mul_f32_e32 v30, 0.5, v30
	v_mul_f32_e32 v37, 0x3d372713, v31
	v_mul_f32_e32 v37, v31, v37
	v_fma_f32 v37, v31, v37, v31
	v_mul_f32_e32 v37, 0x3f4c422a, v37
	v_add_f32_e32 v37, v37, v37
	v_mul_f32_e32 v37, 0x3fb8aa3b, v37
	v_exp_f32_e32 v37, v37
	v_rcp_f32_e32 v35, v36
	s_nop 0
	v_add_f32_e32 v35, v35, v35
	v_sub_f32_e32 v35, 1.0, v35
	v_add_f32_e32 v36, 1.0, v37
	v_add_f32_e32 v35, 1.0, v35
	v_mul_f32_e32 v30, v30, v35
	v_mul_f32_e32 v31, 0.5, v31
	v_mul_f32_e32 v37, 0x3d372713, v32
	v_mul_f32_e32 v37, v32, v37
	v_fma_f32 v37, v32, v37, v32
	v_mul_f32_e32 v37, 0x3f4c422a, v37
	v_add_f32_e32 v37, v37, v37
	v_mul_f32_e32 v37, 0x3fb8aa3b, v37
	v_exp_f32_e32 v37, v37
	v_rcp_f32_e32 v35, v36
	s_nop 0
	v_add_f32_e32 v35, v35, v35
; #define LAS __attribute__((address_space(3)))
; __device__ __forceinline__ unsigned cvt_pk_bf16(float lo, float hi) { unsigned r; asm volatile("v_cvt_pk_bf16_f32 %0, %1, %2" : "=v"(r) : "v"(lo), "v"(hi)); return r; }
; __device__ __forceinline__ float gelu_tanh(float x) { const float z = 0.7978845608f * (x + 0.044715f * x * x * x); const float th = 1.0f - 2.0f / (__expf(2.0f * z) + 1.0f); return 0.5f * x * (1.0f + th); }
;     __device__ __forceinline__ void operator()(const f32x4 (&acc)[2][2][4][2], const Unit& u, int ui, const LAS float* rtab, int wr, int wc, int fr, int fq) const {
;         const int g = u.pm; const int n0 = wr * 64 + fr; const int lc0 = (u.pn & 1) * 256 + wc * 32 + 8 * fq;
; #pragma unroll
;         for (int ai = 0; ai < 2; ++ai)
; #pragma unroll
;             for (int m = 0; m < 4; ++m) {
;                 const int n = n0 + ai * HALF + m * 16;
; #pragma unroll
;                 for (int bj = 0; bj < 2; ++bj) {
;                     const int lc = lc0 + bj * HALF, t = lc >> 4, co = lc & 15; const int token = n * 32 + t;
;                     const f32x4 a0 = acc[ai][bj][m][0], a1 = acc[ai][bj][m][1];
;                     u32x4 w; w.x = cvt_pk_bf16(gelu_tanh(a0[0]), gelu_tanh(a0[1])); w.y = cvt_pk_bf16(gelu_tanh(a0[2]), gelu_tanh(a0[3]));
;                     w.z = cvt_pk_bf16(gelu_tanh(a1[0]), gelu_tanh(a1[1])); w.w = cvt_pk_bf16(gelu_tanh(a1[2]), gelu_tanh(a1[3]));
;                     *(u32x4*)(Y + (size_t)token * 1024 + 16 * g + co) = w;
	v_sub_f32_e32 v35, 1.0, v35
	v_add_f32_e32 v36, 1.0, v37
	v_add_f32_e32 v35, 1.0, v35
	v_mul_f32_e32 v31, v31, v35
	v_cvt_pk_bf16_f32 v30, v30, v31
	v_mul_f32_e32 v37, 0x3d372713, v33
	v_mul_f32_e32 v37, v33, v37
	v_fma_f32 v37, v33, v37, v33
	v_mul_f32_e32 v37, 0x3f4c422a, v37
	v_add_f32_e32 v37, v37, v37
	v_mul_f32_e32 v37, 0x3fb8aa3b, v37
	v_exp_f32_e32 v37, v37
	v_rcp_f32_e32 v31, v36
	s_nop 0
	v_add_f32_e32 v31, v31, v31
	v_sub_f32_e32 v31, 1.0, v31
	v_add_f32_e32 v35, 1.0, v37
	v_mul_f32_e32 v32, 0.5, v32
	v_add_f32_e32 v31, 1.0, v31
	v_mul_f32_e32 v31, v32, v31
	v_mul_f32_e32 v36, 0x3d372713, v26
	v_mul_f32_e32 v36, v26, v36
	v_fma_f32 v36, v26, v36, v26
	v_mul_f32_e32 v36, 0x3f4c422a, v36
	v_add_f32_e32 v36, v36, v36
	v_mul_f32_e32 v36, 0x3fb8aa3b, v36
	v_exp_f32_e32 v36, v36
	v_rcp_f32_e32 v32, v35
	s_nop 0
	v_add_f32_e32 v32, v32, v32
	v_sub_f32_e32 v32, 1.0, v32
	v_add_f32_e32 v35, 1.0, v36
	v_mul_f32_e32 v33, 0.5, v33
	v_add_f32_e32 v32, 1.0, v32
	v_mul_f32_e32 v32, v33, v32
	v_cvt_pk_bf16_f32 v31, v31, v32
	v_mul_f32_e32 v36, 0x3d372713, v27
	v_mul_f32_e32 v36, v27, v36
	v_fma_f32 v36, v27, v36, v27
	v_mul_f32_e32 v36, 0x3f4c422a, v36
	v_add_f32_e32 v36, v36, v36
	v_mul_f32_e32 v36, 0x3fb8aa3b, v36
	v_exp_f32_e32 v36, v36
	v_rcp_f32_e32 v32, v35
	s_nop 0
	v_add_f32_e32 v32, v32, v32
	v_sub_f32_e32 v32, 1.0, v32
	v_add_f32_e32 v33, 1.0, v36
	v_mul_f32_e32 v26, 0.5, v26
	v_add_f32_e32 v32, 1.0, v32
	v_mul_f32_e32 v26, v26, v32
	v_mul_f32_e32 v35, 0x3d372713, v28
	v_mul_f32_e32 v35, v28, v35
	v_fma_f32 v35, v28, v35, v28
	v_mul_f32_e32 v35, 0x3f4c422a, v35
	v_add_f32_e32 v35, v35, v35
	v_mul_f32_e32 v35, 0x3fb8aa3b, v35
	v_exp_f32_e32 v35, v35
	v_rcp_f32_e32 v32, v33
	s_nop 0
	v_add_f32_e32 v32, v32, v32
	v_sub_f32_e32 v32, 1.0, v32
	v_add_f32_e32 v33, 1.0, v35
	v_mul_f32_e32 v27, 0.5, v27
	v_add_f32_e32 v32, 1.0, v32
	v_mul_f32_e32 v27, v27, v32
	v_cvt_pk_bf16_f32 v32, v26, v27
	v_mul_f32_e32 v35, 0x3d372713, v29
	v_mul_f32_e32 v35, v29, v35
	v_fma_f32 v35, v29, v35, v29
	v_mul_f32_e32 v35, 0x3f4c422a, v35
	v_add_f32_e32 v35, v35, v35
	v_mul_f32_e32 v35, 0x3fb8aa3b, v35
	v_exp_f32_e32 v35, v35
	v_rcp_f32_e32 v26, v33
	s_nop 0
	v_add_f32_e32 v26, v26, v26
	v_sub_f32_e32 v26, 1.0, v26
	v_add_f32_e32 v27, 1.0, v35
	v_mul_f32_e32 v28, 0.5, v28
	v_add_f32_e32 v26, 1.0, v26
	v_mul_f32_e32 v26, v28, v26
	v_rcp_f32_e32 v27, v27
	s_nop 0
	v_add_f32_e32 v27, v27, v27
	v_sub_f32_e32 v27, 1.0, v27
	v_mul_f32_e32 v28, 0.5, v29
	v_add_f32_e32 v27, 1.0, v27
	v_mul_f32_e32 v27, v28, v27
	v_mul_f32_e32 v28, 0x3d372713, v22
	v_mul_f32_e32 v28, v22, v28
	v_fma_f32 v28, v22, v28, v22
	v_mul_f32_e32 v28, 0x3f4c422a, v28
	v_add_f32_e32 v28, v28, v28
	v_mul_f32_e32 v28, 0x3fb8aa3b, v28
	v_exp_f32_e32 v28, v28
	v_or_b32_e32 v34, v171, v152
	v_ashrrev_i32_e32 v35, 31, v34
	v_cvt_pk_bf16_f32 v33, v26, v27
	v_add_f32_e32 v28, 1.0, v28
	v_lshlrev_b64 v[26:27], 11, v[34:35]
	v_lshl_add_u64 v[26:27], v[138:139], 0, v[26:27]
	global_store_dwordx4 v[26:27], v[30:33], off
	v_mul_f32_e32 v22, 0.5, v22
	v_mul_f32_e32 v29, 0x3d372713, v23
	v_mul_f32_e32 v29, v23, v29
	v_fma_f32 v29, v23, v29, v23
	v_mul_f32_e32 v29, 0x3f4c422a, v29
	v_add_f32_e32 v29, v29, v29
	v_mul_f32_e32 v29, 0x3fb8aa3b, v29
	v_exp_f32_e32 v29, v29
	v_rcp_f32_e32 v27, v28
	s_nop 0
	v_add_f32_e32 v27, v27, v27
	v_sub_f32_e32 v27, 1.0, v27
	v_add_f32_e32 v28, 1.0, v29
	v_add_f32_e32 v27, 1.0, v27
	v_mul_f32_e32 v22, v22, v27
	v_mul_f32_e32 v23, 0.5, v23
	v_mul_f32_e32 v29, 0x3d372713, v24
	v_mul_f32_e32 v29, v24, v29
	v_fma_f32 v29, v24, v29, v24
	v_mul_f32_e32 v29, 0x3f4c422a, v29
	v_add_f32_e32 v29, v29, v29
	v_mul_f32_e32 v29, 0x3fb8aa3b, v29
	v_exp_f32_e32 v29, v29
	v_rcp_f32_e32 v27, v28
	s_nop 0
	v_add_f32_e32 v27, v27, v27
	v_sub_f32_e32 v27, 1.0, v27
	v_add_f32_e32 v28, 1.0, v29
	v_add_f32_e32 v27, 1.0, v27
	v_mul_f32_e32 v23, v23, v27
	v_cvt_pk_bf16_f32 v22, v22, v23
	v_mul_f32_e32 v29, 0x3d372713, v25
	v_mul_f32_e32 v29, v25, v29
	v_fma_f32 v29, v25, v29, v25
	v_mul_f32_e32 v29, 0x3f4c422a, v29
	v_add_f32_e32 v29, v29, v29
	v_mul_f32_e32 v29, 0x3fb8aa3b, v29
	v_exp_f32_e32 v29, v29
	v_rcp_f32_e32 v23, v28
	s_nop 0
	v_add_f32_e32 v23, v23, v23
	v_sub_f32_e32 v23, 1.0, v23
	v_add_f32_e32 v27, 1.0, v29
	v_mul_f32_e32 v24, 0.5, v24
	v_add_f32_e32 v23, 1.0, v23
	v_mul_f32_e32 v23, v24, v23
	v_mul_f32_e32 v28, 0x3d372713, v18
	v_mul_f32_e32 v28, v18, v28
	v_fma_f32 v28, v18, v28, v18
	v_mul_f32_e32 v28, 0x3f4c422a, v28
	v_add_f32_e32 v28, v28, v28
	v_mul_f32_e32 v28, 0x3fb8aa3b, v28
	v_exp_f32_e32 v28, v28
	v_rcp_f32_e32 v24, v27
	s_nop 0
	v_add_f32_e32 v24, v24, v24
	v_sub_f32_e32 v24, 1.0, v24
	v_add_f32_e32 v27, 1.0, v28
	v_mul_f32_e32 v25, 0.5, v25
	v_add_f32_e32 v24, 1.0, v24
	v_mul_f32_e32 v24, v25, v24
	v_cvt_pk_bf16_f32 v23, v23, v24
	v_mul_f32_e32 v28, 0x3d372713, v19
	v_mul_f32_e32 v28, v19, v28
	v_fma_f32 v28, v19, v28, v19
	v_mul_f32_e32 v28, 0x3f4c422a, v28
	v_add_f32_e32 v28, v28, v28
	v_mul_f32_e32 v28, 0x3fb8aa3b, v28
	v_exp_f32_e32 v28, v28
	v_rcp_f32_e32 v24, v27
	s_nop 0
	v_add_f32_e32 v24, v24, v24
	v_sub_f32_e32 v24, 1.0, v24
	v_add_f32_e32 v25, 1.0, v28
	v_mul_f32_e32 v18, 0.5, v18
	v_add_f32_e32 v24, 1.0, v24
	v_mul_f32_e32 v18, v18, v24
	v_mul_f32_e32 v27, 0x3d372713, v20
	v_mul_f32_e32 v27, v20, v27
	v_fma_f32 v27, v20, v27, v20
	v_mul_f32_e32 v27, 0x3f4c422a, v27
	v_add_f32_e32 v27, v27, v27
	v_mul_f32_e32 v27, 0x3fb8aa3b, v27
	v_exp_f32_e32 v27, v27
	v_rcp_f32_e32 v24, v25
	s_nop 0
	v_add_f32_e32 v24, v24, v24
	v_sub_f32_e32 v24, 1.0, v24
	v_add_f32_e32 v25, 1.0, v27
	v_mul_f32_e32 v19, 0.5, v19
	v_add_f32_e32 v24, 1.0, v24
	v_mul_f32_e32 v19, v19, v24
; __device__ __forceinline__ unsigned cvt_pk_bf16(float lo, float hi) { unsigned r; asm volatile("v_cvt_pk_bf16_f32 %0, %1, %2" : "=v"(r) : "v"(lo), "v"(hi)); return r; }
; __device__ __forceinline__ float gelu_tanh(float x) { const float z = 0.7978845608f * (x + 0.044715f * x * x * x); const float th = 1.0f - 2.0f / (__expf(2.0f * z) + 1.0f); return 0.5f * x * (1.0f + th); }
;     __device__ __forceinline__ void operator()(const f32x4 (&acc)[2][2][4][2], const Unit& u, int ui, const LAS float* rtab, int wr, int wc, int fr, int fq) const {
;     ...
;                 for (int bj = 0; bj < 2; ++bj) {
;                     const int lc = lc0 + bj * HALF, t = lc >> 4, co = lc & 15; const int token = n * 32 + t;
;                     const f32x4 a0 = acc[ai][bj][m][0], a1 = acc[ai][bj][m][1];
;                     u32x4 w; w.x = cvt_pk_bf16(gelu_tanh(a0[0]), gelu_tanh(a0[1])); w.y = cvt_pk_bf16(gelu_tanh(a0[2]), gelu_tanh(a0[3]));
;                     w.z = cvt_pk_bf16(gelu_tanh(a1[0]), gelu_tanh(a1[1])); w.w = cvt_pk_bf16(gelu_tanh(a1[2]), gelu_tanh(a1[3]));
;                     *(u32x4*)(Y + (size_t)token * 1024 + 16 * g + co) = w;
	v_cvt_pk_bf16_f32 v24, v18, v19
	v_mul_f32_e32 v27, 0x3d372713, v21
	v_mul_f32_e32 v27, v21, v27
	v_fma_f32 v27, v21, v27, v21
	v_mul_f32_e32 v27, 0x3f4c422a, v27
	v_add_f32_e32 v27, v27, v27
	v_mul_f32_e32 v27, 0x3fb8aa3b, v27
	v_exp_f32_e32 v27, v27
	v_rcp_f32_e32 v18, v25
	s_nop 0
	v_add_f32_e32 v18, v18, v18
	v_sub_f32_e32 v18, 1.0, v18
	v_add_f32_e32 v19, 1.0, v27
	v_mul_f32_e32 v20, 0.5, v20
	v_add_f32_e32 v18, 1.0, v18
	v_mul_f32_e32 v18, v20, v18
	v_rcp_f32_e32 v19, v19
	s_nop 0
	v_add_f32_e32 v19, v19, v19
	v_sub_f32_e32 v19, 1.0, v19
	v_mul_f32_e32 v20, 0.5, v21
	v_add_f32_e32 v19, 1.0, v19
	v_mul_f32_e32 v19, v20, v19
	v_mul_f32_e32 v20, 0x3d372713, v14
	v_mul_f32_e32 v20, v14, v20
	v_fma_f32 v20, v14, v20, v14
	v_mul_f32_e32 v20, 0x3f4c422a, v20
	v_add_f32_e32 v20, v20, v20
	v_mul_f32_e32 v20, 0x3fb8aa3b, v20
	v_exp_f32_e32 v20, v20
	v_or_b32_e32 v26, v124, v152
	v_ashrrev_i32_e32 v27, 31, v26
	v_cvt_pk_bf16_f32 v25, v18, v19
	v_add_f32_e32 v20, 1.0, v20
	v_lshlrev_b64 v[18:19], 11, v[26:27]
	v_lshl_add_u64 v[18:19], v[138:139], 0, v[18:19]
	global_store_dwordx4 v[18:19], v[22:25], off
	v_mul_f32_e32 v14, 0.5, v14
	v_mul_f32_e32 v21, 0x3d372713, v15
	v_mul_f32_e32 v21, v15, v21
	v_fma_f32 v21, v15, v21, v15
	v_mul_f32_e32 v21, 0x3f4c422a, v21
	v_add_f32_e32 v21, v21, v21
	v_mul_f32_e32 v21, 0x3fb8aa3b, v21
	v_exp_f32_e32 v21, v21
	v_rcp_f32_e32 v19, v20
	s_nop 0
	v_add_f32_e32 v19, v19, v19
	v_sub_f32_e32 v19, 1.0, v19
	v_add_f32_e32 v20, 1.0, v21
	v_add_f32_e32 v19, 1.0, v19
	v_mul_f32_e32 v14, v14, v19
	v_mul_f32_e32 v15, 0.5, v15
	v_mul_f32_e32 v21, 0x3d372713, v16
	v_mul_f32_e32 v21, v16, v21
	v_fma_f32 v21, v16, v21, v16
	v_mul_f32_e32 v21, 0x3f4c422a, v21
	v_add_f32_e32 v21, v21, v21
	v_mul_f32_e32 v21, 0x3fb8aa3b, v21
	v_exp_f32_e32 v21, v21
	v_rcp_f32_e32 v19, v20
	s_nop 0
	v_add_f32_e32 v19, v19, v19
	v_sub_f32_e32 v19, 1.0, v19
	v_add_f32_e32 v20, 1.0, v21
	v_add_f32_e32 v19, 1.0, v19
	v_mul_f32_e32 v15, v15, v19
	v_cvt_pk_bf16_f32 v14, v14, v15
	v_mul_f32_e32 v21, 0x3d372713, v17
	v_mul_f32_e32 v21, v17, v21
	v_fma_f32 v21, v17, v21, v17
	v_mul_f32_e32 v21, 0x3f4c422a, v21
	v_add_f32_e32 v21, v21, v21
	v_mul_f32_e32 v21, 0x3fb8aa3b, v21
	v_exp_f32_e32 v21, v21
	v_rcp_f32_e32 v15, v20
	s_nop 0
	v_add_f32_e32 v15, v15, v15
	v_sub_f32_e32 v15, 1.0, v15
	v_add_f32_e32 v19, 1.0, v21
	v_mul_f32_e32 v16, 0.5, v16
	v_add_f32_e32 v15, 1.0, v15
	v_mul_f32_e32 v15, v16, v15
	v_mul_f32_e32 v20, 0x3d372713, v10
	v_mul_f32_e32 v20, v10, v20
	v_fma_f32 v20, v10, v20, v10
	v_mul_f32_e32 v20, 0x3f4c422a, v20
	v_add_f32_e32 v20, v20, v20
	v_mul_f32_e32 v20, 0x3fb8aa3b, v20
	v_exp_f32_e32 v20, v20
	v_rcp_f32_e32 v16, v19
	s_nop 0
	v_add_f32_e32 v16, v16, v16
	v_sub_f32_e32 v16, 1.0, v16
	v_add_f32_e32 v19, 1.0, v20
	v_mul_f32_e32 v17, 0.5, v17
	v_add_f32_e32 v16, 1.0, v16
	v_mul_f32_e32 v16, v17, v16
	v_cvt_pk_bf16_f32 v15, v15, v16
	v_mul_f32_e32 v20, 0x3d372713, v11
	v_mul_f32_e32 v20, v11, v20
	v_fma_f32 v20, v11, v20, v11
	v_mul_f32_e32 v20, 0x3f4c422a, v20
	v_add_f32_e32 v20, v20, v20
	v_mul_f32_e32 v20, 0x3fb8aa3b, v20
	v_exp_f32_e32 v20, v20
	v_rcp_f32_e32 v16, v19
	s_nop 0
	v_add_f32_e32 v16, v16, v16
	v_sub_f32_e32 v16, 1.0, v16
	v_add_f32_e32 v17, 1.0, v20
	v_mul_f32_e32 v10, 0.5, v10
	v_add_f32_e32 v16, 1.0, v16
	v_mul_f32_e32 v10, v10, v16
	v_mul_f32_e32 v19, 0x3d372713, v12
	v_mul_f32_e32 v19, v12, v19
	v_fma_f32 v19, v12, v19, v12
	v_mul_f32_e32 v19, 0x3f4c422a, v19
	v_add_f32_e32 v19, v19, v19
	v_mul_f32_e32 v19, 0x3fb8aa3b, v19
	v_exp_f32_e32 v19, v19
	v_rcp_f32_e32 v16, v17
	s_nop 0
	v_add_f32_e32 v16, v16, v16
	v_sub_f32_e32 v16, 1.0, v16
	v_add_f32_e32 v17, 1.0, v19
	v_mul_f32_e32 v11, 0.5, v11
	v_add_f32_e32 v16, 1.0, v16
	v_mul_f32_e32 v11, v11, v16
	v_cvt_pk_bf16_f32 v16, v10, v11
	v_mul_f32_e32 v19, 0x3d372713, v13
	v_mul_f32_e32 v19, v13, v19
	v_fma_f32 v19, v13, v19, v13
	v_mul_f32_e32 v19, 0x3f4c422a, v19
	v_add_f32_e32 v19, v19, v19
	v_mul_f32_e32 v19, 0x3fb8aa3b, v19
	v_exp_f32_e32 v19, v19
	v_rcp_f32_e32 v10, v17
	s_nop 0
	v_add_f32_e32 v10, v10, v10
	v_sub_f32_e32 v10, 1.0, v10
	v_add_f32_e32 v11, 1.0, v19
	v_mul_f32_e32 v12, 0.5, v12
	v_add_f32_e32 v10, 1.0, v10
	v_mul_f32_e32 v10, v12, v10
	v_rcp_f32_e32 v11, v11
	s_nop 0
; __device__ __forceinline__ unsigned cvt_pk_bf16(float lo, float hi) { unsigned r; asm volatile("v_cvt_pk_bf16_f32 %0, %1, %2" : "=v"(r) : "v"(lo), "v"(hi)); return r; }
; __device__ __forceinline__ float gelu_tanh(float x) { const float z = 0.7978845608f * (x + 0.044715f * x * x * x); const float th = 1.0f - 2.0f / (__expf(2.0f * z) + 1.0f); return 0.5f * x * (1.0f + th); }
;     __device__ __forceinline__ void operator()(const f32x4 (&acc)[2][2][4][2], const Unit& u, int ui, const LAS float* rtab, int wr, int wc, int fr, int fq) const {
;     ...
;                 for (int bj = 0; bj < 2; ++bj) {
;                     const int lc = lc0 + bj * HALF, t = lc >> 4, co = lc & 15; const int token = n * 32 + t;
;                     const f32x4 a0 = acc[ai][bj][m][0], a1 = acc[ai][bj][m][1];
;                     u32x4 w; w.x = cvt_pk_bf16(gelu_tanh(a0[0]), gelu_tanh(a0[1])); w.y = cvt_pk_bf16(gelu_tanh(a0[2]), gelu_tanh(a0[3]));
;                     w.z = cvt_pk_bf16(gelu_tanh(a1[0]), gelu_tanh(a1[1])); w.w = cvt_pk_bf16(gelu_tanh(a1[2]), gelu_tanh(a1[3]));
;                     *(u32x4*)(Y + (size_t)token * 1024 + 16 * g + co) = w;
	v_add_f32_e32 v11, v11, v11
	v_sub_f32_e32 v11, 1.0, v11
	v_mul_f32_e32 v12, 0.5, v13
	v_add_f32_e32 v11, 1.0, v11
	v_mul_f32_e32 v11, v12, v11
	v_mul_f32_e32 v12, 0x3d372713, v6
	v_mul_f32_e32 v12, v6, v12
	v_fma_f32 v12, v6, v12, v6
	v_mul_f32_e32 v12, 0x3f4c422a, v12
	v_add_f32_e32 v12, v12, v12
	v_mul_f32_e32 v12, 0x3fb8aa3b, v12
	v_exp_f32_e32 v12, v12
	v_or_b32_e32 v18, v171, v153
	v_ashrrev_i32_e32 v19, 31, v18
	v_cvt_pk_bf16_f32 v17, v10, v11
	v_add_f32_e32 v12, 1.0, v12
	v_lshlrev_b64 v[10:11], 11, v[18:19]
	v_lshl_add_u64 v[10:11], v[138:139], 0, v[10:11]
	global_store_dwordx4 v[10:11], v[14:17], off
	v_mul_f32_e32 v6, 0.5, v6
	v_mul_f32_e32 v13, 0x3d372713, v7
	v_mul_f32_e32 v13, v7, v13
	v_fma_f32 v13, v7, v13, v7
	v_mul_f32_e32 v13, 0x3f4c422a, v13
	v_add_f32_e32 v13, v13, v13
	v_mul_f32_e32 v13, 0x3fb8aa3b, v13
	v_exp_f32_e32 v13, v13
	v_rcp_f32_e32 v11, v12
	s_nop 0
	v_add_f32_e32 v11, v11, v11
	v_sub_f32_e32 v11, 1.0, v11
	v_add_f32_e32 v12, 1.0, v13
	v_add_f32_e32 v11, 1.0, v11
	v_mul_f32_e32 v6, v6, v11
	v_mul_f32_e32 v7, 0.5, v7
	v_mul_f32_e32 v13, 0x3d372713, v8
	v_mul_f32_e32 v13, v8, v13
	v_fma_f32 v13, v8, v13, v8
	v_mul_f32_e32 v13, 0x3f4c422a, v13
	v_add_f32_e32 v13, v13, v13
	v_mul_f32_e32 v13, 0x3fb8aa3b, v13
	v_exp_f32_e32 v13, v13
	v_rcp_f32_e32 v11, v12
	s_nop 0
	v_add_f32_e32 v11, v11, v11
	v_sub_f32_e32 v11, 1.0, v11
	v_add_f32_e32 v12, 1.0, v13
	v_add_f32_e32 v11, 1.0, v11
	v_mul_f32_e32 v7, v7, v11
	v_cvt_pk_bf16_f32 v6, v6, v7
	v_mul_f32_e32 v13, 0x3d372713, v9
	v_mul_f32_e32 v13, v9, v13
	v_fma_f32 v13, v9, v13, v9
	v_mul_f32_e32 v13, 0x3f4c422a, v13
	v_add_f32_e32 v13, v13, v13
	v_mul_f32_e32 v13, 0x3fb8aa3b, v13
	v_exp_f32_e32 v13, v13
	v_rcp_f32_e32 v7, v12
	s_nop 0
	v_add_f32_e32 v7, v7, v7
	v_sub_f32_e32 v7, 1.0, v7
	v_add_f32_e32 v11, 1.0, v13
	v_mul_f32_e32 v8, 0.5, v8
	v_add_f32_e32 v7, 1.0, v7
	v_mul_f32_e32 v7, v8, v7
	v_mul_f32_e32 v12, 0x3d372713, v2
	v_mul_f32_e32 v12, v2, v12
	v_fma_f32 v12, v2, v12, v2
	v_mul_f32_e32 v12, 0x3f4c422a, v12
	v_add_f32_e32 v12, v12, v12
	v_mul_f32_e32 v12, 0x3fb8aa3b, v12
	v_exp_f32_e32 v12, v12
	v_rcp_f32_e32 v8, v11
	s_nop 0
	v_add_f32_e32 v8, v8, v8
	v_sub_f32_e32 v8, 1.0, v8
	v_add_f32_e32 v11, 1.0, v12
	v_mul_f32_e32 v9, 0.5, v9
	v_add_f32_e32 v8, 1.0, v8
	v_mul_f32_e32 v8, v9, v8
	v_cvt_pk_bf16_f32 v7, v7, v8
	v_mul_f32_e32 v12, 0x3d372713, v3
	v_mul_f32_e32 v12, v3, v12
	v_fma_f32 v12, v3, v12, v3
	v_mul_f32_e32 v12, 0x3f4c422a, v12
	v_add_f32_e32 v12, v12, v12
	v_mul_f32_e32 v12, 0x3fb8aa3b, v12
	v_exp_f32_e32 v12, v12
	v_rcp_f32_e32 v8, v11
	s_nop 0
	v_add_f32_e32 v8, v8, v8
	v_sub_f32_e32 v8, 1.0, v8
	v_add_f32_e32 v9, 1.0, v12
	v_mul_f32_e32 v2, 0.5, v2
	v_add_f32_e32 v8, 1.0, v8
	v_mul_f32_e32 v2, v2, v8
	v_mul_f32_e32 v11, 0x3d372713, v4
	v_mul_f32_e32 v11, v4, v11
	v_fma_f32 v11, v4, v11, v4
	v_mul_f32_e32 v11, 0x3f4c422a, v11
	v_add_f32_e32 v11, v11, v11
	v_mul_f32_e32 v11, 0x3fb8aa3b, v11
	v_exp_f32_e32 v11, v11
	v_rcp_f32_e32 v8, v9
	s_nop 0
	v_add_f32_e32 v8, v8, v8
	v_sub_f32_e32 v8, 1.0, v8
	v_add_f32_e32 v9, 1.0, v11
	v_mul_f32_e32 v3, 0.5, v3
	v_add_f32_e32 v8, 1.0, v8
	v_mul_f32_e32 v3, v3, v8
	v_cvt_pk_bf16_f32 v8, v2, v3
	v_mul_f32_e32 v11, 0x3d372713, v5
	v_mul_f32_e32 v11, v5, v11
	v_fma_f32 v11, v5, v11, v5
	v_mul_f32_e32 v11, 0x3f4c422a, v11
	v_add_f32_e32 v11, v11, v11
	v_mul_f32_e32 v11, 0x3fb8aa3b, v11
	v_exp_f32_e32 v11, v11
	v_rcp_f32_e32 v2, v9
	s_nop 0
	v_add_f32_e32 v2, v2, v2
	v_sub_f32_e32 v2, 1.0, v2
	v_add_f32_e32 v3, 1.0, v11
	v_div_scale_f32 v9, s[28:29], v3, v3, 2.0
	v_mul_f32_e32 v4, 0.5, v4
	v_add_f32_e32 v2, 1.0, v2
	v_mul_f32_e32 v2, v4, v2
	v_div_scale_f32 v4, vcc, 2.0, v3, 2.0
	v_rcp_f32_e32 v3, v3
	s_nop 0
	v_add_f32_e32 v3, v3, v3
	v_sub_f32_e32 v3, 1.0, v3
	v_or_b32_e32 v10, v124, v153
	v_mul_f32_e32 v4, 0.5, v5
	v_add_f32_e32 v3, 1.0, v3
	v_mul_f32_e32 v3, v4, v3
	v_ashrrev_i32_e32 v11, 31, v10
	v_cvt_pk_bf16_f32 v9, v2, v3
	v_lshlrev_b64 v[2:3], 11, v[10:11]
	v_lshl_add_u64 v[2:3], v[138:139], 0, v[2:3]
	s_mov_b64 s[42:43], 0
	s_and_b64 vcc, exec, s[40:41]
	v_readlane_b32 s26, v254, 32
	global_store_dwordx4 v[2:3], v[6:9], off
	s_cbranch_vccz .LBB0_594
	s_waitcnt vmcnt(0)
	s_cmpk_gt_u32 s12, 0xff
	s_cbranch_scc1 .LBB0_599
	s_barrier

; #define PG8_STAGE(bufoff, gbase, voff) do { _Pragma("unroll") for (int _i = 0; _i < 2; ++_i) \
;         __builtin_amdgcn_global_load_lds((const unsigned*)((const char*)(gbase) + (voff)[_i]), (LAS unsigned*)(lds + (bufoff) + ldsw + _i * 8192), 16, 0, 0); } while (0)
; #define PG8_LDA(dst, b, h) do { _Pragma("unroll") for (int m = 0; m < 4; ++m) _Pragma("unroll") for (int k = 0; k < 2; ++k) dst[m][k] = *(const LAS bf16x8*)(lds + PG8_SA(b, h) + aoff + m * 2048 + k * 1024); } while (0)
; #define PG8_LDB(dst, b, h) do { _Pragma("unroll") for (int n = 0; n < 2; ++n) _Pragma("unroll") for (int k = 0; k < 2; ++k) dst[n][k] = *(const LAS bf16x8*)(lds + PG8_SB(b, h) + boff + n * 2048 + k * 1024); } while (0)
; #define PG8_MMA(ai, bj, At, Bt) do { __builtin_amdgcn_s_setprio(1); _Pragma("unroll") for (int m = 0; m < 4; ++m) _Pragma("unroll") for (int n = 0; n < 2; ++n) _Pragma("unroll") for (int k = 0; k < 2; ++k) \
;         acc[ai][bj][m][n] = __builtin_amdgcn_mfma_f32_16x16x32_bf16(Bt[n][k], At[m][k], acc[ai][bj][m][n], 0, 0, 0); __builtin_amdgcn_s_setprio(0); } while (0)
; #define PG8_WAIT_V(n) asm volatile("s_waitcnt vmcnt(" #n ")" ::: "memory")
; #define PG8_WAIT_L(n) asm volatile("s_waitcnt lgkmcnt(" #n ")" ::: "memory")
; #define PG8_BAR __builtin_amdgcn_s_barrier()
; #define PG8_SCHED __builtin_amdgcn_sched_barrier(0)
; template <class Epi, class Sched>
; __device__ __forceinline__ void gemm_phase(LAS unsigned char* lds, const Gemm g, const Sched& S, const Epi& E) {
;     ...
;             PG8_LDB(B0, 0, 0); PG8_SCHED; PG8_LDA(At, 0, 0); PG8_STAGE(PG8_SA(1, 1), a1 + hstepA, voffA);
;             PG8_WAIT_L(8); PG8_BAR; PG8_WAIT_L(0); PG8_MMA(0, 0, At, B0); PG8_BAR; PG8_SCHED;
;             PG8_LDB(B1, 0, 1); PG8_STAGE(PG8_SB(0, 0), b2, voffB);
;             PG8_BAR; PG8_WAIT_L(0); PG8_MMA(0, 1, At, B1); PG8_BAR;
;             PG8_LDA(At, 0, 1); PG8_STAGE(PG8_SA(0, 0), a2, voffA);
;             PG8_BAR; PG8_WAIT_L(0); PG8_MMA(1, 0, At, B0); PG8_BAR; PG8_SCHED;
;             PG8_STAGE(PG8_SB(0, 1), b2 + hstepB, voffB);
;             PG8_WAIT_V(6); PG8_BAR; PG8_MMA(1, 1, At, B1); PG8_BAR;
.LBB0_668:
	s_add_u32 s23, s20, 0xfffc0080
	s_addc_u32 s34, s21, -1
	s_add_i32 s43, 0, 0x10000
	v_add_u32_e32 v153, s43, v150
	ds_read_b128 v[142:145], v153
	ds_read_b128 v[146:149], v153 offset:1024
	ds_read_b128 v[170:173], v153 offset:2048
	ds_read_b128 v[174:177], v153 offset:3072
	s_cmp_eq_u32 s31, 12
	s_cselect_b32 s49, s24, s34
	s_cselect_b32 s48, s25, s23
	s_cselect_b32 s37, s1, s29
	s_cselect_b32 s36, s26, s28
	v_lshl_add_u64 v[198:199], s[20:21], 0, v[138:139]
	s_add_i32 m0, s52, 0xc000
	ds_read_b128 v[178:181], v152
	ds_read_b128 v[182:185], v152 offset:1024
	ds_read_b128 v[186:189], v152 offset:2048
	ds_read_b128 v[190:193], v152 offset:3072
	ds_read_b128 v[194:197], v152 offset:4096
	ds_read_b128 v[210:213], v152 offset:5120
	ds_read_b128 v[214:217], v152 offset:6144
	ds_read_b128 v[218:221], v152 offset:7168
	global_load_lds_dwordx4 v[198:199], off
	v_lshl_add_u64 v[198:199], s[20:21], 0, v[140:141]
	s_add_i32 m0, s52, 0xe000
	s_nop 0
	global_load_lds_dwordx4 v[198:199], off
	s_waitcnt lgkmcnt(8)
	s_barrier
	s_waitcnt lgkmcnt(0)
	v_mfma_f32_16x16x32_bf16 v[126:129], v[142:145], v[178:181], v[126:129]
	v_mfma_f32_16x16x32_bf16 v[122:125], v[170:173], v[178:181], v[122:125]
	v_mfma_f32_16x16x32_bf16 v[110:113], v[142:145], v[186:189], v[110:113]
	v_mfma_f32_16x16x32_bf16 v[106:109], v[170:173], v[186:189], v[106:109]
	v_mfma_f32_16x16x32_bf16 v[94:97], v[142:145], v[194:197], v[94:97]
	v_mfma_f32_16x16x32_bf16 v[90:93], v[170:173], v[194:197], v[90:93]
	v_mfma_f32_16x16x32_bf16 v[78:81], v[142:145], v[214:217], v[78:81]
	v_mfma_f32_16x16x32_bf16 v[74:77], v[170:173], v[214:217], v[74:77]
	v_mfma_f32_16x16x32_bf16 v[126:129], v[146:149], v[182:185], v[126:129]
	v_mfma_f32_16x16x32_bf16 v[122:125], v[174:177], v[182:185], v[122:125]
	v_mfma_f32_16x16x32_bf16 v[110:113], v[146:149], v[190:193], v[110:113]
	v_mfma_f32_16x16x32_bf16 v[106:109], v[174:177], v[190:193], v[106:109]
	v_mfma_f32_16x16x32_bf16 v[94:97], v[146:149], v[210:213], v[94:97]
	v_mfma_f32_16x16x32_bf16 v[90:93], v[174:177], v[210:213], v[90:93]
	v_mfma_f32_16x16x32_bf16 v[78:81], v[146:149], v[218:221], v[78:81]
	v_mfma_f32_16x16x32_bf16 v[74:77], v[174:177], v[218:221], v[74:77]
	s_barrier
	s_add_i32 s23, 0, 0x14000
	s_add_i32 s34, s43, s51
	v_add_u32_e32 v153, s23, v150
	v_lshl_add_u64 v[198:199], s[36:37], 0, v[134:135]
	s_mov_b32 m0, s34
	ds_read_b128 v[222:225], v153
	ds_read_b128 v[226:229], v153 offset:1024
	ds_read_b128 v[230:233], v153 offset:2048
	ds_read_b128 v[234:237], v153 offset:3072
	global_load_lds_dwordx4 v[198:199], off
	v_lshl_add_u64 v[238:239], s[36:37], 0, v[130:131]
	s_add_i32 m0, s34, 0x2000
	s_nop 0
	global_load_lds_dwordx4 v[238:239], off
	s_barrier
	s_waitcnt lgkmcnt(0)
	v_mfma_f32_16x16x32_bf16 v[118:121], v[222:225], v[178:181], v[118:121]
	v_mfma_f32_16x16x32_bf16 v[114:117], v[230:233], v[178:181], v[114:117]
	v_mfma_f32_16x16x32_bf16 v[102:105], v[222:225], v[186:189], v[102:105]
	v_mfma_f32_16x16x32_bf16 v[98:101], v[230:233], v[186:189], v[98:101]
	v_mfma_f32_16x16x32_bf16 v[86:89], v[222:225], v[194:197], v[86:89]
	v_mfma_f32_16x16x32_bf16 v[82:85], v[230:233], v[194:197], v[82:85]
	v_mfma_f32_16x16x32_bf16 v[70:73], v[222:225], v[214:217], v[70:73]
	v_mfma_f32_16x16x32_bf16 v[66:69], v[230:233], v[214:217], v[66:69]
	v_mfma_f32_16x16x32_bf16 v[118:121], v[226:229], v[182:185], v[118:121]
	v_mfma_f32_16x16x32_bf16 v[114:117], v[234:237], v[182:185], v[114:117]
	v_mfma_f32_16x16x32_bf16 v[102:105], v[226:229], v[190:193], v[102:105]
	v_mfma_f32_16x16x32_bf16 v[98:101], v[234:237], v[190:193], v[98:101]
	v_mfma_f32_16x16x32_bf16 v[86:89], v[226:229], v[210:213], v[86:89]
	v_mfma_f32_16x16x32_bf16 v[82:85], v[234:237], v[210:213], v[82:85]
	v_mfma_f32_16x16x32_bf16 v[70:73], v[226:229], v[218:221], v[70:73]
	v_mfma_f32_16x16x32_bf16 v[66:69], v[234:237], v[218:221], v[66:69]
	s_mov_b32 m0, s52
	v_lshl_add_u64 v[240:241], s[48:49], 0, v[136:137]
	s_barrier
	ds_read_b128 v[178:181], v152 offset:16384
	ds_read_b128 v[182:185], v152 offset:17408
	ds_read_b128 v[186:189], v152 offset:18432
	ds_read_b128 v[190:193], v152 offset:19456
	ds_read_b128 v[194:197], v152 offset:20480
	ds_read_b128 v[210:213], v152 offset:21504
	ds_read_b128 v[214:217], v152 offset:22528
	ds_read_b128 v[218:221], v152 offset:23552
	global_load_lds_dwordx4 v[240:241], off
	v_lshl_add_u64 v[242:243], s[48:49], 0, v[132:133]
	s_mov_b32 m0, s53
	s_nop 0
	global_load_lds_dwordx4 v[242:243], off
	s_barrier
	s_waitcnt lgkmcnt(0)
	v_mfma_f32_16x16x32_bf16 v[62:65], v[142:145], v[178:181], v[62:65]
	v_mfma_f32_16x16x32_bf16 v[58:61], v[170:173], v[178:181], v[58:61]
	v_mfma_f32_16x16x32_bf16 v[46:49], v[142:145], v[186:189], v[46:49]
	v_mfma_f32_16x16x32_bf16 v[42:45], v[170:173], v[186:189], v[42:45]
	v_mfma_f32_16x16x32_bf16 v[30:33], v[142:145], v[194:197], v[30:33]
	v_mfma_f32_16x16x32_bf16 v[26:29], v[170:173], v[194:197], v[26:29]
	v_mfma_f32_16x16x32_bf16 v[14:17], v[142:145], v[214:217], v[14:17]
	v_mfma_f32_16x16x32_bf16 v[10:13], v[170:173], v[214:217], v[10:13]
	v_mfma_f32_16x16x32_bf16 v[62:65], v[146:149], v[182:185], v[62:65]
	v_mfma_f32_16x16x32_bf16 v[58:61], v[174:177], v[182:185], v[58:61]
	v_mfma_f32_16x16x32_bf16 v[46:49], v[146:149], v[190:193], v[46:49]
	v_mfma_f32_16x16x32_bf16 v[42:45], v[174:177], v[190:193], v[42:45]
	v_mfma_f32_16x16x32_bf16 v[30:33], v[146:149], v[210:213], v[30:33]
	v_mfma_f32_16x16x32_bf16 v[26:29], v[174:177], v[210:213], v[26:29]
	v_mfma_f32_16x16x32_bf16 v[14:17], v[146:149], v[218:221], v[14:17]
	v_mfma_f32_16x16x32_bf16 v[10:13], v[174:177], v[218:221], v[10:13]
	s_barrier
; #define PG8_STAGE(bufoff, gbase, voff) do { _Pragma("unroll") for (int _i = 0; _i < 2; ++_i) \
;         __builtin_amdgcn_global_load_lds((const unsigned*)((const char*)(gbase) + (voff)[_i]), (LAS unsigned*)(lds + (bufoff) + ldsw + _i * 8192), 16, 0, 0); } while (0)
; #define PG8_LDA(dst, b, h) do { _Pragma("unroll") for (int m = 0; m < 4; ++m) _Pragma("unroll") for (int k = 0; k < 2; ++k) dst[m][k] = *(const LAS bf16x8*)(lds + PG8_SA(b, h) + aoff + m * 2048 + k * 1024); } while (0)
; #define PG8_LDB(dst, b, h) do { _Pragma("unroll") for (int n = 0; n < 2; ++n) _Pragma("unroll") for (int k = 0; k < 2; ++k) dst[n][k] = *(const LAS bf16x8*)(lds + PG8_SB(b, h) + boff + n * 2048 + k * 1024); } while (0)
; #define PG8_MMA(ai, bj, At, Bt) do { __builtin_amdgcn_s_setprio(1); _Pragma("unroll") for (int m = 0; m < 4; ++m) _Pragma("unroll") for (int n = 0; n < 2; ++n) _Pragma("unroll") for (int k = 0; k < 2; ++k) \
;         acc[ai][bj][m][n] = __builtin_amdgcn_mfma_f32_16x16x32_bf16(Bt[n][k], At[m][k], acc[ai][bj][m][n], 0, 0, 0); __builtin_amdgcn_s_setprio(0); } while (0)
; #define PG8_WAIT_L(n) asm volatile("s_waitcnt lgkmcnt(" #n ")" ::: "memory")
; #define PG8_BAR __builtin_amdgcn_s_barrier()
; #define PG8_SCHED __builtin_amdgcn_sched_barrier(0)
; template <class Epi, class Sched>
; __device__ __forceinline__ void gemm_phase(LAS unsigned char* lds, const Gemm g, const Sched& S, const Epi& E) {
;     ...
;             PG8_LDB(B0, 1, 0); PG8_SCHED; PG8_LDA(At, 1, 0); PG8_STAGE(PG8_SA(0, 1), a2 + hstepA, voffA);
;             PG8_WAIT_L(8); PG8_BAR; PG8_WAIT_L(0); PG8_MMA(0, 0, At, B0); PG8_BAR; PG8_SCHED;
;             PG8_LDB(B1, 1, 1); PG8_STAGE(PG8_SB(1, 0), b3, voffB);
;             PG8_BAR; PG8_WAIT_L(0); PG8_MMA(0, 1, At, B1); PG8_BAR;
;             PG8_LDA(At, 1, 1); PG8_STAGE(PG8_SA(1, 0), a3, voffA);
;             PG8_BAR; PG8_WAIT_L(0); PG8_MMA(1, 0, At, B0); PG8_BAR; PG8_SCHED;
;             PG8_STAGE(PG8_SB(1, 1), b3 + hstepB, voffB);
	s_add_u32 s66, s36, 0x40000
	s_addc_u32 s67, s37, 0
	s_add_i32 s23, s23, s51
	v_lshl_add_u64 v[142:143], s[66:67], 0, v[134:135]
	s_mov_b32 m0, s23
	s_nop 0
	global_load_lds_dwordx4 v[142:143], off
	v_lshl_add_u64 v[142:143], s[66:67], 0, v[130:131]
	s_add_i32 m0, s23, 0x2000
	s_nop 0
	global_load_lds_dwordx4 v[142:143], off
	s_waitcnt vmcnt(6)
	s_barrier
	v_mfma_f32_16x16x32_bf16 v[54:57], v[222:225], v[178:181], v[54:57]
	v_mfma_f32_16x16x32_bf16 v[50:53], v[230:233], v[178:181], v[50:53]
	v_mfma_f32_16x16x32_bf16 v[38:41], v[222:225], v[186:189], v[38:41]
	v_mfma_f32_16x16x32_bf16 v[34:37], v[230:233], v[186:189], v[34:37]
	v_mfma_f32_16x16x32_bf16 v[22:25], v[222:225], v[194:197], v[22:25]
	v_mfma_f32_16x16x32_bf16 v[18:21], v[230:233], v[194:197], v[18:21]
	v_mfma_f32_16x16x32_bf16 v[6:9], v[222:225], v[214:217], v[6:9]
	v_mfma_f32_16x16x32_bf16 v[2:5], v[230:233], v[214:217], v[2:5]
	v_mfma_f32_16x16x32_bf16 v[54:57], v[226:229], v[182:185], v[54:57]
	v_mfma_f32_16x16x32_bf16 v[50:53], v[234:237], v[182:185], v[50:53]
	v_mfma_f32_16x16x32_bf16 v[38:41], v[226:229], v[190:193], v[38:41]
	v_mfma_f32_16x16x32_bf16 v[34:37], v[234:237], v[190:193], v[34:37]
	v_mfma_f32_16x16x32_bf16 v[22:25], v[226:229], v[210:213], v[22:25]
	v_mfma_f32_16x16x32_bf16 v[18:21], v[234:237], v[210:213], v[18:21]
	v_mfma_f32_16x16x32_bf16 v[6:9], v[226:229], v[218:221], v[6:9]
	v_mfma_f32_16x16x32_bf16 v[2:5], v[234:237], v[218:221], v[2:5]
	s_add_i32 s23, 0, 0x18000
	v_add_u32_e32 v153, s23, v150
	s_barrier
	ds_read_b128 v[142:145], v153
	ds_read_b128 v[146:149], v153 offset:1024
	ds_read_b128 v[170:173], v153 offset:2048
	ds_read_b128 v[174:177], v153 offset:3072
	s_add_u32 s48, s48, 0x40000
	s_addc_u32 s49, s49, 0
	s_mov_b32 m0, s54
	v_lshl_add_u64 v[222:223], s[48:49], 0, v[136:137]
	ds_read_b128 v[178:181], v152 offset:32768
	ds_read_b128 v[182:185], v152 offset:33792
	ds_read_b128 v[186:189], v152 offset:34816
	ds_read_b128 v[190:193], v152 offset:35840
	ds_read_b128 v[194:197], v152 offset:36864
	ds_read_b128 v[210:213], v152 offset:37888
	ds_read_b128 v[214:217], v152 offset:38912
	ds_read_b128 v[218:221], v152 offset:39936
	global_load_lds_dwordx4 v[222:223], off
	v_lshl_add_u64 v[222:223], s[48:49], 0, v[132:133]
	s_mov_b32 m0, s55
	s_nop 0
	global_load_lds_dwordx4 v[222:223], off
	s_waitcnt lgkmcnt(8)
	s_barrier
	s_waitcnt lgkmcnt(0)
	v_mfma_f32_16x16x32_bf16 v[126:129], v[142:145], v[178:181], v[126:129]
	v_mfma_f32_16x16x32_bf16 v[122:125], v[170:173], v[178:181], v[122:125]
	v_mfma_f32_16x16x32_bf16 v[110:113], v[142:145], v[186:189], v[110:113]
	v_mfma_f32_16x16x32_bf16 v[106:109], v[170:173], v[186:189], v[106:109]
	v_mfma_f32_16x16x32_bf16 v[94:97], v[142:145], v[194:197], v[94:97]
	v_mfma_f32_16x16x32_bf16 v[90:93], v[170:173], v[194:197], v[90:93]
	v_mfma_f32_16x16x32_bf16 v[78:81], v[142:145], v[214:217], v[78:81]
	v_mfma_f32_16x16x32_bf16 v[74:77], v[170:173], v[214:217], v[74:77]
	v_mfma_f32_16x16x32_bf16 v[126:129], v[146:149], v[182:185], v[126:129]
	v_mfma_f32_16x16x32_bf16 v[122:125], v[174:177], v[182:185], v[122:125]
	v_mfma_f32_16x16x32_bf16 v[110:113], v[146:149], v[190:193], v[110:113]
	v_mfma_f32_16x16x32_bf16 v[106:109], v[174:177], v[190:193], v[106:109]
	v_mfma_f32_16x16x32_bf16 v[94:97], v[146:149], v[210:213], v[94:97]
	v_mfma_f32_16x16x32_bf16 v[90:93], v[174:177], v[210:213], v[90:93]
	v_mfma_f32_16x16x32_bf16 v[78:81], v[146:149], v[218:221], v[78:81]
	v_mfma_f32_16x16x32_bf16 v[74:77], v[174:177], v[218:221], v[74:77]
	s_barrier
	s_add_i32 s34, 0, 0x1c000
	s_add_i32 s23, s23, s51
	v_add_u32_e32 v153, s34, v150
	v_lshl_add_u64 v[198:199], v[198:199], 0, s[10:11]
	s_mov_b32 m0, s23
	ds_read_b128 v[222:225], v153
	ds_read_b128 v[226:229], v153 offset:1024
	ds_read_b128 v[230:233], v153 offset:2048
	ds_read_b128 v[234:237], v153 offset:3072
	global_load_lds_dwordx4 v[198:199], off
	v_lshl_add_u64 v[198:199], v[238:239], 0, s[10:11]
	s_add_i32 m0, s23, 0x2000
	s_nop 0
	global_load_lds_dwordx4 v[198:199], off
	s_barrier
	s_waitcnt lgkmcnt(0)
	v_mfma_f32_16x16x32_bf16 v[118:121], v[222:225], v[178:181], v[118:121]
	v_mfma_f32_16x16x32_bf16 v[114:117], v[230:233], v[178:181], v[114:117]
	v_mfma_f32_16x16x32_bf16 v[102:105], v[222:225], v[186:189], v[102:105]
	v_mfma_f32_16x16x32_bf16 v[98:101], v[230:233], v[186:189], v[98:101]
	v_mfma_f32_16x16x32_bf16 v[86:89], v[222:225], v[194:197], v[86:89]
	v_mfma_f32_16x16x32_bf16 v[82:85], v[230:233], v[194:197], v[82:85]
	v_mfma_f32_16x16x32_bf16 v[70:73], v[222:225], v[214:217], v[70:73]
	v_mfma_f32_16x16x32_bf16 v[66:69], v[230:233], v[214:217], v[66:69]
	v_mfma_f32_16x16x32_bf16 v[118:121], v[226:229], v[182:185], v[118:121]
	v_mfma_f32_16x16x32_bf16 v[114:117], v[234:237], v[182:185], v[114:117]
	v_mfma_f32_16x16x32_bf16 v[102:105], v[226:229], v[190:193], v[102:105]
	v_mfma_f32_16x16x32_bf16 v[98:101], v[234:237], v[190:193], v[98:101]
	v_mfma_f32_16x16x32_bf16 v[86:89], v[226:229], v[210:213], v[86:89]
	v_mfma_f32_16x16x32_bf16 v[82:85], v[234:237], v[210:213], v[82:85]
	v_mfma_f32_16x16x32_bf16 v[70:73], v[226:229], v[218:221], v[70:73]
	v_mfma_f32_16x16x32_bf16 v[66:69], v[234:237], v[218:221], v[66:69]
	s_mov_b32 m0, s56
	v_lshl_add_u64 v[198:199], v[240:241], 0, s[10:11]
	s_barrier
	ds_read_b128 v[178:181], v152 offset:49152
	ds_read_b128 v[182:185], v152 offset:50176
	ds_read_b128 v[186:189], v152 offset:51200
	ds_read_b128 v[190:193], v152 offset:52224
	ds_read_b128 v[194:197], v152 offset:53248
	ds_read_b128 v[210:213], v152 offset:54272
	ds_read_b128 v[214:217], v152 offset:55296
	ds_read_b128 v[218:221], v152 offset:56320
	global_load_lds_dwordx4 v[198:199], off
	v_lshl_add_u64 v[198:199], v[242:243], 0, s[10:11]
	s_mov_b32 m0, s57
	s_nop 0
	global_load_lds_dwordx4 v[198:199], off
	s_barrier
; __device__ __forceinline__ float bf_lo(unsigned w) { return __uint_as_float(w << 16); }
; __device__ __forceinline__ float bf_hi(unsigned w) { return __uint_as_float(w & 0xffff0000u); }
; #define PG8_MMA(ai, bj, At, Bt) do { __builtin_amdgcn_s_setprio(1); _Pragma("unroll") for (int m = 0; m < 4; ++m) _Pragma("unroll") for (int n = 0; n < 2; ++n) _Pragma("unroll") for (int k = 0; k < 2; ++k) \
;         acc[ai][bj][m][n] = __builtin_amdgcn_mfma_f32_16x16x32_bf16(Bt[n][k], At[m][k], acc[ai][bj][m][n], 0, 0, 0); __builtin_amdgcn_s_setprio(0); } while (0)
; #define PG8_WAIT_V(n) asm volatile("s_waitcnt vmcnt(" #n ")" ::: "memory")
; #define PG8_BAR __builtin_amdgcn_s_barrier()
;     __device__ __forceinline__ void operator()(const f32x4 (&acc)[2][2][4][2], const Unit& u, int ui, const LAS float* rtab, int wr, int wc, int fr, int fq) const {
;         const int row0 = u.pm * BM + wr * 64 + fr, col0 = u.pn * BM + wc * 32 + 8 * fq;
; #pragma unroll
;         for (int ai = 0; ai < 2; ++ai)
; #pragma unroll
;             for (int m = 0; m < 4; ++m) {
;                 const int row = row0 + ai * HALF + m * 16;
; #pragma unroll
;                 for (int bj = 0; bj < 2; ++bj) {
;                     const int col = col0 + bj * HALF; const u32x4 yv = *(const u32x4*)(Y + (size_t)row * 1024 + col);
;                     const f32x4 a0 = acc[ai][bj][m][0], a1 = acc[ai][bj][m][1]; float o[8];
;                     const float yy[8] = {bf_lo(yv.x), bf_hi(yv.x), bf_lo(yv.y), bf_hi(yv.y), bf_lo(yv.z), bf_hi(yv.z), bf_lo(yv.w), bf_hi(yv.w)};
; #pragma unroll
;                     for (int e = 0; e < 4; ++e) { o[e] = yy[e] / (1.0f + __expf(-a0[e])); o[4 + e] = yy[4 + e] / (1.0f + __expf(-a1[e])); }
; template <class Epi, class Sched>
; __device__ __forceinline__ void gemm_phase(LAS unsigned char* lds, const Gemm g, const Sched& S, const Epi& E) {
;     ...
;             PG8_WAIT_V(6); PG8_BAR; PG8_MMA(1, 1, At, B1); PG8_BAR;
;         }
	s_waitcnt lgkmcnt(0)
	v_mfma_f32_16x16x32_bf16 v[62:65], v[142:145], v[178:181], v[62:65]
	v_mfma_f32_16x16x32_bf16 v[58:61], v[170:173], v[178:181], v[58:61]
	v_mfma_f32_16x16x32_bf16 v[46:49], v[142:145], v[186:189], v[46:49]
	v_mfma_f32_16x16x32_bf16 v[42:45], v[170:173], v[186:189], v[42:45]
	v_mfma_f32_16x16x32_bf16 v[30:33], v[142:145], v[194:197], v[30:33]
	v_mfma_f32_16x16x32_bf16 v[26:29], v[170:173], v[194:197], v[26:29]
	v_mfma_f32_16x16x32_bf16 v[14:17], v[142:145], v[214:217], v[14:17]
	v_mfma_f32_16x16x32_bf16 v[10:13], v[170:173], v[214:217], v[10:13]
	v_mfma_f32_16x16x32_bf16 v[62:65], v[146:149], v[182:185], v[62:65]
	v_mfma_f32_16x16x32_bf16 v[58:61], v[174:177], v[182:185], v[58:61]
	v_mfma_f32_16x16x32_bf16 v[46:49], v[146:149], v[190:193], v[46:49]
	v_mfma_f32_16x16x32_bf16 v[42:45], v[174:177], v[190:193], v[42:45]
	v_mfma_f32_16x16x32_bf16 v[30:33], v[146:149], v[210:213], v[30:33]
	v_mfma_f32_16x16x32_bf16 v[26:29], v[174:177], v[210:213], v[26:29]
	v_mfma_f32_16x16x32_bf16 v[14:17], v[146:149], v[218:221], v[14:17]
	v_mfma_f32_16x16x32_bf16 v[10:13], v[174:177], v[218:221], v[10:13]
	s_barrier
	s_add_u32 s36, s36, 0x40080
	s_addc_u32 s37, s37, 0
	s_add_i32 s23, s34, s51
	v_lshl_add_u64 v[142:143], s[36:37], 0, v[134:135]
	s_mov_b32 m0, s23
	s_nop 0
	global_load_lds_dwordx4 v[142:143], off
	v_lshl_add_u64 v[142:143], s[36:37], 0, v[130:131]
	s_add_i32 m0, s23, 0x2000
	s_nop 0
	global_load_lds_dwordx4 v[142:143], off
	s_waitcnt vmcnt(6)
	s_barrier
	v_mfma_f32_16x16x32_bf16 v[54:57], v[222:225], v[178:181], v[54:57]
	v_mfma_f32_16x16x32_bf16 v[50:53], v[230:233], v[178:181], v[50:53]
	v_mfma_f32_16x16x32_bf16 v[38:41], v[222:225], v[186:189], v[38:41]
	v_mfma_f32_16x16x32_bf16 v[34:37], v[230:233], v[186:189], v[34:37]
	v_mfma_f32_16x16x32_bf16 v[22:25], v[222:225], v[194:197], v[22:25]
	v_mfma_f32_16x16x32_bf16 v[18:21], v[230:233], v[194:197], v[18:21]
	v_mfma_f32_16x16x32_bf16 v[6:9], v[222:225], v[214:217], v[6:9]
	v_mfma_f32_16x16x32_bf16 v[2:5], v[230:233], v[214:217], v[2:5]
	v_mfma_f32_16x16x32_bf16 v[54:57], v[226:229], v[182:185], v[54:57]
	v_mfma_f32_16x16x32_bf16 v[50:53], v[234:237], v[182:185], v[50:53]
	v_mfma_f32_16x16x32_bf16 v[38:41], v[226:229], v[190:193], v[38:41]
	v_mfma_f32_16x16x32_bf16 v[34:37], v[234:237], v[190:193], v[34:37]
	v_mfma_f32_16x16x32_bf16 v[22:25], v[226:229], v[210:213], v[22:25]
	v_mfma_f32_16x16x32_bf16 v[18:21], v[234:237], v[210:213], v[18:21]
	v_mfma_f32_16x16x32_bf16 v[6:9], v[226:229], v[218:221], v[6:9]
	v_mfma_f32_16x16x32_bf16 v[2:5], v[234:237], v[218:221], v[2:5]
	s_add_i32 s31, s31, 2
	s_add_u32 s20, s20, 0x100
	s_addc_u32 s21, s21, 0
	s_add_u32 s28, s28, 0x100
	s_addc_u32 s29, s29, 0
	s_cmp_gt_u32 s31, 13
	s_barrier
	s_cbranch_scc0 .LBB0_668
	v_lshl_add_u32 v144, s13, 8, v1
	v_lshl_or_b32 v142, s12, 8, v151
	v_ashrrev_i32_e32 v145, 31, v144
	v_lshlrev_b64 v[146:147], 11, v[144:145]
	v_ashrrev_i32_e32 v143, 31, v142
	v_lshl_add_u64 v[146:147], s[86:87], 0, v[146:147]
	v_lshlrev_b64 v[142:143], 1, v[142:143]
	v_lshl_add_u64 v[146:147], v[146:147], 0, v[142:143]
	global_load_dwordx4 v[170:173], v[146:147], off
	v_mul_f32_e32 v126, 0xbfb8aa3b, v126
	v_exp_f32_e32 v126, v126
	v_lshlrev_b64 v[148:149], 12, v[144:145]
	v_mul_f32_e32 v122, 0xbfb8aa3b, v122
	v_exp_f32_e32 v122, v122
	v_add_f32_e32 v126, 1.0, v126
	v_mul_f32_e32 v127, 0xbfb8aa3b, v127
	v_exp_f32_e32 v127, v127
	v_add_f32_e32 v122, 1.0, v122
	v_mul_f32_e32 v123, 0xbfb8aa3b, v123
	v_exp_f32_e32 v123, v123
	v_add_f32_e32 v127, 1.0, v127
	v_mul_f32_e32 v128, 0xbfb8aa3b, v128
	v_exp_f32_e32 v128, v128
	v_add_f32_e32 v123, 1.0, v123
	v_mul_f32_e32 v124, 0xbfb8aa3b, v124
	v_exp_f32_e32 v124, v124
	v_add_f32_e32 v128, 1.0, v128
	v_mul_f32_e32 v118, 0xbfb8aa3b, v118
	v_exp_f32_e32 v118, v118
	v_add_f32_e32 v124, 1.0, v124
	v_mul_f32_e32 v114, 0xbfb8aa3b, v114
	v_exp_f32_e32 v114, v114
	v_add_f32_e32 v118, 1.0, v118
	v_mul_f32_e32 v119, 0xbfb8aa3b, v119
	v_exp_f32_e32 v119, v119
	v_add_f32_e32 v114, 1.0, v114
	v_mul_f32_e32 v115, 0xbfb8aa3b, v115
	v_exp_f32_e32 v115, v115
	v_add_f32_e32 v119, 1.0, v119
	v_mul_f32_e32 v120, 0xbfb8aa3b, v120
	v_exp_f32_e32 v120, v120
	v_add_f32_e32 v115, 1.0, v115
	v_mul_f32_e32 v116, 0xbfb8aa3b, v116
	v_exp_f32_e32 v116, v116
	v_add_f32_e32 v120, 1.0, v120
	v_mul_f32_e32 v110, 0xbfb8aa3b, v110
	v_exp_f32_e32 v110, v110
	v_add_f32_e32 v116, 1.0, v116
	v_mul_f32_e32 v106, 0xbfb8aa3b, v106
	v_exp_f32_e32 v106, v106
	v_add_f32_e32 v110, 1.0, v110
	v_mul_f32_e32 v111, 0xbfb8aa3b, v111
	v_exp_f32_e32 v111, v111
	v_add_f32_e32 v106, 1.0, v106
	v_mul_f32_e32 v107, 0xbfb8aa3b, v107
	v_exp_f32_e32 v107, v107
	v_add_f32_e32 v111, 1.0, v111
	v_mul_f32_e32 v112, 0xbfb8aa3b, v112
	v_exp_f32_e32 v112, v112
	v_add_f32_e32 v107, 1.0, v107
	v_mul_f32_e32 v108, 0xbfb8aa3b, v108
	v_exp_f32_e32 v108, v108
	v_add_f32_e32 v112, 1.0, v112
	v_mul_f32_e32 v102, 0xbfb8aa3b, v102
	v_exp_f32_e32 v102, v102
	v_add_f32_e32 v108, 1.0, v108
	v_mul_f32_e32 v98, 0xbfb8aa3b, v98
	v_exp_f32_e32 v98, v98
	v_add_f32_e32 v102, 1.0, v102
	v_mul_f32_e32 v99, 0xbfb8aa3b, v99
	v_exp_f32_e32 v99, v99
	v_add_f32_e32 v98, 1.0, v98
	v_mul_f32_e32 v100, 0xbfb8aa3b, v100
	v_exp_f32_e32 v100, v100
	v_add_f32_e32 v99, 1.0, v99
	v_mul_f32_e32 v101, 0xbfb8aa3b, v101
	v_exp_f32_e32 v101, v101
	v_add_f32_e32 v100, 1.0, v100
	v_mul_f32_e32 v94, 0xbfb8aa3b, v94
	v_exp_f32_e32 v94, v94
	v_add_f32_e32 v101, 1.0, v101
	v_mul_f32_e32 v90, 0xbfb8aa3b, v90
	v_exp_f32_e32 v90, v90
	v_add_f32_e32 v94, 1.0, v94
	v_mul_f32_e32 v95, 0xbfb8aa3b, v95
	v_exp_f32_e32 v95, v95
	v_add_f32_e32 v90, 1.0, v90
	v_mul_f32_e32 v91, 0xbfb8aa3b, v91
	s_waitcnt vmcnt(0)
; __device__ __forceinline__ unsigned cvt_pk_bf16(float lo, float hi) { unsigned r; asm volatile("v_cvt_pk_bf16_f32 %0, %1, %2" : "=v"(r) : "v"(lo), "v"(hi)); return r; }
; __device__ __forceinline__ float bf_lo(unsigned w) { return __uint_as_float(w << 16); }
; __device__ __forceinline__ float bf_hi(unsigned w) { return __uint_as_float(w & 0xffff0000u); }
;     __device__ __forceinline__ void operator()(const f32x4 (&acc)[2][2][4][2], const Unit& u, int ui, const LAS float* rtab, int wr, int wc, int fr, int fq) const {
;     ...
;             for (int m = 0; m < 4; ++m) {
;                 const int row = row0 + ai * HALF + m * 16;
; #pragma unroll
;                 for (int bj = 0; bj < 2; ++bj) {
;                     const int col = col0 + bj * HALF; const u32x4 yv = *(const u32x4*)(Y + (size_t)row * 1024 + col);
;                     const f32x4 a0 = acc[ai][bj][m][0], a1 = acc[ai][bj][m][1]; float o[8];
;                     const float yy[8] = {bf_lo(yv.x), bf_hi(yv.x), bf_lo(yv.y), bf_hi(yv.y), bf_lo(yv.z), bf_hi(yv.z), bf_lo(yv.w), bf_hi(yv.w)};
; #pragma unroll
;                     for (int e = 0; e < 4; ++e) { o[e] = yy[e] / (1.0f + __expf(-a0[e])); o[4 + e] = yy[4 + e] / (1.0f + __expf(-a1[e])); }
;                     u32x4 w; w.x = cvt_pk_bf16(o[0], o[1]); w.y = cvt_pk_bf16(o[2], o[3]); w.z = cvt_pk_bf16(o[4], o[5]); w.w = cvt_pk_bf16(o[6], o[7]);
;                     *(u32x4*)(MG + (size_t)row * DM + 1024 + col) = w;
	v_lshlrev_b32_e32 v174, 16, v170
	v_lshlrev_b32_e32 v162, 16, v173
	v_and_b32_e32 v145, 0xffff0000, v173
	v_div_scale_f32 v173, s[12:13], v126, v126, v174
	v_rcp_f32_e32 v176, v173
	v_lshlrev_b32_e32 v175, 16, v171
	v_and_b32_e32 v153, 0xffff0000, v171
	v_lshlrev_b32_e32 v171, 16, v172
	v_fma_f32 v177, -v173, v176, 1.0
	v_fmac_f32_e32 v176, v177, v176
	v_div_scale_f32 v177, vcc, v174, v126, v174
	v_mul_f32_e32 v178, v177, v176
	v_fma_f32 v179, -v173, v178, v177
	v_rcp_f32_e32 v126, v126
	s_nop 0
	v_mul_f32_e32 v126, v174, v126
	v_div_scale_f32 v173, s[12:13], v122, v122, v171
	v_rcp_f32_e32 v174, v173
	v_and_b32_e32 v170, 0xffff0000, v170
	v_and_b32_e32 v172, 0xffff0000, v172
	v_add_f32_e32 v95, 1.0, v95
	v_fma_f32 v176, -v173, v174, 1.0
	v_fmac_f32_e32 v174, v176, v174
	v_div_scale_f32 v176, vcc, v171, v122, v171
	v_mul_f32_e32 v177, v176, v174
	v_fma_f32 v178, -v173, v177, v176
	v_rcp_f32_e32 v122, v122
	s_nop 0
	v_mul_f32_e32 v122, v171, v122
	v_exp_f32_e32 v91, v91
	v_mul_f32_e32 v96, 0xbfb8aa3b, v96
	v_exp_f32_e32 v96, v96
	v_rcp_f32_e32 v127, v127
	s_nop 0
	v_mul_f32_e32 v127, v170, v127
	v_add_f32_e32 v91, 1.0, v91
	v_add_f32_e32 v96, 1.0, v96
	v_mul_f32_e32 v92, 0xbfb8aa3b, v92
	v_rcp_f32_e32 v123, v123
	s_nop 0
	v_mul_f32_e32 v123, v172, v123
	v_exp_f32_e32 v92, v92
	v_mul_f32_e32 v86, 0xbfb8aa3b, v86
	v_exp_f32_e32 v86, v86
	v_rcp_f32_e32 v128, v128
	s_nop 0
	v_mul_f32_e32 v128, v175, v128
	v_add_f32_e32 v92, 1.0, v92
	v_add_f32_e32 v86, 1.0, v86
	v_mul_f32_e32 v82, 0xbfb8aa3b, v82
	v_rcp_f32_e32 v170, v124
	s_nop 0
	v_mul_f32_e32 v162, v162, v170
	v_mul_f32_e32 v124, 0xbfb8aa3b, v129
	v_exp_f32_e32 v124, v124
	v_exp_f32_e32 v82, v82
	v_mul_f32_e32 v83, 0xbfb8aa3b, v83
	v_exp_f32_e32 v83, v83
	v_add_f32_e32 v124, 1.0, v124
	v_add_f32_e32 v82, 1.0, v82
	v_add_f32_e32 v83, 1.0, v83
	v_mul_f32_e32 v84, 0xbfb8aa3b, v84
	v_rcp_f32_e32 v129, v124
	s_nop 0
	v_mul_f32_e32 v129, v153, v129
	v_mul_f32_e32 v124, 0xbfb8aa3b, v125
	v_exp_f32_e32 v124, v124
	v_exp_f32_e32 v84, v84
	v_mul_f32_e32 v85, 0xbfb8aa3b, v85
	v_exp_f32_e32 v85, v85
	v_add_f32_e32 v124, 1.0, v124
	v_add_f32_e32 v84, 1.0, v84
	v_add_f32_e32 v85, 1.0, v85
	v_mul_f32_e32 v78, 0xbfb8aa3b, v78
	v_rcp_f32_e32 v125, v124
	s_nop 0
	v_mul_f32_e32 v145, v145, v125
	v_cvt_pk_bf16_f32 v124, v126, v127
	v_cvt_pk_bf16_f32 v125, v128, v129
	v_cvt_pk_bf16_f32 v126, v122, v123
	v_lshl_add_u64 v[122:123], s[88:89], 0, v[148:149]
	v_cvt_pk_bf16_f32 v127, v162, v145
	v_lshl_add_u64 v[122:123], v[122:123], 0, v[142:143]
	global_store_dwordx4 v[122:123], v[124:127], off offset:2048
	global_load_dwordx4 v[124:127], v[146:147], off offset:256
	v_exp_f32_e32 v78, v78
	v_mul_f32_e32 v74, 0xbfb8aa3b, v74
	v_exp_f32_e32 v74, v74
	v_mul_f32_e32 v79, 0xbfb8aa3b, v79
	v_add_f32_e32 v78, 1.0, v78
	v_exp_f32_e32 v79, v79
	v_add_f32_e32 v74, 1.0, v74
	v_mul_f32_e32 v75, 0xbfb8aa3b, v75
	v_exp_f32_e32 v75, v75
	v_add_f32_e32 v79, 1.0, v79
	v_mul_f32_e32 v80, 0xbfb8aa3b, v80
	v_exp_f32_e32 v80, v80
	v_add_f32_e32 v75, 1.0, v75
	v_mul_f32_e32 v76, 0xbfb8aa3b, v76
	v_exp_f32_e32 v76, v76
	v_add_f32_e32 v80, 1.0, v80
	v_mul_f32_e32 v70, 0xbfb8aa3b, v70
	v_exp_f32_e32 v70, v70
	v_add_f32_e32 v76, 1.0, v76
	v_mul_f32_e32 v66, 0xbfb8aa3b, v66
	v_exp_f32_e32 v66, v66
	v_add_f32_e32 v70, 1.0, v70
	v_mul_f32_e32 v67, 0xbfb8aa3b, v67
	v_exp_f32_e32 v67, v67
	v_add_f32_e32 v66, 1.0, v66
	v_mul_f32_e32 v68, 0xbfb8aa3b, v68
	v_exp_f32_e32 v68, v68
	v_add_f32_e32 v67, 1.0, v67
	v_mul_f32_e32 v69, 0xbfb8aa3b, v69
	v_exp_f32_e32 v69, v69
	v_add_f32_e32 v68, 1.0, v68
	v_mul_f32_e32 v62, 0xbfb8aa3b, v62
	v_exp_f32_e32 v62, v62
	v_add_f32_e32 v69, 1.0, v69
	v_mul_f32_e32 v58, 0xbfb8aa3b, v58
	v_exp_f32_e32 v58, v58
	v_add_f32_e32 v62, 1.0, v62
	v_mul_f32_e32 v63, 0xbfb8aa3b, v63
	v_exp_f32_e32 v63, v63
	v_add_f32_e32 v58, 1.0, v58
	v_mul_f32_e32 v59, 0xbfb8aa3b, v59
	v_exp_f32_e32 v59, v59
	v_add_f32_e32 v63, 1.0, v63
	v_mul_f32_e32 v64, 0xbfb8aa3b, v64
	v_exp_f32_e32 v64, v64
	v_add_f32_e32 v59, 1.0, v59
	v_mul_f32_e32 v60, 0xbfb8aa3b, v60
	v_exp_f32_e32 v60, v60
	v_add_f32_e32 v64, 1.0, v64
	v_mul_f32_e32 v54, 0xbfb8aa3b, v54
	v_exp_f32_e32 v54, v54
	v_add_f32_e32 v60, 1.0, v60
	v_mul_f32_e32 v50, 0xbfb8aa3b, v50
	v_exp_f32_e32 v50, v50
	v_add_f32_e32 v54, 1.0, v54
	v_mul_f32_e32 v51, 0xbfb8aa3b, v51
	v_exp_f32_e32 v51, v51
	v_add_f32_e32 v50, 1.0, v50
	v_mul_f32_e32 v52, 0xbfb8aa3b, v52
	v_exp_f32_e32 v52, v52
	v_add_f32_e32 v51, 1.0, v51
	v_mul_f32_e32 v53, 0xbfb8aa3b, v53
	v_exp_f32_e32 v53, v53
	v_add_f32_e32 v52, 1.0, v52
	v_mul_f32_e32 v46, 0xbfb8aa3b, v46
	v_exp_f32_e32 v46, v46
	v_add_f32_e32 v53, 1.0, v53
	v_mul_f32_e32 v42, 0xbfb8aa3b, v42
	v_exp_f32_e32 v42, v42
	v_add_f32_e32 v46, 1.0, v46
	v_mul_f32_e32 v47, 0xbfb8aa3b, v47
	v_exp_f32_e32 v47, v47
	v_add_f32_e32 v42, 1.0, v42
	v_mul_f32_e32 v43, 0xbfb8aa3b, v43
	v_exp_f32_e32 v43, v43
	v_add_f32_e32 v47, 1.0, v47
	v_mul_f32_e32 v48, 0xbfb8aa3b, v48
	v_exp_f32_e32 v48, v48
	v_add_f32_e32 v43, 1.0, v43
	s_waitcnt vmcnt(0)
; __device__ __forceinline__ unsigned cvt_pk_bf16(float lo, float hi) { unsigned r; asm volatile("v_cvt_pk_bf16_f32 %0, %1, %2" : "=v"(r) : "v"(lo), "v"(hi)); return r; }
; __device__ __forceinline__ float bf_lo(unsigned w) { return __uint_as_float(w << 16); }
; __device__ __forceinline__ float bf_hi(unsigned w) { return __uint_as_float(w & 0xffff0000u); }
;     __device__ __forceinline__ void operator()(const f32x4 (&acc)[2][2][4][2], const Unit& u, int ui, const LAS float* rtab, int wr, int wc, int fr, int fq) const {
;     ...
;             for (int m = 0; m < 4; ++m) {
;                 const int row = row0 + ai * HALF + m * 16;
; #pragma unroll
;                 for (int bj = 0; bj < 2; ++bj) {
;                     const int col = col0 + bj * HALF; const u32x4 yv = *(const u32x4*)(Y + (size_t)row * 1024 + col);
;                     const f32x4 a0 = acc[ai][bj][m][0], a1 = acc[ai][bj][m][1]; float o[8];
;                     const float yy[8] = {bf_lo(yv.x), bf_hi(yv.x), bf_lo(yv.y), bf_hi(yv.y), bf_lo(yv.z), bf_hi(yv.z), bf_lo(yv.w), bf_hi(yv.w)};
; #pragma unroll
;                     for (int e = 0; e < 4; ++e) { o[e] = yy[e] / (1.0f + __expf(-a0[e])); o[4 + e] = yy[4 + e] / (1.0f + __expf(-a1[e])); }
;                     u32x4 w; w.x = cvt_pk_bf16(o[0], o[1]); w.y = cvt_pk_bf16(o[2], o[3]); w.z = cvt_pk_bf16(o[4], o[5]); w.w = cvt_pk_bf16(o[6], o[7]);
;                     *(u32x4*)(MG + (size_t)row * DM + 1024 + col) = w;
	v_lshlrev_b32_e32 v128, 16, v124
	v_and_b32_e32 v129, 0xffff0000, v124
	v_lshlrev_b32_e32 v146, 16, v126
	v_and_b32_e32 v147, 0xffff0000, v126
	v_lshlrev_b32_e32 v126, 16, v127
	v_and_b32_e32 v124, 0xffff0000, v127
	v_div_scale_f32 v127, s[12:13], v118, v118, v128
	v_rcp_f32_e32 v148, v127
	v_lshlrev_b32_e32 v145, 16, v125
	v_and_b32_e32 v125, 0xffff0000, v125
	v_add_f32_e32 v48, 1.0, v48
	v_fma_f32 v149, -v127, v148, 1.0
	v_fmac_f32_e32 v148, v149, v148
	v_div_scale_f32 v149, vcc, v128, v118, v128
	v_mul_f32_e32 v153, v149, v148
	v_fma_f32 v162, -v127, v153, v149
	v_rcp_f32_e32 v118, v118
	s_nop 0
	v_mul_f32_e32 v118, v128, v118
	v_div_scale_f32 v127, s[12:13], v114, v114, v146
	v_rcp_f32_e32 v128, v127
	v_mul_f32_e32 v44, 0xbfb8aa3b, v44
	v_exp_f32_e32 v44, v44
	v_mul_f32_e32 v38, 0xbfb8aa3b, v38
	v_fma_f32 v148, -v127, v128, 1.0
	v_fmac_f32_e32 v128, v148, v128
	v_div_scale_f32 v148, vcc, v146, v114, v146
	v_mul_f32_e32 v149, v148, v128
	v_fma_f32 v153, -v127, v149, v148
	v_rcp_f32_e32 v114, v114
	s_nop 0
	v_mul_f32_e32 v114, v146, v114
	v_add_f32_e32 v44, 1.0, v44
	v_exp_f32_e32 v38, v38
	v_mul_f32_e32 v34, 0xbfb8aa3b, v34
	v_rcp_f32_e32 v119, v119
	s_nop 0
	v_mul_f32_e32 v119, v129, v119
	v_add_f32_e32 v38, 1.0, v38
	v_exp_f32_e32 v34, v34
	v_mul_f32_e32 v35, 0xbfb8aa3b, v35
	v_rcp_f32_e32 v115, v115
	s_nop 0
	v_mul_f32_e32 v115, v147, v115
	v_div_scale_f32 v127, s[12:13], v120, v120, v145
	v_rcp_f32_e32 v128, v127
	v_add_f32_e32 v34, 1.0, v34
	v_exp_f32_e32 v35, v35
	v_mul_f32_e32 v36, 0xbfb8aa3b, v36
	v_fma_f32 v129, -v127, v128, 1.0
	v_fmac_f32_e32 v128, v129, v128
	v_div_scale_f32 v129, vcc, v145, v120, v145
	v_mul_f32_e32 v146, v129, v128
	v_fma_f32 v147, -v127, v146, v129
	v_rcp_f32_e32 v120, v120
	s_nop 0
	v_mul_f32_e32 v120, v145, v120
	v_add_f32_e32 v35, 1.0, v35
	v_exp_f32_e32 v36, v36
	v_mul_f32_e32 v37, 0xbfb8aa3b, v37
	v_rcp_f32_e32 v127, v116
	s_nop 0
	v_mul_f32_e32 v126, v126, v127
	v_mul_f32_e32 v116, 0xbfb8aa3b, v121
	v_exp_f32_e32 v116, v116
	v_add_f32_e32 v36, 1.0, v36
	v_exp_f32_e32 v37, v37
	v_mul_f32_e32 v30, 0xbfb8aa3b, v30
	v_add_f32_e32 v116, 1.0, v116
	v_add_f32_e32 v37, 1.0, v37
	v_exp_f32_e32 v30, v30
	v_mul_f32_e32 v26, 0xbfb8aa3b, v26
	v_rcp_f32_e32 v121, v116
	s_nop 0
	v_mul_f32_e32 v121, v125, v121
	v_mul_f32_e32 v116, 0xbfb8aa3b, v117
	v_exp_f32_e32 v116, v116
	v_add_f32_e32 v30, 1.0, v30
	v_exp_f32_e32 v26, v26
	v_mul_f32_e32 v31, 0xbfb8aa3b, v31
	v_add_f32_e32 v116, 1.0, v116
	v_add_f32_e32 v26, 1.0, v26
	v_exp_f32_e32 v31, v31
	v_mul_f32_e32 v27, 0xbfb8aa3b, v27
	v_rcp_f32_e32 v117, v116
	s_nop 0
	v_mul_f32_e32 v124, v124, v117
	v_cvt_pk_bf16_f32 v116, v118, v119
	v_cvt_pk_bf16_f32 v117, v120, v121
	v_cvt_pk_bf16_f32 v118, v114, v115
	v_or_b32_e32 v114, 16, v144
	v_cvt_pk_bf16_f32 v119, v126, v124
	v_ashrrev_i32_e32 v115, 31, v114
	global_store_dwordx4 v[122:123], v[116:119], off offset:2304
	v_add_f32_e32 v31, 1.0, v31
	v_exp_f32_e32 v27, v27
	v_lshlrev_b64 v[118:119], 11, v[114:115]
	v_lshlrev_b64 v[116:117], 12, v[114:115]
	v_lshl_add_u64 v[114:115], s[86:87], 0, v[118:119]
	v_lshl_add_u64 v[114:115], v[114:115], 0, v[142:143]
	global_load_dwordx4 v[118:121], v[114:115], off
	v_add_f32_e32 v27, 1.0, v27
	v_mul_f32_e32 v32, 0xbfb8aa3b, v32
	v_exp_f32_e32 v32, v32
	v_mul_f32_e32 v28, 0xbfb8aa3b, v28
	v_exp_f32_e32 v28, v28
	v_mul_f32_e32 v22, 0xbfb8aa3b, v22
	v_add_f32_e32 v32, 1.0, v32
	v_exp_f32_e32 v22, v22
	v_add_f32_e32 v28, 1.0, v28
	v_mul_f32_e32 v18, 0xbfb8aa3b, v18
	v_exp_f32_e32 v18, v18
	v_add_f32_e32 v22, 1.0, v22
	v_mul_f32_e32 v19, 0xbfb8aa3b, v19
	v_exp_f32_e32 v19, v19
	v_add_f32_e32 v18, 1.0, v18
	v_mul_f32_e32 v20, 0xbfb8aa3b, v20
	v_exp_f32_e32 v20, v20
	v_add_f32_e32 v19, 1.0, v19
	v_mul_f32_e32 v21, 0xbfb8aa3b, v21
	v_exp_f32_e32 v21, v21
	v_add_f32_e32 v20, 1.0, v20
	v_mul_f32_e32 v14, 0xbfb8aa3b, v14
	v_exp_f32_e32 v14, v14
	v_add_f32_e32 v21, 1.0, v21
	v_mul_f32_e32 v10, 0xbfb8aa3b, v10
	v_exp_f32_e32 v10, v10
	v_add_f32_e32 v14, 1.0, v14
	v_mul_f32_e32 v15, 0xbfb8aa3b, v15
	v_exp_f32_e32 v15, v15
	v_add_f32_e32 v10, 1.0, v10
	v_mul_f32_e32 v11, 0xbfb8aa3b, v11
	v_exp_f32_e32 v11, v11
	v_add_f32_e32 v15, 1.0, v15
	v_mul_f32_e32 v16, 0xbfb8aa3b, v16
	v_exp_f32_e32 v16, v16
	v_add_f32_e32 v11, 1.0, v11
	v_mul_f32_e32 v12, 0xbfb8aa3b, v12
	v_exp_f32_e32 v12, v12
	v_add_f32_e32 v16, 1.0, v16
	v_mul_f32_e32 v6, 0xbfb8aa3b, v6
	v_exp_f32_e32 v6, v6
	v_add_f32_e32 v12, 1.0, v12
	v_mul_f32_e32 v2, 0xbfb8aa3b, v2
	v_exp_f32_e32 v2, v2
	v_add_f32_e32 v6, 1.0, v6
	v_mul_f32_e32 v3, 0xbfb8aa3b, v3
	v_exp_f32_e32 v3, v3
	v_add_f32_e32 v2, 1.0, v2
	v_mul_f32_e32 v4, 0xbfb8aa3b, v4
	v_exp_f32_e32 v4, v4
	v_add_f32_e32 v3, 1.0, v3
	v_mul_f32_e32 v5, 0xbfb8aa3b, v5
	v_exp_f32_e32 v5, v5
	v_add_f32_e32 v4, 1.0, v4
	s_mov_b64 s[36:37], s[46:47]
	s_mov_b64 s[20:21], s[44:45]
	v_add_f32_e32 v5, 1.0, v5
	s_waitcnt vmcnt(0)
; __device__ __forceinline__ unsigned cvt_pk_bf16(float lo, float hi) { unsigned r; asm volatile("v_cvt_pk_bf16_f32 %0, %1, %2" : "=v"(r) : "v"(lo), "v"(hi)); return r; }
; __device__ __forceinline__ float bf_lo(unsigned w) { return __uint_as_float(w << 16); }
; __device__ __forceinline__ float bf_hi(unsigned w) { return __uint_as_float(w & 0xffff0000u); }
;     __device__ __forceinline__ void operator()(const f32x4 (&acc)[2][2][4][2], const Unit& u, int ui, const LAS float* rtab, int wr, int wc, int fr, int fq) const {
;     ...
;             for (int m = 0; m < 4; ++m) {
;                 const int row = row0 + ai * HALF + m * 16;
; #pragma unroll
;                 for (int bj = 0; bj < 2; ++bj) {
;                     const int col = col0 + bj * HALF; const u32x4 yv = *(const u32x4*)(Y + (size_t)row * 1024 + col);
;                     const f32x4 a0 = acc[ai][bj][m][0], a1 = acc[ai][bj][m][1]; float o[8];
;                     const float yy[8] = {bf_lo(yv.x), bf_hi(yv.x), bf_lo(yv.y), bf_hi(yv.y), bf_lo(yv.z), bf_hi(yv.z), bf_lo(yv.w), bf_hi(yv.w)};
; #pragma unroll
;                     for (int e = 0; e < 4; ++e) { o[e] = yy[e] / (1.0f + __expf(-a0[e])); o[4 + e] = yy[4 + e] / (1.0f + __expf(-a1[e])); }
;                     u32x4 w; w.x = cvt_pk_bf16(o[0], o[1]); w.y = cvt_pk_bf16(o[2], o[3]); w.z = cvt_pk_bf16(o[4], o[5]); w.w = cvt_pk_bf16(o[6], o[7]);
;                     *(u32x4*)(MG + (size_t)row * DM + 1024 + col) = w;
	v_lshlrev_b32_e32 v122, 16, v118
	v_and_b32_e32 v123, 0xffff0000, v118
	v_lshlrev_b32_e32 v126, 16, v121
	v_and_b32_e32 v118, 0xffff0000, v121
	v_div_scale_f32 v121, s[12:13], v110, v110, v122
	v_rcp_f32_e32 v127, v121
	v_lshlrev_b32_e32 v125, 16, v120
	v_and_b32_e32 v120, 0xffff0000, v120
	v_lshlrev_b32_e32 v124, 16, v119
	v_fma_f32 v128, -v121, v127, 1.0
	v_fmac_f32_e32 v127, v128, v127
	v_div_scale_f32 v128, vcc, v122, v110, v122
	v_mul_f32_e32 v129, v128, v127
	v_fma_f32 v145, -v121, v129, v128
	v_rcp_f32_e32 v110, v110
	s_nop 0
	v_mul_f32_e32 v110, v122, v110
	v_and_b32_e32 v119, 0xffff0000, v119
	v_rcp_f32_e32 v106, v106
	s_nop 0
	v_mul_f32_e32 v106, v125, v106
	s_nop 0
	v_rcp_f32_e32 v111, v111
	s_nop 0
	v_mul_f32_e32 v111, v123, v111
	s_nop 0
	v_rcp_f32_e32 v107, v107
	s_nop 0
	v_mul_f32_e32 v107, v120, v107
	s_nop 0
	v_rcp_f32_e32 v112, v112
	s_nop 0
	v_mul_f32_e32 v112, v124, v112
	s_nop 0
	v_rcp_f32_e32 v120, v108
	s_nop 0
	v_mul_f32_e32 v120, v126, v120
	v_mul_f32_e32 v108, 0xbfb8aa3b, v113
	v_exp_f32_e32 v108, v108
	s_nop 0
	v_add_f32_e32 v108, 1.0, v108
	s_nop 0
	v_rcp_f32_e32 v113, v108
	s_nop 0
	v_mul_f32_e32 v113, v119, v113
	v_mul_f32_e32 v108, 0xbfb8aa3b, v109
	v_exp_f32_e32 v108, v108
	s_nop 0
	v_add_f32_e32 v108, 1.0, v108
	s_nop 0
	v_rcp_f32_e32 v109, v108
	s_nop 0
	v_mul_f32_e32 v118, v118, v109
	v_cvt_pk_bf16_f32 v108, v110, v111
	v_cvt_pk_bf16_f32 v109, v112, v113
	v_cvt_pk_bf16_f32 v110, v106, v107
	v_lshl_add_u64 v[106:107], s[88:89], 0, v[116:117]
	v_cvt_pk_bf16_f32 v111, v120, v118
	v_lshl_add_u64 v[106:107], v[106:107], 0, v[142:143]
	global_store_dwordx4 v[106:107], v[108:111], off offset:2048
	global_load_dwordx4 v[108:111], v[114:115], off offset:256
	s_waitcnt vmcnt(0)
	v_lshlrev_b32_e32 v112, 16, v108
	v_and_b32_e32 v113, 0xffff0000, v108
	v_lshlrev_b32_e32 v116, 16, v111
	v_and_b32_e32 v108, 0xffff0000, v111
	v_lshlrev_b32_e32 v115, 16, v110
	v_and_b32_e32 v110, 0xffff0000, v110
	v_lshlrev_b32_e32 v114, 16, v109
	v_rcp_f32_e32 v102, v102
	s_nop 0
	v_mul_f32_e32 v102, v112, v102
	v_and_b32_e32 v109, 0xffff0000, v109
	v_rcp_f32_e32 v111, v98
	s_nop 0
	v_mul_f32_e32 v111, v115, v111
	v_mul_f32_e32 v98, 0xbfb8aa3b, v103
	v_exp_f32_e32 v98, v98
	s_nop 0
	v_add_f32_e32 v98, 1.0, v98
	s_nop 0
	v_rcp_f32_e32 v98, v98
	s_nop 0
	v_mul_f32_e32 v98, v113, v98
	v_cvt_pk_bf16_f32 v98, v102, v98
	s_nop 0
	v_rcp_f32_e32 v103, v99
	s_nop 0
	v_mul_f32_e32 v103, v110, v103
	v_mul_f32_e32 v99, 0xbfb8aa3b, v104
	v_exp_f32_e32 v99, v99
	s_nop 0
	v_add_f32_e32 v99, 1.0, v99
	s_nop 0
	v_rcp_f32_e32 v99, v99
	s_nop 0
	v_mul_f32_e32 v99, v114, v99
	s_nop 0
	v_rcp_f32_e32 v104, v100
	s_nop 0
	v_mul_f32_e32 v104, v116, v104
	v_mul_f32_e32 v100, 0xbfb8aa3b, v105
	v_exp_f32_e32 v100, v100
	s_nop 0
	v_add_f32_e32 v100, 1.0, v100
	s_nop 0
	v_rcp_f32_e32 v100, v100
	s_nop 0
	v_mul_f32_e32 v100, v109, v100
	v_cvt_pk_bf16_f32 v99, v99, v100
	v_cvt_pk_bf16_f32 v100, v111, v103
	s_nop 0
	v_rcp_f32_e32 v101, v101
	s_nop 0
	v_mul_f32_e32 v101, v108, v101
	v_cvt_pk_bf16_f32 v101, v104, v101
	global_store_dwordx4 v[106:107], v[98:101], off offset:2304
	s_nop 1
	v_or_b32_e32 v98, 32, v144
	v_ashrrev_i32_e32 v99, 31, v98
	v_lshlrev_b64 v[102:103], 11, v[98:99]
	v_lshlrev_b64 v[100:101], 12, v[98:99]
	v_lshl_add_u64 v[98:99], s[86:87], 0, v[102:103]
	v_lshl_add_u64 v[98:99], v[98:99], 0, v[142:143]
	global_load_dwordx4 v[102:105], v[98:99], off
	s_waitcnt vmcnt(0)
	v_lshlrev_b32_e32 v106, 16, v102
	v_and_b32_e32 v107, 0xffff0000, v102
	v_lshlrev_b32_e32 v110, 16, v105
	v_and_b32_e32 v102, 0xffff0000, v105
	v_lshlrev_b32_e32 v109, 16, v104
	v_and_b32_e32 v104, 0xffff0000, v104
	v_lshlrev_b32_e32 v108, 16, v103
	v_rcp_f32_e32 v94, v94
	s_nop 0
	v_mul_f32_e32 v94, v106, v94
	v_and_b32_e32 v103, 0xffff0000, v103
	v_rcp_f32_e32 v90, v90
	s_nop 0
	v_mul_f32_e32 v90, v109, v90
	s_nop 0
	v_rcp_f32_e32 v95, v95
	s_nop 0
	v_mul_f32_e32 v95, v107, v95
	s_nop 0
	v_rcp_f32_e32 v91, v91
	s_nop 0
	v_mul_f32_e32 v91, v104, v91
	s_nop 0
	v_rcp_f32_e32 v96, v96
	s_nop 0
	v_mul_f32_e32 v96, v108, v96
	s_nop 0
	v_rcp_f32_e32 v104, v92
	s_nop 0
	v_mul_f32_e32 v104, v110, v104
	v_mul_f32_e32 v92, 0xbfb8aa3b, v97
	v_exp_f32_e32 v92, v92
	s_nop 0
	v_add_f32_e32 v92, 1.0, v92
	s_nop 0
	v_rcp_f32_e32 v97, v92
	s_nop 0
	v_mul_f32_e32 v97, v103, v97
	v_mul_f32_e32 v92, 0xbfb8aa3b, v93
	v_exp_f32_e32 v92, v92
	s_nop 0
	v_add_f32_e32 v92, 1.0, v92
	s_nop 0
	v_rcp_f32_e32 v93, v92
	s_nop 0
	v_mul_f32_e32 v102, v102, v93
	v_cvt_pk_bf16_f32 v92, v94, v95
	v_cvt_pk_bf16_f32 v93, v96, v97
	v_cvt_pk_bf16_f32 v94, v90, v91
	v_lshl_add_u64 v[90:91], s[88:89], 0, v[100:101]
	v_cvt_pk_bf16_f32 v95, v104, v102
	v_lshl_add_u64 v[90:91], v[90:91], 0, v[142:143]
	global_store_dwordx4 v[90:91], v[92:95], off offset:2048
	global_load_dwordx4 v[92:95], v[98:99], off offset:256
	s_waitcnt vmcnt(0)
; __device__ __forceinline__ unsigned cvt_pk_bf16(float lo, float hi) { unsigned r; asm volatile("v_cvt_pk_bf16_f32 %0, %1, %2" : "=v"(r) : "v"(lo), "v"(hi)); return r; }
; __device__ __forceinline__ float bf_lo(unsigned w) { return __uint_as_float(w << 16); }
; __device__ __forceinline__ float bf_hi(unsigned w) { return __uint_as_float(w & 0xffff0000u); }
;     __device__ __forceinline__ void operator()(const f32x4 (&acc)[2][2][4][2], const Unit& u, int ui, const LAS float* rtab, int wr, int wc, int fr, int fq) const {
;     ...
;             for (int m = 0; m < 4; ++m) {
;                 const int row = row0 + ai * HALF + m * 16;
; #pragma unroll
;                 for (int bj = 0; bj < 2; ++bj) {
;                     const int col = col0 + bj * HALF; const u32x4 yv = *(const u32x4*)(Y + (size_t)row * 1024 + col);
;                     const f32x4 a0 = acc[ai][bj][m][0], a1 = acc[ai][bj][m][1]; float o[8];
;                     const float yy[8] = {bf_lo(yv.x), bf_hi(yv.x), bf_lo(yv.y), bf_hi(yv.y), bf_lo(yv.z), bf_hi(yv.z), bf_lo(yv.w), bf_hi(yv.w)};
; #pragma unroll
;                     for (int e = 0; e < 4; ++e) { o[e] = yy[e] / (1.0f + __expf(-a0[e])); o[4 + e] = yy[4 + e] / (1.0f + __expf(-a1[e])); }
;                     u32x4 w; w.x = cvt_pk_bf16(o[0], o[1]); w.y = cvt_pk_bf16(o[2], o[3]); w.z = cvt_pk_bf16(o[4], o[5]); w.w = cvt_pk_bf16(o[6], o[7]);
;                     *(u32x4*)(MG + (size_t)row * DM + 1024 + col) = w;
	v_lshlrev_b32_e32 v96, 16, v92
	v_and_b32_e32 v97, 0xffff0000, v92
	v_lshlrev_b32_e32 v100, 16, v95
	v_and_b32_e32 v92, 0xffff0000, v95
	v_lshlrev_b32_e32 v99, 16, v94
	v_and_b32_e32 v94, 0xffff0000, v94
	v_lshlrev_b32_e32 v98, 16, v93
	v_rcp_f32_e32 v86, v86
	s_nop 0
	v_mul_f32_e32 v86, v96, v86
	v_and_b32_e32 v93, 0xffff0000, v93
	v_rcp_f32_e32 v95, v82
	s_nop 0
	v_mul_f32_e32 v95, v99, v95
	v_mul_f32_e32 v82, 0xbfb8aa3b, v87
	v_exp_f32_e32 v82, v82
	s_nop 0
	v_add_f32_e32 v82, 1.0, v82
	s_nop 0
	v_rcp_f32_e32 v82, v82
	s_nop 0
	v_mul_f32_e32 v82, v97, v82
	v_cvt_pk_bf16_f32 v82, v86, v82
	s_nop 0
	v_rcp_f32_e32 v87, v83
	s_nop 0
	v_mul_f32_e32 v87, v94, v87
	v_mul_f32_e32 v83, 0xbfb8aa3b, v88
	v_exp_f32_e32 v83, v83
	s_nop 0
	v_add_f32_e32 v83, 1.0, v83
	s_nop 0
	v_rcp_f32_e32 v83, v83
	s_nop 0
	v_mul_f32_e32 v83, v98, v83
	s_nop 0
	v_rcp_f32_e32 v88, v84
	s_nop 0
	v_mul_f32_e32 v88, v100, v88
	v_mul_f32_e32 v84, 0xbfb8aa3b, v89
	v_exp_f32_e32 v84, v84
	s_nop 0
	v_add_f32_e32 v84, 1.0, v84
	s_nop 0
	v_rcp_f32_e32 v84, v84
	s_nop 0
	v_mul_f32_e32 v84, v93, v84
	v_cvt_pk_bf16_f32 v83, v83, v84
	v_cvt_pk_bf16_f32 v84, v95, v87
	s_nop 0
	v_rcp_f32_e32 v85, v85
	s_nop 0
	v_mul_f32_e32 v85, v92, v85
	v_cvt_pk_bf16_f32 v85, v88, v85
	global_store_dwordx4 v[90:91], v[82:85], off offset:2304
	s_nop 1
	v_or_b32_e32 v82, 48, v144
	v_ashrrev_i32_e32 v83, 31, v82
	v_lshlrev_b64 v[86:87], 11, v[82:83]
	v_lshlrev_b64 v[84:85], 12, v[82:83]
	v_lshl_add_u64 v[82:83], s[86:87], 0, v[86:87]
	v_lshl_add_u64 v[82:83], v[82:83], 0, v[142:143]
	global_load_dwordx4 v[86:89], v[82:83], off
	s_waitcnt vmcnt(0)
	v_lshlrev_b32_e32 v90, 16, v86
	v_and_b32_e32 v91, 0xffff0000, v86
	v_lshlrev_b32_e32 v94, 16, v89
	v_and_b32_e32 v86, 0xffff0000, v89
	v_lshlrev_b32_e32 v93, 16, v88
	v_and_b32_e32 v88, 0xffff0000, v88
	v_lshlrev_b32_e32 v92, 16, v87
	v_rcp_f32_e32 v78, v78
	s_nop 0
	v_mul_f32_e32 v78, v90, v78
	v_and_b32_e32 v87, 0xffff0000, v87
	v_rcp_f32_e32 v74, v74
	s_nop 0
	v_mul_f32_e32 v74, v93, v74
	s_nop 0
	v_rcp_f32_e32 v79, v79
	s_nop 0
	v_mul_f32_e32 v79, v91, v79
	s_nop 0
	v_rcp_f32_e32 v75, v75
	s_nop 0
	v_mul_f32_e32 v75, v88, v75
	s_nop 0
	v_rcp_f32_e32 v80, v80
	s_nop 0
	v_mul_f32_e32 v80, v92, v80
	s_nop 0
	v_rcp_f32_e32 v88, v76
	s_nop 0
	v_mul_f32_e32 v88, v94, v88
	v_mul_f32_e32 v76, 0xbfb8aa3b, v81
	v_exp_f32_e32 v76, v76
	s_nop 0
	v_add_f32_e32 v76, 1.0, v76
	s_nop 0
	v_rcp_f32_e32 v81, v76
	s_nop 0
	v_mul_f32_e32 v81, v87, v81
	v_mul_f32_e32 v76, 0xbfb8aa3b, v77
	v_exp_f32_e32 v76, v76
	s_nop 0
	v_add_f32_e32 v76, 1.0, v76
	s_nop 0
	v_rcp_f32_e32 v77, v76
	s_nop 0
	v_mul_f32_e32 v86, v86, v77
	v_cvt_pk_bf16_f32 v76, v78, v79
	v_cvt_pk_bf16_f32 v77, v80, v81
	v_cvt_pk_bf16_f32 v78, v74, v75
	v_lshl_add_u64 v[74:75], s[88:89], 0, v[84:85]
	v_cvt_pk_bf16_f32 v79, v88, v86
	v_lshl_add_u64 v[74:75], v[74:75], 0, v[142:143]
	global_store_dwordx4 v[74:75], v[76:79], off offset:2048
	global_load_dwordx4 v[76:79], v[82:83], off offset:256
	s_waitcnt vmcnt(0)
	v_lshlrev_b32_e32 v80, 16, v76
	v_and_b32_e32 v81, 0xffff0000, v76
	v_lshlrev_b32_e32 v84, 16, v79
	v_and_b32_e32 v76, 0xffff0000, v79
	v_lshlrev_b32_e32 v83, 16, v78
	v_and_b32_e32 v78, 0xffff0000, v78
	v_lshlrev_b32_e32 v82, 16, v77
	v_rcp_f32_e32 v70, v70
	s_nop 0
	v_mul_f32_e32 v70, v80, v70
	v_and_b32_e32 v77, 0xffff0000, v77
	v_rcp_f32_e32 v79, v66
	s_nop 0
	v_mul_f32_e32 v79, v83, v79
	v_mul_f32_e32 v66, 0xbfb8aa3b, v71
	v_exp_f32_e32 v66, v66
	s_nop 0
	v_add_f32_e32 v66, 1.0, v66
	s_nop 0
	v_rcp_f32_e32 v66, v66
	s_nop 0
	v_mul_f32_e32 v66, v81, v66
	v_cvt_pk_bf16_f32 v66, v70, v66
	s_nop 0
	v_rcp_f32_e32 v71, v67
	s_nop 0
	v_mul_f32_e32 v71, v78, v71
	v_mul_f32_e32 v67, 0xbfb8aa3b, v72
	v_exp_f32_e32 v67, v67
	s_nop 0
	v_add_f32_e32 v67, 1.0, v67
	s_nop 0
	v_rcp_f32_e32 v67, v67
	s_nop 0
	v_mul_f32_e32 v67, v82, v67
	s_nop 0
	v_rcp_f32_e32 v72, v68
	s_nop 0
	v_mul_f32_e32 v72, v84, v72
	v_mul_f32_e32 v68, 0xbfb8aa3b, v73
	v_exp_f32_e32 v68, v68
	s_nop 0
	v_add_f32_e32 v68, 1.0, v68
	s_nop 0
	v_rcp_f32_e32 v68, v68
	s_nop 0
	v_mul_f32_e32 v68, v77, v68
	v_cvt_pk_bf16_f32 v67, v67, v68
	v_cvt_pk_bf16_f32 v68, v79, v71
	s_nop 0
	v_rcp_f32_e32 v69, v69
	s_nop 0
	v_mul_f32_e32 v69, v76, v69
	v_cvt_pk_bf16_f32 v69, v72, v69
	global_store_dwordx4 v[74:75], v[66:69], off offset:2304
	s_nop 1
	v_add_u32_e32 v66, 0x80, v144
	v_ashrrev_i32_e32 v67, 31, v66
	v_lshlrev_b64 v[70:71], 11, v[66:67]
	v_lshlrev_b64 v[68:69], 12, v[66:67]
	v_lshl_add_u64 v[66:67], s[86:87], 0, v[70:71]
	v_lshl_add_u64 v[66:67], v[66:67], 0, v[142:143]
	global_load_dwordx4 v[70:73], v[66:67], off
	s_waitcnt vmcnt(0)
	v_lshlrev_b32_e32 v74, 16, v70
	v_and_b32_e32 v75, 0xffff0000, v70
	v_lshlrev_b32_e32 v78, 16, v73
	v_and_b32_e32 v70, 0xffff0000, v73
	v_lshlrev_b32_e32 v77, 16, v72
	v_and_b32_e32 v72, 0xffff0000, v72
	v_lshlrev_b32_e32 v76, 16, v71
	v_rcp_f32_e32 v62, v62
	s_nop 0
	v_mul_f32_e32 v62, v74, v62
	v_and_b32_e32 v71, 0xffff0000, v71
	v_rcp_f32_e32 v58, v58
	s_nop 0
	v_mul_f32_e32 v58, v77, v58
	s_nop 0
	v_rcp_f32_e32 v63, v63
	s_nop 0
	v_mul_f32_e32 v63, v75, v63
	s_nop 0
	v_rcp_f32_e32 v59, v59
	s_nop 0
	v_mul_f32_e32 v59, v72, v59
	s_nop 0
	v_rcp_f32_e32 v64, v64
	s_nop 0
	v_mul_f32_e32 v64, v76, v64
	s_nop 0
	v_rcp_f32_e32 v72, v60
	s_nop 0
	v_mul_f32_e32 v72, v78, v72
	v_mul_f32_e32 v60, 0xbfb8aa3b, v65
	v_exp_f32_e32 v60, v60
	s_nop 0
	v_add_f32_e32 v60, 1.0, v60
	s_nop 0
	v_rcp_f32_e32 v65, v60
	s_nop 0
	v_mul_f32_e32 v65, v71, v65
	v_mul_f32_e32 v60, 0xbfb8aa3b, v61
	v_exp_f32_e32 v60, v60
	s_nop 0
	v_add_f32_e32 v60, 1.0, v60
	s_nop 0
	v_rcp_f32_e32 v61, v60
	s_nop 0
	v_mul_f32_e32 v70, v70, v61
	v_cvt_pk_bf16_f32 v60, v62, v63
	v_cvt_pk_bf16_f32 v61, v64, v65
	v_cvt_pk_bf16_f32 v62, v58, v59
	v_lshl_add_u64 v[58:59], s[88:89], 0, v[68:69]
	v_cvt_pk_bf16_f32 v63, v72, v70
	v_lshl_add_u64 v[58:59], v[58:59], 0, v[142:143]
	global_store_dwordx4 v[58:59], v[60:63], off offset:2048
	global_load_dwordx4 v[60:63], v[66:67], off offset:256
	s_waitcnt vmcnt(0)
; __device__ __forceinline__ unsigned cvt_pk_bf16(float lo, float hi) { unsigned r; asm volatile("v_cvt_pk_bf16_f32 %0, %1, %2" : "=v"(r) : "v"(lo), "v"(hi)); return r; }
; __device__ __forceinline__ float bf_lo(unsigned w) { return __uint_as_float(w << 16); }
; __device__ __forceinline__ float bf_hi(unsigned w) { return __uint_as_float(w & 0xffff0000u); }
;     __device__ __forceinline__ void operator()(const f32x4 (&acc)[2][2][4][2], const Unit& u, int ui, const LAS float* rtab, int wr, int wc, int fr, int fq) const {
;     ...
;             for (int m = 0; m < 4; ++m) {
;                 const int row = row0 + ai * HALF + m * 16;
; #pragma unroll
;                 for (int bj = 0; bj < 2; ++bj) {
;                     const int col = col0 + bj * HALF; const u32x4 yv = *(const u32x4*)(Y + (size_t)row * 1024 + col);
;                     const f32x4 a0 = acc[ai][bj][m][0], a1 = acc[ai][bj][m][1]; float o[8];
;                     const float yy[8] = {bf_lo(yv.x), bf_hi(yv.x), bf_lo(yv.y), bf_hi(yv.y), bf_lo(yv.z), bf_hi(yv.z), bf_lo(yv.w), bf_hi(yv.w)};
; #pragma unroll
;                     for (int e = 0; e < 4; ++e) { o[e] = yy[e] / (1.0f + __expf(-a0[e])); o[4 + e] = yy[4 + e] / (1.0f + __expf(-a1[e])); }
;                     u32x4 w; w.x = cvt_pk_bf16(o[0], o[1]); w.y = cvt_pk_bf16(o[2], o[3]); w.z = cvt_pk_bf16(o[4], o[5]); w.w = cvt_pk_bf16(o[6], o[7]);
;                     *(u32x4*)(MG + (size_t)row * DM + 1024 + col) = w;
	v_lshlrev_b32_e32 v64, 16, v60
	v_and_b32_e32 v65, 0xffff0000, v60
	v_lshlrev_b32_e32 v68, 16, v63
	v_and_b32_e32 v60, 0xffff0000, v63
	v_lshlrev_b32_e32 v67, 16, v62
	v_and_b32_e32 v62, 0xffff0000, v62
	v_lshlrev_b32_e32 v66, 16, v61
	v_rcp_f32_e32 v54, v54
	s_nop 0
	v_mul_f32_e32 v54, v64, v54
	v_and_b32_e32 v61, 0xffff0000, v61
	v_rcp_f32_e32 v63, v50
	s_nop 0
	v_mul_f32_e32 v63, v67, v63
	v_mul_f32_e32 v50, 0xbfb8aa3b, v55
	v_exp_f32_e32 v50, v50
	s_nop 0
	v_add_f32_e32 v50, 1.0, v50
	s_nop 0
	v_rcp_f32_e32 v50, v50
	s_nop 0
	v_mul_f32_e32 v50, v65, v50
	v_cvt_pk_bf16_f32 v50, v54, v50
	s_nop 0
	v_rcp_f32_e32 v55, v51
	s_nop 0
	v_mul_f32_e32 v55, v62, v55
	v_mul_f32_e32 v51, 0xbfb8aa3b, v56
	v_exp_f32_e32 v51, v51
	s_nop 0
	v_add_f32_e32 v51, 1.0, v51
	s_nop 0
	v_rcp_f32_e32 v51, v51
	s_nop 0
	v_mul_f32_e32 v51, v66, v51
	s_nop 0
	v_rcp_f32_e32 v56, v52
	s_nop 0
	v_mul_f32_e32 v56, v68, v56
	v_mul_f32_e32 v52, 0xbfb8aa3b, v57
	v_exp_f32_e32 v52, v52
	s_nop 0
	v_add_f32_e32 v52, 1.0, v52
	s_nop 0
	v_rcp_f32_e32 v52, v52
	s_nop 0
	v_mul_f32_e32 v52, v61, v52
	v_cvt_pk_bf16_f32 v51, v51, v52
	v_cvt_pk_bf16_f32 v52, v63, v55
	s_nop 0
	v_rcp_f32_e32 v53, v53
	s_nop 0
	v_mul_f32_e32 v53, v60, v53
	v_cvt_pk_bf16_f32 v53, v56, v53
	global_store_dwordx4 v[58:59], v[50:53], off offset:2304
	s_nop 1
	v_add_u32_e32 v50, 0x90, v144
	v_ashrrev_i32_e32 v51, 31, v50
	v_lshlrev_b64 v[54:55], 11, v[50:51]
	v_lshlrev_b64 v[52:53], 12, v[50:51]
	v_lshl_add_u64 v[50:51], s[86:87], 0, v[54:55]
	v_lshl_add_u64 v[50:51], v[50:51], 0, v[142:143]
	global_load_dwordx4 v[54:57], v[50:51], off
	s_waitcnt vmcnt(0)
	v_lshlrev_b32_e32 v58, 16, v54
	v_and_b32_e32 v59, 0xffff0000, v54
	v_lshlrev_b32_e32 v62, 16, v57
	v_and_b32_e32 v54, 0xffff0000, v57
	v_lshlrev_b32_e32 v61, 16, v56
	v_and_b32_e32 v56, 0xffff0000, v56
	v_lshlrev_b32_e32 v60, 16, v55
	v_rcp_f32_e32 v46, v46
	s_nop 0
	v_mul_f32_e32 v46, v58, v46
	v_and_b32_e32 v55, 0xffff0000, v55
	v_rcp_f32_e32 v42, v42
	s_nop 0
	v_mul_f32_e32 v42, v61, v42
	s_nop 0
	v_rcp_f32_e32 v47, v47
	s_nop 0
	v_mul_f32_e32 v47, v59, v47
	s_nop 0
	v_rcp_f32_e32 v43, v43
	s_nop 0
	v_mul_f32_e32 v43, v56, v43
	s_nop 0
	v_rcp_f32_e32 v48, v48
	s_nop 0
	v_mul_f32_e32 v48, v60, v48
	s_nop 0
	v_rcp_f32_e32 v56, v44
	s_nop 0
	v_mul_f32_e32 v56, v62, v56
	v_mul_f32_e32 v44, 0xbfb8aa3b, v49
	v_exp_f32_e32 v44, v44
	s_nop 0
	v_add_f32_e32 v44, 1.0, v44
	s_nop 0
	v_rcp_f32_e32 v49, v44
	s_nop 0
	v_mul_f32_e32 v49, v55, v49
	v_mul_f32_e32 v44, 0xbfb8aa3b, v45
	v_exp_f32_e32 v44, v44
	s_nop 0
	v_add_f32_e32 v44, 1.0, v44
	s_nop 0
	v_rcp_f32_e32 v45, v44
	s_nop 0
	v_mul_f32_e32 v54, v54, v45
	v_cvt_pk_bf16_f32 v44, v46, v47
	v_cvt_pk_bf16_f32 v45, v48, v49
	v_cvt_pk_bf16_f32 v46, v42, v43
	v_lshl_add_u64 v[42:43], s[88:89], 0, v[52:53]
	v_cvt_pk_bf16_f32 v47, v56, v54
	v_lshl_add_u64 v[42:43], v[42:43], 0, v[142:143]
	global_store_dwordx4 v[42:43], v[44:47], off offset:2048
	global_load_dwordx4 v[44:47], v[50:51], off offset:256
	s_waitcnt vmcnt(0)
	v_lshlrev_b32_e32 v48, 16, v44
	v_and_b32_e32 v49, 0xffff0000, v44
	v_lshlrev_b32_e32 v52, 16, v47
	v_and_b32_e32 v44, 0xffff0000, v47
	v_lshlrev_b32_e32 v51, 16, v46
	v_and_b32_e32 v46, 0xffff0000, v46
	v_lshlrev_b32_e32 v50, 16, v45
	v_rcp_f32_e32 v38, v38
	s_nop 0
	v_mul_f32_e32 v38, v48, v38
	v_and_b32_e32 v45, 0xffff0000, v45
	v_rcp_f32_e32 v47, v34
	s_nop 0
	v_mul_f32_e32 v47, v51, v47
	v_mul_f32_e32 v34, 0xbfb8aa3b, v39
	v_exp_f32_e32 v34, v34
	s_nop 0
	v_add_f32_e32 v34, 1.0, v34
	s_nop 0
	v_rcp_f32_e32 v34, v34
	s_nop 0
	v_mul_f32_e32 v34, v49, v34
	v_cvt_pk_bf16_f32 v34, v38, v34
	s_nop 0
	v_rcp_f32_e32 v39, v35
	s_nop 0
	v_mul_f32_e32 v39, v46, v39
	v_mul_f32_e32 v35, 0xbfb8aa3b, v40
	v_exp_f32_e32 v35, v35
	s_nop 0
	v_add_f32_e32 v35, 1.0, v35
	s_nop 0
	v_rcp_f32_e32 v35, v35
	s_nop 0
	v_mul_f32_e32 v35, v50, v35
	s_nop 0
	v_rcp_f32_e32 v40, v36
	s_nop 0
	v_mul_f32_e32 v40, v52, v40
	v_mul_f32_e32 v36, 0xbfb8aa3b, v41
	v_exp_f32_e32 v36, v36
	s_nop 0
	v_add_f32_e32 v36, 1.0, v36
	s_nop 0
	v_rcp_f32_e32 v36, v36
	s_nop 0
	v_mul_f32_e32 v36, v45, v36
	v_cvt_pk_bf16_f32 v35, v35, v36
	v_cvt_pk_bf16_f32 v36, v47, v39
	s_nop 0
	v_rcp_f32_e32 v37, v37
	s_nop 0
	v_mul_f32_e32 v37, v44, v37
	v_cvt_pk_bf16_f32 v37, v40, v37
	global_store_dwordx4 v[42:43], v[34:37], off offset:2304
	s_nop 1
	v_add_u32_e32 v34, 0xa0, v144
	v_ashrrev_i32_e32 v35, 31, v34
	v_lshlrev_b64 v[38:39], 11, v[34:35]
	v_lshlrev_b64 v[36:37], 12, v[34:35]
	v_lshl_add_u64 v[34:35], s[86:87], 0, v[38:39]
	v_lshl_add_u64 v[34:35], v[34:35], 0, v[142:143]
	global_load_dwordx4 v[38:41], v[34:35], off
	s_waitcnt vmcnt(0)
; __device__ __forceinline__ unsigned cvt_pk_bf16(float lo, float hi) { unsigned r; asm volatile("v_cvt_pk_bf16_f32 %0, %1, %2" : "=v"(r) : "v"(lo), "v"(hi)); return r; }
; __device__ __forceinline__ float bf_lo(unsigned w) { return __uint_as_float(w << 16); }
; __device__ __forceinline__ float bf_hi(unsigned w) { return __uint_as_float(w & 0xffff0000u); }
;     __device__ __forceinline__ void operator()(const f32x4 (&acc)[2][2][4][2], const Unit& u, int ui, const LAS float* rtab, int wr, int wc, int fr, int fq) const {
;     ...
;             for (int m = 0; m < 4; ++m) {
;                 const int row = row0 + ai * HALF + m * 16;
; #pragma unroll
;                 for (int bj = 0; bj < 2; ++bj) {
;                     const int col = col0 + bj * HALF; const u32x4 yv = *(const u32x4*)(Y + (size_t)row * 1024 + col);
;                     const f32x4 a0 = acc[ai][bj][m][0], a1 = acc[ai][bj][m][1]; float o[8];
;                     const float yy[8] = {bf_lo(yv.x), bf_hi(yv.x), bf_lo(yv.y), bf_hi(yv.y), bf_lo(yv.z), bf_hi(yv.z), bf_lo(yv.w), bf_hi(yv.w)};
; #pragma unroll
;                     for (int e = 0; e < 4; ++e) { o[e] = yy[e] / (1.0f + __expf(-a0[e])); o[4 + e] = yy[4 + e] / (1.0f + __expf(-a1[e])); }
;                     u32x4 w; w.x = cvt_pk_bf16(o[0], o[1]); w.y = cvt_pk_bf16(o[2], o[3]); w.z = cvt_pk_bf16(o[4], o[5]); w.w = cvt_pk_bf16(o[6], o[7]);
;                     *(u32x4*)(MG + (size_t)row * DM + 1024 + col) = w;
	v_lshlrev_b32_e32 v42, 16, v38
	v_and_b32_e32 v43, 0xffff0000, v38
	v_lshlrev_b32_e32 v46, 16, v41
	v_and_b32_e32 v38, 0xffff0000, v41
	v_lshlrev_b32_e32 v45, 16, v40
	v_and_b32_e32 v40, 0xffff0000, v40
	v_lshlrev_b32_e32 v44, 16, v39
	v_rcp_f32_e32 v30, v30
	s_nop 0
	v_mul_f32_e32 v30, v42, v30
	v_and_b32_e32 v39, 0xffff0000, v39
	v_rcp_f32_e32 v26, v26
	s_nop 0
	v_mul_f32_e32 v26, v45, v26
	s_nop 0
	v_rcp_f32_e32 v31, v31
	s_nop 0
	v_mul_f32_e32 v31, v43, v31
	s_nop 0
	v_rcp_f32_e32 v27, v27
	s_nop 0
	v_mul_f32_e32 v27, v40, v27
	s_nop 0
	v_rcp_f32_e32 v32, v32
	s_nop 0
	v_mul_f32_e32 v32, v44, v32
	s_nop 0
	v_rcp_f32_e32 v40, v28
	s_nop 0
	v_mul_f32_e32 v40, v46, v40
	v_mul_f32_e32 v28, 0xbfb8aa3b, v33
	v_exp_f32_e32 v28, v28
	s_nop 0
	v_add_f32_e32 v28, 1.0, v28
	s_nop 0
	v_rcp_f32_e32 v33, v28
	s_nop 0
	v_mul_f32_e32 v33, v39, v33
	v_mul_f32_e32 v28, 0xbfb8aa3b, v29
	v_exp_f32_e32 v28, v28
	s_nop 0
	v_add_f32_e32 v28, 1.0, v28
	s_nop 0
	v_rcp_f32_e32 v29, v28
	s_nop 0
	v_mul_f32_e32 v38, v38, v29
	v_cvt_pk_bf16_f32 v28, v30, v31
	v_cvt_pk_bf16_f32 v29, v32, v33
	v_cvt_pk_bf16_f32 v30, v26, v27
	v_lshl_add_u64 v[26:27], s[88:89], 0, v[36:37]
	v_cvt_pk_bf16_f32 v31, v40, v38
	v_lshl_add_u64 v[26:27], v[26:27], 0, v[142:143]
	global_store_dwordx4 v[26:27], v[28:31], off offset:2048
	global_load_dwordx4 v[28:31], v[34:35], off offset:256
	s_waitcnt vmcnt(0)
	v_lshlrev_b32_e32 v32, 16, v28
	v_and_b32_e32 v33, 0xffff0000, v28
	v_lshlrev_b32_e32 v36, 16, v31
	v_and_b32_e32 v28, 0xffff0000, v31
	v_lshlrev_b32_e32 v35, 16, v30
	v_and_b32_e32 v30, 0xffff0000, v30
	v_lshlrev_b32_e32 v34, 16, v29
	v_rcp_f32_e32 v22, v22
	s_nop 0
	v_mul_f32_e32 v22, v32, v22
	v_and_b32_e32 v29, 0xffff0000, v29
	v_rcp_f32_e32 v31, v18
	s_nop 0
	v_mul_f32_e32 v31, v35, v31
	v_mul_f32_e32 v18, 0xbfb8aa3b, v23
	v_exp_f32_e32 v18, v18
	s_nop 0
	v_add_f32_e32 v18, 1.0, v18
	s_nop 0
	v_rcp_f32_e32 v18, v18
	s_nop 0
	v_mul_f32_e32 v18, v33, v18
	v_cvt_pk_bf16_f32 v18, v22, v18
	s_nop 0
	v_rcp_f32_e32 v23, v19
	s_nop 0
	v_mul_f32_e32 v23, v30, v23
	v_mul_f32_e32 v19, 0xbfb8aa3b, v24
	v_exp_f32_e32 v19, v19
	s_nop 0
	v_add_f32_e32 v19, 1.0, v19
	s_nop 0
	v_rcp_f32_e32 v19, v19
	s_nop 0
	v_mul_f32_e32 v19, v34, v19
	s_nop 0
	v_rcp_f32_e32 v24, v20
	s_nop 0
	v_mul_f32_e32 v24, v36, v24
	v_mul_f32_e32 v20, 0xbfb8aa3b, v25
	v_exp_f32_e32 v20, v20
	s_nop 0
	v_add_f32_e32 v20, 1.0, v20
	s_nop 0
	v_rcp_f32_e32 v20, v20
	s_nop 0
	v_mul_f32_e32 v20, v29, v20
	v_cvt_pk_bf16_f32 v19, v19, v20
	v_cvt_pk_bf16_f32 v20, v31, v23
	s_nop 0
	v_rcp_f32_e32 v21, v21
	s_nop 0
	v_mul_f32_e32 v21, v28, v21
	v_cvt_pk_bf16_f32 v21, v24, v21
	global_store_dwordx4 v[26:27], v[18:21], off offset:2304
	s_nop 1
	v_add_u32_e32 v18, 0xb0, v144
	v_ashrrev_i32_e32 v19, 31, v18
	v_lshlrev_b64 v[22:23], 11, v[18:19]
	v_lshlrev_b64 v[20:21], 12, v[18:19]
	v_lshl_add_u64 v[18:19], s[86:87], 0, v[22:23]
	v_lshl_add_u64 v[18:19], v[18:19], 0, v[142:143]
	global_load_dwordx4 v[22:25], v[18:19], off
	s_waitcnt vmcnt(0)
	v_lshlrev_b32_e32 v26, 16, v22
	v_and_b32_e32 v27, 0xffff0000, v22
	v_lshlrev_b32_e32 v30, 16, v25
	v_and_b32_e32 v22, 0xffff0000, v25
	v_lshlrev_b32_e32 v29, 16, v24
	v_and_b32_e32 v24, 0xffff0000, v24
	v_lshlrev_b32_e32 v28, 16, v23
	v_rcp_f32_e32 v14, v14
	s_nop 0
	v_mul_f32_e32 v14, v26, v14
	v_and_b32_e32 v23, 0xffff0000, v23
	v_rcp_f32_e32 v10, v10
	s_nop 0
	v_mul_f32_e32 v10, v29, v10
	s_nop 0
	v_rcp_f32_e32 v15, v15
	s_nop 0
	v_mul_f32_e32 v15, v27, v15
	s_nop 0
	v_rcp_f32_e32 v11, v11
	s_nop 0
	v_mul_f32_e32 v11, v24, v11
	s_nop 0
	v_rcp_f32_e32 v16, v16
	s_nop 0
	v_mul_f32_e32 v16, v28, v16
	s_nop 0
	v_rcp_f32_e32 v24, v12
	s_nop 0
	v_mul_f32_e32 v24, v30, v24
	v_mul_f32_e32 v12, 0xbfb8aa3b, v17
	v_exp_f32_e32 v12, v12
	s_nop 0
	v_add_f32_e32 v12, 1.0, v12
	s_nop 0
	v_rcp_f32_e32 v17, v12
	s_nop 0
	v_mul_f32_e32 v17, v23, v17
	v_mul_f32_e32 v12, 0xbfb8aa3b, v13
	v_exp_f32_e32 v12, v12
	s_nop 0
	v_add_f32_e32 v12, 1.0, v12
	s_nop 0
	v_rcp_f32_e32 v13, v12
	s_nop 0
	v_mul_f32_e32 v22, v22, v13
	v_cvt_pk_bf16_f32 v12, v14, v15
	v_cvt_pk_bf16_f32 v13, v16, v17
	v_cvt_pk_bf16_f32 v14, v10, v11
	v_lshl_add_u64 v[10:11], s[88:89], 0, v[20:21]
	v_cvt_pk_bf16_f32 v15, v24, v22
	v_lshl_add_u64 v[10:11], v[10:11], 0, v[142:143]
	global_store_dwordx4 v[10:11], v[12:15], off offset:2048
	global_load_dwordx4 v[12:15], v[18:19], off offset:256
	s_waitcnt vmcnt(0)
	v_lshlrev_b32_e32 v16, 16, v12
	v_and_b32_e32 v17, 0xffff0000, v12
	v_lshlrev_b32_e32 v20, 16, v15
	v_and_b32_e32 v12, 0xffff0000, v15
	v_lshlrev_b32_e32 v19, 16, v14
	v_and_b32_e32 v14, 0xffff0000, v14
	v_lshlrev_b32_e32 v18, 16, v13
	v_rcp_f32_e32 v6, v6
	s_nop 0
	v_mul_f32_e32 v6, v16, v6
	v_and_b32_e32 v13, 0xffff0000, v13
	v_rcp_f32_e32 v15, v2
	s_nop 0
	v_mul_f32_e32 v15, v19, v15
	v_mul_f32_e32 v2, 0xbfb8aa3b, v7
	v_exp_f32_e32 v2, v2
	s_nop 0
	v_add_f32_e32 v2, 1.0, v2
	s_nop 0
	v_rcp_f32_e32 v2, v2
	s_nop 0
	v_mul_f32_e32 v2, v17, v2
	v_cvt_pk_bf16_f32 v2, v6, v2
	s_nop 0
	v_rcp_f32_e32 v7, v3
	s_nop 0
	v_mul_f32_e32 v7, v14, v7
	v_mul_f32_e32 v3, 0xbfb8aa3b, v8
	v_exp_f32_e32 v3, v3
	s_nop 0
	v_add_f32_e32 v3, 1.0, v3
	s_nop 0
	v_rcp_f32_e32 v3, v3
	s_nop 0
	v_mul_f32_e32 v3, v18, v3
	s_nop 0
	v_rcp_f32_e32 v8, v4
	s_nop 0
	v_mul_f32_e32 v8, v20, v8
	v_mul_f32_e32 v4, 0xbfb8aa3b, v9
	v_exp_f32_e32 v4, v4
	s_nop 0
	v_add_f32_e32 v4, 1.0, v4
	s_nop 0
	v_rcp_f32_e32 v4, v4
	s_nop 0
	v_mul_f32_e32 v4, v13, v4
	v_div_scale_f32 v9, s[12:13], v5, v5, v12
	s_mov_b32 s12, s0
	s_mov_b32 s13, s42
	v_cvt_pk_bf16_f32 v3, v3, v4
	v_div_scale_f32 v14, vcc, v12, v5, v12
	v_rcp_f32_e32 v5, v5
	s_nop 0
	v_mul_f32_e32 v5, v12, v5
	s_and_b64 vcc, exec, s[40:41]
	v_cvt_pk_bf16_f32 v4, v15, v7
	v_cvt_pk_bf16_f32 v5, v8, v5
	global_store_dwordx4 v[10:11], v[2:5], off offset:2304
	s_cbranch_vccz .LBB0_661
	s_waitcnt vmcnt(0)
	s_cmpk_gt_u32 s27, 0xff
	s_cbranch_scc1 .LBB0_672
	s_barrier
